# GEMM load segments: M0-hazard s_nop slots filled by the address add (82 s_nops removed) on top of the trimmed barrier hand-off
# baseline (speedup 1.0000x reference)
; #define PG8_STAGE(bufoff, gbase, voff) do { _Pragma("unroll") for (int _i = 0; _i < 2; ++_i) \
;         __builtin_amdgcn_global_load_lds((const unsigned*)((const char*)(gbase) + (voff)[_i]), (PG8_LAS unsigned*)(lds + (bufoff) + ldsw + _i * 8192), 16, 0, 0); } while (0)
; #define PG8_LDA(dst, b, h) do { _Pragma("unroll") for (int m = 0; m < 4; ++m) _Pragma("unroll") for (int k = 0; k < 2; ++k) dst[m][k] = *(const PG8_LAS bf16x8*)(lds + PG8_SA(b, h) + aoff + m * 2048 + k * 1024); } while (0)
; #define PG8_LDB(dst, b, h) do { _Pragma("unroll") for (int n = 0; n < 2; ++n) _Pragma("unroll") for (int k = 0; k < 2; ++k) dst[n][k] = *(const PG8_LAS bf16x8*)(lds + PG8_SB(b, h) + boff + n * 2048 + k * 1024); } while (0)
; #define PG8_MMA(ai, bj, At, Bt) do { __builtin_amdgcn_s_setprio(1); _Pragma("unroll") for (int m = 0; m < 4; ++m) _Pragma("unroll") for (int n = 0; n < 2; ++n) _Pragma("unroll") for (int k = 0; k < 2; ++k) \
;         acc[ai][bj][m][n] = __builtin_amdgcn_mfma_f32_16x16x32_bf16(Bt[n][k], At[m][k], acc[ai][bj][m][n], 0, 0, 0); __builtin_amdgcn_s_setprio(0); } while (0)
; #define PG8_WAIT_V(n) asm volatile("s_waitcnt vmcnt(" #n ")" ::: "memory")
; #define PG8_WAIT_L(n) asm volatile("s_waitcnt lgkmcnt(" #n ")" ::: "memory")
; #define PG8_BAR __builtin_amdgcn_s_barrier()
; #define PG8_SCHED __builtin_amdgcn_sched_barrier(0)
; template <class Epi, class Sched, bool ALIGN_EPI = false, bool SP2 = false>
; __device__ __forceinline__ void gemm_phase(PG8_LAS unsigned char* lds, const Gemm g, const Sched& S, const Epi& E) {
;     ...
;             const bool last = (t == nt - 2);
;             const char* a1 = cA + (size_t)(t + 1) * kstep;
;             const char* a2 = last ? nA : cA + (size_t)(t + 2) * kstep; const char* b2 = last ? nB : cB + (size_t)(t + 2) * kstep;
;             const char* a3 = a2 + kstep; const char* b3 = b2 + kstep;
;             if (last && has_next) S.a_ready(nxt);
;             if constexpr (SP2) {
;             PG8_LDB(B0, 0, 0); PG8_LDB(B1, 0, 1); PG8_SCHED; PG8_LDA(At, 0, 0); PG8_STAGE(PG8_SA(1, 1), a1 + hstepA, voffA);
;             PG8_WAIT_V(8); PG8_WAIT_L(0); PG8_BAR; PG8_MMA(0, 0, At, B0); PG8_MMA(0, 1, At, B1); PG8_BAR; PG8_SCHED;
;             PG8_LDA(At, 0, 1); PG8_STAGE(PG8_SB(0, 0), b2, voffB); PG8_STAGE(PG8_SB(0, 1), b2 + hstepB, voffB); PG8_STAGE(PG8_SA(0, 0), a2, voffA);
.LBB0_244:
	ds_read_b128 v[152:155], v147
	ds_read_b128 v[156:159], v147 offset:1024
	ds_read_b128 v[160:163], v147 offset:2048
	ds_read_b128 v[164:167], v147 offset:3072
	ds_read_b128 v[168:171], v148
	ds_read_b128 v[172:175], v148 offset:1024
	ds_read_b128 v[176:179], v148 offset:2048
	ds_read_b128 v[180:183], v148 offset:3072
	s_add_u32 s28, s26, 0xfffc0080
	s_addc_u32 s29, s27, -1
	s_cmp_eq_u32 s68, 12
	s_cselect_b32 s31, s15, s29
	s_cselect_b32 s30, s62, s28
	s_cselect_b32 s29, s13, s67
	s_cselect_b32 s28, s63, s66
	v_lshl_add_u64 v[184:185], s[26:27], 0, v[136:137]
	s_add_i32 m0, s25, 0xc000
	ds_read_b128 v[188:191], v149
	ds_read_b128 v[192:195], v149 offset:1024
	ds_read_b128 v[196:199], v149 offset:2048
	ds_read_b128 v[200:203], v149 offset:3072
	ds_read_b128 v[204:207], v149 offset:4096
	ds_read_b128 v[208:211], v149 offset:5120
	ds_read_b128 v[212:215], v149 offset:6144
	ds_read_b128 v[216:219], v149 offset:7168
	global_load_lds_dwordx4 v[184:185], off
	s_add_i32 m0, s25, 0xe000
	v_lshl_add_u64 v[184:185], s[26:27], 0, v[138:139]
	global_load_lds_dwordx4 v[184:185], off
	s_waitcnt vmcnt(8) lgkmcnt(0)
	s_barrier
	s_setprio 1
	v_mfma_f32_16x16x32_bf16 v[116:119], v[152:155], v[188:191], v[116:119]
	v_mfma_f32_16x16x32_bf16 v[108:111], v[160:163], v[188:191], v[108:111]
	v_mfma_f32_16x16x32_bf16 v[104:107], v[152:155], v[196:199], v[104:107]
	v_mfma_f32_16x16x32_bf16 v[100:103], v[160:163], v[196:199], v[100:103]
	v_mfma_f32_16x16x32_bf16 v[92:95], v[152:155], v[204:207], v[92:95]
	v_mfma_f32_16x16x32_bf16 v[84:87], v[160:163], v[204:207], v[84:87]
	v_mfma_f32_16x16x32_bf16 v[76:79], v[152:155], v[212:215], v[76:79]
	v_mfma_f32_16x16x32_bf16 v[68:71], v[160:163], v[212:215], v[68:71]
	v_mfma_f32_16x16x32_bf16 v[116:119], v[156:159], v[192:195], v[116:119]
	v_mfma_f32_16x16x32_bf16 v[108:111], v[164:167], v[192:195], v[108:111]
	v_mfma_f32_16x16x32_bf16 v[104:107], v[156:159], v[200:203], v[104:107]
	v_mfma_f32_16x16x32_bf16 v[100:103], v[164:167], v[200:203], v[100:103]
	v_mfma_f32_16x16x32_bf16 v[92:95], v[156:159], v[208:211], v[92:95]
	v_mfma_f32_16x16x32_bf16 v[84:87], v[164:167], v[208:211], v[84:87]
	v_mfma_f32_16x16x32_bf16 v[76:79], v[156:159], v[216:219], v[76:79]
	v_mfma_f32_16x16x32_bf16 v[68:71], v[164:167], v[216:219], v[68:71]
	s_setprio 0
	s_setprio 1
	v_mfma_f32_16x16x32_bf16 v[124:127], v[168:171], v[188:191], v[124:127]
	v_mfma_f32_16x16x32_bf16 v[120:123], v[176:179], v[188:191], v[120:123]
	v_mfma_f32_16x16x32_bf16 v[112:115], v[168:171], v[196:199], v[112:115]
	v_mfma_f32_16x16x32_bf16 v[96:99], v[176:179], v[196:199], v[96:99]
	v_mfma_f32_16x16x32_bf16 v[88:91], v[168:171], v[204:207], v[88:91]
	v_mfma_f32_16x16x32_bf16 v[80:83], v[176:179], v[204:207], v[80:83]
	v_mfma_f32_16x16x32_bf16 v[72:75], v[168:171], v[212:215], v[72:75]
	v_mfma_f32_16x16x32_bf16 v[64:67], v[176:179], v[212:215], v[64:67]
	v_mfma_f32_16x16x32_bf16 v[124:127], v[172:175], v[192:195], v[124:127]
	v_mfma_f32_16x16x32_bf16 v[120:123], v[180:183], v[192:195], v[120:123]
	v_mfma_f32_16x16x32_bf16 v[112:115], v[172:175], v[200:203], v[112:115]
	v_mfma_f32_16x16x32_bf16 v[96:99], v[180:183], v[200:203], v[96:99]
	v_mfma_f32_16x16x32_bf16 v[88:91], v[172:175], v[208:211], v[88:91]
	v_mfma_f32_16x16x32_bf16 v[80:83], v[180:183], v[208:211], v[80:83]
	v_mfma_f32_16x16x32_bf16 v[72:75], v[172:175], v[216:219], v[72:75]
	v_mfma_f32_16x16x32_bf16 v[64:67], v[180:183], v[216:219], v[64:67]
	s_barrier
	s_setprio 0
	s_add_i32 s58, s46, s36
	v_lshl_add_u64 v[184:185], s[28:29], 0, v[132:133]
	s_mov_b32 m0, s58
	ds_read_b128 v[188:191], v149 offset:16384
	ds_read_b128 v[192:195], v149 offset:17408
	ds_read_b128 v[196:199], v149 offset:18432
	ds_read_b128 v[200:203], v149 offset:19456
	ds_read_b128 v[204:207], v149 offset:20480
	ds_read_b128 v[208:211], v149 offset:21504
	ds_read_b128 v[212:215], v149 offset:22528
	ds_read_b128 v[216:219], v149 offset:23552
	global_load_lds_dwordx4 v[184:185], off
	s_add_i32 m0, s58, 0x2000
	s_add_u32 s58, s28, 0x40000
	v_lshl_add_u64 v[220:221], s[28:29], 0, v[128:129]
	s_addc_u32 s59, s29, 0
	s_add_i32 s69, s47, s36
	global_load_lds_dwordx4 v[220:221], off
	v_lshl_add_u64 v[222:223], s[58:59], 0, v[132:133]
	s_mov_b32 m0, s69
	v_lshl_add_u64 v[224:225], s[30:31], 0, v[130:131]
	global_load_lds_dwordx4 v[222:223], off
	s_add_i32 m0, s69, 0x2000
	v_lshl_add_u64 v[222:223], s[58:59], 0, v[128:129]
	global_load_lds_dwordx4 v[222:223], off
	s_mov_b32 m0, s25
	v_lshl_add_u64 v[222:223], s[30:31], 0, v[134:135]
	global_load_lds_dwordx4 v[222:223], off
	s_mov_b32 m0, s39
	s_nop 0
	global_load_lds_dwordx4 v[224:225], off
	s_waitcnt vmcnt(8) lgkmcnt(0)
	s_barrier
; #define PG8_STAGE(bufoff, gbase, voff) do { _Pragma("unroll") for (int _i = 0; _i < 2; ++_i) \
;         __builtin_amdgcn_global_load_lds((const unsigned*)((const char*)(gbase) + (voff)[_i]), (PG8_LAS unsigned*)(lds + (bufoff) + ldsw + _i * 8192), 16, 0, 0); } while (0)
; #define PG8_LDA(dst, b, h) do { _Pragma("unroll") for (int m = 0; m < 4; ++m) _Pragma("unroll") for (int k = 0; k < 2; ++k) dst[m][k] = *(const PG8_LAS bf16x8*)(lds + PG8_SA(b, h) + aoff + m * 2048 + k * 1024); } while (0)
; #define PG8_LDB(dst, b, h) do { _Pragma("unroll") for (int n = 0; n < 2; ++n) _Pragma("unroll") for (int k = 0; k < 2; ++k) dst[n][k] = *(const PG8_LAS bf16x8*)(lds + PG8_SB(b, h) + boff + n * 2048 + k * 1024); } while (0)
; #define PG8_MMA(ai, bj, At, Bt) do { __builtin_amdgcn_s_setprio(1); _Pragma("unroll") for (int m = 0; m < 4; ++m) _Pragma("unroll") for (int n = 0; n < 2; ++n) _Pragma("unroll") for (int k = 0; k < 2; ++k) \
;         acc[ai][bj][m][n] = __builtin_amdgcn_mfma_f32_16x16x32_bf16(Bt[n][k], At[m][k], acc[ai][bj][m][n], 0, 0, 0); __builtin_amdgcn_s_setprio(0); } while (0)
; #define PG8_WAIT_V(n) asm volatile("s_waitcnt vmcnt(" #n ")" ::: "memory")
; #define PG8_WAIT_L(n) asm volatile("s_waitcnt lgkmcnt(" #n ")" ::: "memory")
; #define PG8_BAR __builtin_amdgcn_s_barrier()
; #define PG8_SCHED __builtin_amdgcn_sched_barrier(0)
; template <class Epi, class Sched, bool ALIGN_EPI = false, bool SP2 = false>
; __device__ __forceinline__ void gemm_phase(PG8_LAS unsigned char* lds, const Gemm g, const Sched& S, const Epi& E) {
;     ...
;             PG8_WAIT_V(8); PG8_WAIT_L(0); PG8_BAR; PG8_MMA(1, 0, At, B0); PG8_MMA(1, 1, At, B1); PG8_BAR; PG8_SCHED;
;             PG8_LDB(B0, 1, 0); PG8_LDB(B1, 1, 1); PG8_SCHED; PG8_LDA(At, 1, 0); PG8_STAGE(PG8_SA(0, 1), a2 + hstepA, voffA);
;             PG8_WAIT_V(8); PG8_WAIT_L(0); PG8_BAR; PG8_MMA(0, 0, At, B0); PG8_MMA(0, 1, At, B1); PG8_BAR; PG8_SCHED;
	s_setprio 1
	v_mfma_f32_16x16x32_bf16 v[60:63], v[152:155], v[188:191], v[60:63]
	v_mfma_f32_16x16x32_bf16 v[52:55], v[160:163], v[188:191], v[52:55]
	v_mfma_f32_16x16x32_bf16 v[44:47], v[152:155], v[196:199], v[44:47]
	v_mfma_f32_16x16x32_bf16 v[36:39], v[160:163], v[196:199], v[36:39]
	v_mfma_f32_16x16x32_bf16 v[28:31], v[152:155], v[204:207], v[28:31]
	v_mfma_f32_16x16x32_bf16 v[20:23], v[160:163], v[204:207], v[20:23]
	v_mfma_f32_16x16x32_bf16 v[12:15], v[152:155], v[212:215], v[12:15]
	v_mfma_f32_16x16x32_bf16 v[4:7], v[160:163], v[212:215], v[4:7]
	v_mfma_f32_16x16x32_bf16 v[60:63], v[156:159], v[192:195], v[60:63]
	v_mfma_f32_16x16x32_bf16 v[52:55], v[164:167], v[192:195], v[52:55]
	v_mfma_f32_16x16x32_bf16 v[44:47], v[156:159], v[200:203], v[44:47]
	v_mfma_f32_16x16x32_bf16 v[36:39], v[164:167], v[200:203], v[36:39]
	v_mfma_f32_16x16x32_bf16 v[28:31], v[156:159], v[208:211], v[28:31]
	v_mfma_f32_16x16x32_bf16 v[20:23], v[164:167], v[208:211], v[20:23]
	v_mfma_f32_16x16x32_bf16 v[12:15], v[156:159], v[216:219], v[12:15]
	v_mfma_f32_16x16x32_bf16 v[4:7], v[164:167], v[216:219], v[4:7]
	s_setprio 0
	s_setprio 1
	v_mfma_f32_16x16x32_bf16 v[56:59], v[168:171], v[188:191], v[56:59]
	v_mfma_f32_16x16x32_bf16 v[48:51], v[176:179], v[188:191], v[48:51]
	v_mfma_f32_16x16x32_bf16 v[40:43], v[168:171], v[196:199], v[40:43]
	v_mfma_f32_16x16x32_bf16 v[32:35], v[176:179], v[196:199], v[32:35]
	v_mfma_f32_16x16x32_bf16 v[24:27], v[168:171], v[204:207], v[24:27]
	v_mfma_f32_16x16x32_bf16 v[16:19], v[176:179], v[204:207], v[16:19]
	v_mfma_f32_16x16x32_bf16 v[8:11], v[168:171], v[212:215], v[8:11]
	v_mfma_f32_16x16x32_bf16 v[0:3], v[176:179], v[212:215], v[0:3]
	v_mfma_f32_16x16x32_bf16 v[56:59], v[172:175], v[192:195], v[56:59]
	v_mfma_f32_16x16x32_bf16 v[48:51], v[180:183], v[192:195], v[48:51]
	v_mfma_f32_16x16x32_bf16 v[40:43], v[172:175], v[200:203], v[40:43]
	v_mfma_f32_16x16x32_bf16 v[32:35], v[180:183], v[200:203], v[32:35]
	v_mfma_f32_16x16x32_bf16 v[24:27], v[172:175], v[208:211], v[24:27]
	v_mfma_f32_16x16x32_bf16 v[16:19], v[180:183], v[208:211], v[16:19]
	v_mfma_f32_16x16x32_bf16 v[8:11], v[172:175], v[216:219], v[8:11]
	v_mfma_f32_16x16x32_bf16 v[0:3], v[180:183], v[216:219], v[0:3]
	s_barrier
	s_setprio 0
	s_add_i32 s58, 0, 0x18000
	v_add_u32_e32 v151, s58, v145
	s_add_i32 s59, 0, 0x1c000
	ds_read_b128 v[152:155], v151
	ds_read_b128 v[156:159], v151 offset:1024
	ds_read_b128 v[160:163], v151 offset:2048
	ds_read_b128 v[164:167], v151 offset:3072
	v_add_u32_e32 v151, s59, v145
	ds_read_b128 v[168:171], v151
	ds_read_b128 v[172:175], v151 offset:1024
	ds_read_b128 v[176:179], v151 offset:2048
	ds_read_b128 v[180:183], v151 offset:3072
	s_add_u32 s30, s30, 0x40000
	s_addc_u32 s31, s31, 0
	s_mov_b32 m0, s40
	v_lshl_add_u64 v[226:227], s[30:31], 0, v[134:135]
	ds_read_b128 v[188:191], v149 offset:32768
	ds_read_b128 v[192:195], v149 offset:33792
	ds_read_b128 v[196:199], v149 offset:34816
	ds_read_b128 v[200:203], v149 offset:35840
	ds_read_b128 v[204:207], v149 offset:36864
	ds_read_b128 v[208:211], v149 offset:37888
	ds_read_b128 v[212:215], v149 offset:38912
	ds_read_b128 v[216:219], v149 offset:39936
	global_load_lds_dwordx4 v[226:227], off
	s_mov_b32 m0, s41
	v_lshl_add_u64 v[226:227], s[30:31], 0, v[130:131]
	global_load_lds_dwordx4 v[226:227], off
	s_waitcnt vmcnt(8) lgkmcnt(0)
	s_barrier
	s_setprio 1
	v_mfma_f32_16x16x32_bf16 v[116:119], v[152:155], v[188:191], v[116:119]
	v_mfma_f32_16x16x32_bf16 v[108:111], v[160:163], v[188:191], v[108:111]
	v_mfma_f32_16x16x32_bf16 v[104:107], v[152:155], v[196:199], v[104:107]
	v_mfma_f32_16x16x32_bf16 v[100:103], v[160:163], v[196:199], v[100:103]
	v_mfma_f32_16x16x32_bf16 v[92:95], v[152:155], v[204:207], v[92:95]
	v_mfma_f32_16x16x32_bf16 v[84:87], v[160:163], v[204:207], v[84:87]
	v_mfma_f32_16x16x32_bf16 v[76:79], v[152:155], v[212:215], v[76:79]
	v_mfma_f32_16x16x32_bf16 v[68:71], v[160:163], v[212:215], v[68:71]
	v_mfma_f32_16x16x32_bf16 v[116:119], v[156:159], v[192:195], v[116:119]
	v_mfma_f32_16x16x32_bf16 v[108:111], v[164:167], v[192:195], v[108:111]
	v_mfma_f32_16x16x32_bf16 v[104:107], v[156:159], v[200:203], v[104:107]
	v_mfma_f32_16x16x32_bf16 v[100:103], v[164:167], v[200:203], v[100:103]
	v_mfma_f32_16x16x32_bf16 v[92:95], v[156:159], v[208:211], v[92:95]
	v_mfma_f32_16x16x32_bf16 v[84:87], v[164:167], v[208:211], v[84:87]
	v_mfma_f32_16x16x32_bf16 v[76:79], v[156:159], v[216:219], v[76:79]
	v_mfma_f32_16x16x32_bf16 v[68:71], v[164:167], v[216:219], v[68:71]
	s_setprio 0
	s_setprio 1
	v_mfma_f32_16x16x32_bf16 v[124:127], v[168:171], v[188:191], v[124:127]
	v_mfma_f32_16x16x32_bf16 v[120:123], v[176:179], v[188:191], v[120:123]
	v_mfma_f32_16x16x32_bf16 v[112:115], v[168:171], v[196:199], v[112:115]
	v_mfma_f32_16x16x32_bf16 v[96:99], v[176:179], v[196:199], v[96:99]
	v_mfma_f32_16x16x32_bf16 v[88:91], v[168:171], v[204:207], v[88:91]
	v_mfma_f32_16x16x32_bf16 v[80:83], v[176:179], v[204:207], v[80:83]
	v_mfma_f32_16x16x32_bf16 v[72:75], v[168:171], v[212:215], v[72:75]
	v_mfma_f32_16x16x32_bf16 v[64:67], v[176:179], v[212:215], v[64:67]
	v_mfma_f32_16x16x32_bf16 v[124:127], v[172:175], v[192:195], v[124:127]
	v_mfma_f32_16x16x32_bf16 v[120:123], v[180:183], v[192:195], v[120:123]
	v_mfma_f32_16x16x32_bf16 v[112:115], v[172:175], v[200:203], v[112:115]
	v_mfma_f32_16x16x32_bf16 v[96:99], v[180:183], v[200:203], v[96:99]
	v_mfma_f32_16x16x32_bf16 v[88:91], v[172:175], v[208:211], v[88:91]
	v_mfma_f32_16x16x32_bf16 v[80:83], v[180:183], v[208:211], v[80:83]
	v_mfma_f32_16x16x32_bf16 v[72:75], v[172:175], v[216:219], v[72:75]
	v_mfma_f32_16x16x32_bf16 v[64:67], v[180:183], v[216:219], v[64:67]
	s_barrier
; #define PG8_STAGE(bufoff, gbase, voff) do { _Pragma("unroll") for (int _i = 0; _i < 2; ++_i) \
;         __builtin_amdgcn_global_load_lds((const unsigned*)((const char*)(gbase) + (voff)[_i]), (PG8_LAS unsigned*)(lds + (bufoff) + ldsw + _i * 8192), 16, 0, 0); } while (0)
; #define PG8_LDA(dst, b, h) do { _Pragma("unroll") for (int m = 0; m < 4; ++m) _Pragma("unroll") for (int k = 0; k < 2; ++k) dst[m][k] = *(const PG8_LAS bf16x8*)(lds + PG8_SA(b, h) + aoff + m * 2048 + k * 1024); } while (0)
; #define PG8_MMA(ai, bj, At, Bt) do { __builtin_amdgcn_s_setprio(1); _Pragma("unroll") for (int m = 0; m < 4; ++m) _Pragma("unroll") for (int n = 0; n < 2; ++n) _Pragma("unroll") for (int k = 0; k < 2; ++k) \
;         acc[ai][bj][m][n] = __builtin_amdgcn_mfma_f32_16x16x32_bf16(Bt[n][k], At[m][k], acc[ai][bj][m][n], 0, 0, 0); __builtin_amdgcn_s_setprio(0); } while (0)
; #define PG8_WAIT_V(n) asm volatile("s_waitcnt vmcnt(" #n ")" ::: "memory")
; #define PG8_WAIT_L(n) asm volatile("s_waitcnt lgkmcnt(" #n ")" ::: "memory")
; #define PG8_BAR __builtin_amdgcn_s_barrier()
; #define PG8_SCHED __builtin_amdgcn_sched_barrier(0)
; template <class Epi, class Sched, bool ALIGN_EPI = false, bool SP2 = false>
; __device__ __forceinline__ void gemm_phase(PG8_LAS unsigned char* lds, const Gemm g, const Sched& S, const Epi& E) {
;     ...
;             PG8_LDA(At, 1, 1); PG8_STAGE(PG8_SB(1, 0), b3, voffB); PG8_STAGE(PG8_SB(1, 1), b3 + hstepB, voffB); PG8_STAGE(PG8_SA(1, 0), a3, voffA);
;             PG8_WAIT_V(8); PG8_WAIT_L(0); PG8_BAR; PG8_MMA(1, 0, At, B0); PG8_MMA(1, 1, At, B1); PG8_BAR; PG8_SCHED;
;     ...
;         if constexpr (ALIGN_EPI) { if (wr == 0) PG8_BAR; }
	s_setprio 0
	s_add_i32 s30, s58, s36
	v_lshl_add_u64 v[184:185], v[184:185], 0, s[8:9]
	s_mov_b32 m0, s30
	ds_read_b128 v[188:191], v149 offset:49152
	ds_read_b128 v[192:195], v149 offset:50176
	ds_read_b128 v[196:199], v149 offset:51200
	ds_read_b128 v[200:203], v149 offset:52224
	ds_read_b128 v[204:207], v149 offset:53248
	ds_read_b128 v[208:211], v149 offset:54272
	ds_read_b128 v[212:215], v149 offset:55296
	ds_read_b128 v[216:219], v149 offset:56320
	global_load_lds_dwordx4 v[184:185], off
	s_add_i32 m0, s30, 0x2000
	s_add_u32 s28, s28, 0x40080
	v_lshl_add_u64 v[184:185], v[220:221], 0, s[8:9]
	s_addc_u32 s29, s29, 0
	s_add_i32 s30, s59, s36
	global_load_lds_dwordx4 v[184:185], off
	s_mov_b32 m0, s30
	v_lshl_add_u64 v[184:185], s[28:29], 0, v[132:133]
	global_load_lds_dwordx4 v[184:185], off
	s_add_i32 m0, s30, 0x2000
	v_lshl_add_u64 v[184:185], s[28:29], 0, v[128:129]
	global_load_lds_dwordx4 v[184:185], off
	s_mov_b32 m0, s43
	v_lshl_add_u64 v[184:185], v[222:223], 0, s[8:9]
	global_load_lds_dwordx4 v[184:185], off
	s_mov_b32 m0, s44
	v_lshl_add_u64 v[184:185], v[224:225], 0, s[8:9]
	global_load_lds_dwordx4 v[184:185], off
	s_waitcnt vmcnt(8) lgkmcnt(0)
	s_barrier
	s_setprio 1
	v_mfma_f32_16x16x32_bf16 v[60:63], v[152:155], v[188:191], v[60:63]
	v_mfma_f32_16x16x32_bf16 v[52:55], v[160:163], v[188:191], v[52:55]
	v_mfma_f32_16x16x32_bf16 v[44:47], v[152:155], v[196:199], v[44:47]
	v_mfma_f32_16x16x32_bf16 v[36:39], v[160:163], v[196:199], v[36:39]
	v_mfma_f32_16x16x32_bf16 v[28:31], v[152:155], v[204:207], v[28:31]
	v_mfma_f32_16x16x32_bf16 v[20:23], v[160:163], v[204:207], v[20:23]
	v_mfma_f32_16x16x32_bf16 v[12:15], v[152:155], v[212:215], v[12:15]
	v_mfma_f32_16x16x32_bf16 v[4:7], v[160:163], v[212:215], v[4:7]
	v_mfma_f32_16x16x32_bf16 v[60:63], v[156:159], v[192:195], v[60:63]
	v_mfma_f32_16x16x32_bf16 v[52:55], v[164:167], v[192:195], v[52:55]
	v_mfma_f32_16x16x32_bf16 v[44:47], v[156:159], v[200:203], v[44:47]
	v_mfma_f32_16x16x32_bf16 v[36:39], v[164:167], v[200:203], v[36:39]
	v_mfma_f32_16x16x32_bf16 v[28:31], v[156:159], v[208:211], v[28:31]
	v_mfma_f32_16x16x32_bf16 v[20:23], v[164:167], v[208:211], v[20:23]
	v_mfma_f32_16x16x32_bf16 v[12:15], v[156:159], v[216:219], v[12:15]
	v_mfma_f32_16x16x32_bf16 v[4:7], v[164:167], v[216:219], v[4:7]
	s_setprio 0
	s_setprio 1
	v_mfma_f32_16x16x32_bf16 v[56:59], v[168:171], v[188:191], v[56:59]
	v_mfma_f32_16x16x32_bf16 v[48:51], v[176:179], v[188:191], v[48:51]
	v_mfma_f32_16x16x32_bf16 v[40:43], v[168:171], v[196:199], v[40:43]
	v_mfma_f32_16x16x32_bf16 v[32:35], v[176:179], v[196:199], v[32:35]
	v_mfma_f32_16x16x32_bf16 v[24:27], v[168:171], v[204:207], v[24:27]
	v_mfma_f32_16x16x32_bf16 v[16:19], v[176:179], v[204:207], v[16:19]
	v_mfma_f32_16x16x32_bf16 v[8:11], v[168:171], v[212:215], v[8:11]
	v_mfma_f32_16x16x32_bf16 v[0:3], v[176:179], v[212:215], v[0:3]
	v_mfma_f32_16x16x32_bf16 v[56:59], v[172:175], v[192:195], v[56:59]
	v_mfma_f32_16x16x32_bf16 v[48:51], v[180:183], v[192:195], v[48:51]
	v_mfma_f32_16x16x32_bf16 v[40:43], v[172:175], v[200:203], v[40:43]
	v_mfma_f32_16x16x32_bf16 v[32:35], v[180:183], v[200:203], v[32:35]
	v_mfma_f32_16x16x32_bf16 v[24:27], v[172:175], v[208:211], v[24:27]
	v_mfma_f32_16x16x32_bf16 v[16:19], v[180:183], v[208:211], v[16:19]
	v_mfma_f32_16x16x32_bf16 v[8:11], v[172:175], v[216:219], v[8:11]
	v_mfma_f32_16x16x32_bf16 v[0:3], v[180:183], v[216:219], v[0:3]
	s_barrier
	s_setprio 0
	s_add_i32 s68, s68, 2
	s_add_u32 s26, s26, 0x100
	s_addc_u32 s27, s27, 0
	s_add_u32 s66, s66, 0x100
	s_addc_u32 s67, s67, 0
	s_cmp_gt_u32 s68, 13
	s_cbranch_scc0 .LBB0_244
	s_and_b64 vcc, exec, s[10:11]
	s_cbranch_vccz .LBB0_247
	s_barrier

; #define PG8_STAGE(bufoff, gbase, voff) do { _Pragma("unroll") for (int _i = 0; _i < 2; ++_i) \
;         __builtin_amdgcn_global_load_lds((const unsigned*)((const char*)(gbase) + (voff)[_i]), (PG8_LAS unsigned*)(lds + (bufoff) + ldsw + _i * 8192), 16, 0, 0); } while (0)
; #define PG8_LDA(dst, b, h) do { _Pragma("unroll") for (int m = 0; m < 4; ++m) _Pragma("unroll") for (int k = 0; k < 2; ++k) dst[m][k] = *(const PG8_LAS bf16x8*)(lds + PG8_SA(b, h) + aoff + m * 2048 + k * 1024); } while (0)
; #define PG8_LDB(dst, b, h) do { _Pragma("unroll") for (int n = 0; n < 2; ++n) _Pragma("unroll") for (int k = 0; k < 2; ++k) dst[n][k] = *(const PG8_LAS bf16x8*)(lds + PG8_SB(b, h) + boff + n * 2048 + k * 1024); } while (0)
; #define PG8_MMA(ai, bj, At, Bt) do { __builtin_amdgcn_s_setprio(1); _Pragma("unroll") for (int m = 0; m < 4; ++m) _Pragma("unroll") for (int n = 0; n < 2; ++n) _Pragma("unroll") for (int k = 0; k < 2; ++k) \
;         acc[ai][bj][m][n] = __builtin_amdgcn_mfma_f32_16x16x32_bf16(Bt[n][k], At[m][k], acc[ai][bj][m][n], 0, 0, 0); __builtin_amdgcn_s_setprio(0); } while (0)
; #define PG8_WAIT_V(n) asm volatile("s_waitcnt vmcnt(" #n ")" ::: "memory")
; #define PG8_WAIT_L(n) asm volatile("s_waitcnt lgkmcnt(" #n ")" ::: "memory")
; #define PG8_BAR __builtin_amdgcn_s_barrier()
; #define PG8_SCHED __builtin_amdgcn_sched_barrier(0)
; template <class Epi, class Sched, bool ALIGN_EPI = false, bool SP2 = false>
; __device__ __forceinline__ void gemm_phase(PG8_LAS unsigned char* lds, const Gemm g, const Sched& S, const Epi& E) {
;     ...
;             const bool last = (t == nt - 2);
;             const char* a1 = cA + (size_t)(t + 1) * kstep;
;             const char* a2 = last ? nA : cA + (size_t)(t + 2) * kstep; const char* b2 = last ? nB : cB + (size_t)(t + 2) * kstep;
;             const char* a3 = a2 + kstep; const char* b3 = b2 + kstep;
;             if (last && has_next) S.a_ready(nxt);
;             if constexpr (SP2) {
;             PG8_LDB(B0, 0, 0); PG8_LDB(B1, 0, 1); PG8_SCHED; PG8_LDA(At, 0, 0); PG8_STAGE(PG8_SA(1, 1), a1 + hstepA, voffA);
;             PG8_WAIT_V(8); PG8_WAIT_L(0); PG8_BAR; PG8_MMA(0, 0, At, B0); PG8_MMA(0, 1, At, B1); PG8_BAR; PG8_SCHED;
;             PG8_LDA(At, 0, 1); PG8_STAGE(PG8_SB(0, 0), b2, voffB); PG8_STAGE(PG8_SB(0, 1), b2 + hstepB, voffB); PG8_STAGE(PG8_SA(0, 0), a2, voffA);
.LBB0_318:
	ds_read_b128 v[128:131], v191
	ds_read_b128 v[132:135], v191 offset:1024
	ds_read_b128 v[136:139], v191 offset:2048
	ds_read_b128 v[140:143], v191 offset:3072
	ds_read_b128 v[144:147], v192
	ds_read_b128 v[148:151], v192 offset:1024
	ds_read_b128 v[168:171], v192 offset:2048
	ds_read_b128 v[172:175], v192 offset:3072
	s_add_u32 s28, s26, 0x100
	s_addc_u32 s29, s27, 0
	s_cmp_eq_u32 s72, 40
	s_cselect_b32 s35, s11, s29
	s_cselect_b32 s34, s10, s28
	s_cselect_b32 s31, s23, s71
	s_cselect_b32 s30, s22, s70
	v_lshl_add_u64 v[184:185], s[26:27], 0, v[160:161]
	s_add_i32 m0, s39, 0xc000
	ds_read_b128 v[176:179], v193
	ds_read_b128 v[180:183], v193 offset:1024
	ds_read_b128 v[196:199], v193 offset:2048
	ds_read_b128 v[200:203], v193 offset:3072
	ds_read_b128 v[204:207], v193 offset:4096
	ds_read_b128 v[208:211], v193 offset:5120
	ds_read_b128 v[212:215], v193 offset:6144
	ds_read_b128 v[216:219], v193 offset:7168
	global_load_lds_dwordx4 v[184:185], off
	s_add_i32 m0, s39, 0xe000
	v_lshl_add_u64 v[184:185], s[26:27], 0, v[162:163]
	global_load_lds_dwordx4 v[184:185], off
	s_waitcnt vmcnt(8) lgkmcnt(0)
	s_barrier
	s_setprio 1
	v_mfma_f32_16x16x32_bf16 v[124:127], v[128:131], v[176:179], v[124:127]
	v_mfma_f32_16x16x32_bf16 v[120:123], v[136:139], v[176:179], v[120:123]
	v_mfma_f32_16x16x32_bf16 v[108:111], v[128:131], v[196:199], v[108:111]
	v_mfma_f32_16x16x32_bf16 v[104:107], v[136:139], v[196:199], v[104:107]
	v_mfma_f32_16x16x32_bf16 v[92:95], v[128:131], v[204:207], v[92:95]
	v_mfma_f32_16x16x32_bf16 v[88:91], v[136:139], v[204:207], v[88:91]
	v_mfma_f32_16x16x32_bf16 v[76:79], v[128:131], v[212:215], v[76:79]
	v_mfma_f32_16x16x32_bf16 v[72:75], v[136:139], v[212:215], v[72:75]
	v_mfma_f32_16x16x32_bf16 v[124:127], v[132:135], v[180:183], v[124:127]
	v_mfma_f32_16x16x32_bf16 v[120:123], v[140:143], v[180:183], v[120:123]
	v_mfma_f32_16x16x32_bf16 v[108:111], v[132:135], v[200:203], v[108:111]
	v_mfma_f32_16x16x32_bf16 v[104:107], v[140:143], v[200:203], v[104:107]
	v_mfma_f32_16x16x32_bf16 v[92:95], v[132:135], v[208:211], v[92:95]
	v_mfma_f32_16x16x32_bf16 v[88:91], v[140:143], v[208:211], v[88:91]
	v_mfma_f32_16x16x32_bf16 v[76:79], v[132:135], v[216:219], v[76:79]
	v_mfma_f32_16x16x32_bf16 v[72:75], v[140:143], v[216:219], v[72:75]
	s_setprio 0
	s_setprio 1
	v_mfma_f32_16x16x32_bf16 v[116:119], v[144:147], v[176:179], v[116:119]
	v_mfma_f32_16x16x32_bf16 v[112:115], v[168:171], v[176:179], v[112:115]
	v_mfma_f32_16x16x32_bf16 v[100:103], v[144:147], v[196:199], v[100:103]
	v_mfma_f32_16x16x32_bf16 v[96:99], v[168:171], v[196:199], v[96:99]
	v_mfma_f32_16x16x32_bf16 v[84:87], v[144:147], v[204:207], v[84:87]
	v_mfma_f32_16x16x32_bf16 v[80:83], v[168:171], v[204:207], v[80:83]
	v_mfma_f32_16x16x32_bf16 v[68:71], v[144:147], v[212:215], v[68:71]
	v_mfma_f32_16x16x32_bf16 v[64:67], v[168:171], v[212:215], v[64:67]
	v_mfma_f32_16x16x32_bf16 v[116:119], v[148:151], v[180:183], v[116:119]
	v_mfma_f32_16x16x32_bf16 v[112:115], v[172:175], v[180:183], v[112:115]
	v_mfma_f32_16x16x32_bf16 v[100:103], v[148:151], v[200:203], v[100:103]
	v_mfma_f32_16x16x32_bf16 v[96:99], v[172:175], v[200:203], v[96:99]
	v_mfma_f32_16x16x32_bf16 v[84:87], v[148:151], v[208:211], v[84:87]
	v_mfma_f32_16x16x32_bf16 v[80:83], v[172:175], v[208:211], v[80:83]
	v_mfma_f32_16x16x32_bf16 v[68:71], v[148:151], v[216:219], v[68:71]
	v_mfma_f32_16x16x32_bf16 v[64:67], v[172:175], v[216:219], v[64:67]
	s_barrier
	s_setprio 0
	s_add_i32 s26, s49, s38
	v_lshl_add_u64 v[184:185], s[30:31], 0, v[154:155]
	s_mov_b32 m0, s26
	ds_read_b128 v[176:179], v193 offset:16384
	ds_read_b128 v[180:183], v193 offset:17408
	ds_read_b128 v[196:199], v193 offset:18432
	ds_read_b128 v[200:203], v193 offset:19456
	ds_read_b128 v[204:207], v193 offset:20480
	ds_read_b128 v[208:211], v193 offset:21504
	ds_read_b128 v[212:215], v193 offset:22528
	ds_read_b128 v[216:219], v193 offset:23552
	global_load_lds_dwordx4 v[184:185], off
	s_add_i32 m0, s26, 0x2000
	s_add_u32 s26, s30, 0xb0000
	v_lshl_add_u64 v[220:221], s[30:31], 0, v[158:159]
	s_addc_u32 s27, s31, 0
	s_add_i32 s58, s62, s38
	global_load_lds_dwordx4 v[220:221], off
	v_lshl_add_u64 v[222:223], s[26:27], 0, v[154:155]
	s_mov_b32 m0, s58
	v_lshl_add_u64 v[224:225], s[34:35], 0, v[156:157]
	global_load_lds_dwordx4 v[222:223], off
	s_add_i32 m0, s58, 0x2000
	v_lshl_add_u64 v[222:223], s[26:27], 0, v[158:159]
	global_load_lds_dwordx4 v[222:223], off
	s_mov_b32 m0, s39
	v_lshl_add_u64 v[222:223], s[34:35], 0, v[152:153]
	global_load_lds_dwordx4 v[222:223], off
	s_mov_b32 m0, s40
	s_nop 0
	global_load_lds_dwordx4 v[224:225], off
	s_waitcnt vmcnt(8) lgkmcnt(0)
	s_barrier
; #define PG8_STAGE(bufoff, gbase, voff) do { _Pragma("unroll") for (int _i = 0; _i < 2; ++_i) \
;         __builtin_amdgcn_global_load_lds((const unsigned*)((const char*)(gbase) + (voff)[_i]), (PG8_LAS unsigned*)(lds + (bufoff) + ldsw + _i * 8192), 16, 0, 0); } while (0)
; #define PG8_LDA(dst, b, h) do { _Pragma("unroll") for (int m = 0; m < 4; ++m) _Pragma("unroll") for (int k = 0; k < 2; ++k) dst[m][k] = *(const PG8_LAS bf16x8*)(lds + PG8_SA(b, h) + aoff + m * 2048 + k * 1024); } while (0)
; #define PG8_LDB(dst, b, h) do { _Pragma("unroll") for (int n = 0; n < 2; ++n) _Pragma("unroll") for (int k = 0; k < 2; ++k) dst[n][k] = *(const PG8_LAS bf16x8*)(lds + PG8_SB(b, h) + boff + n * 2048 + k * 1024); } while (0)
; #define PG8_MMA(ai, bj, At, Bt) do { __builtin_amdgcn_s_setprio(1); _Pragma("unroll") for (int m = 0; m < 4; ++m) _Pragma("unroll") for (int n = 0; n < 2; ++n) _Pragma("unroll") for (int k = 0; k < 2; ++k) \
;         acc[ai][bj][m][n] = __builtin_amdgcn_mfma_f32_16x16x32_bf16(Bt[n][k], At[m][k], acc[ai][bj][m][n], 0, 0, 0); __builtin_amdgcn_s_setprio(0); } while (0)
; #define PG8_WAIT_V(n) asm volatile("s_waitcnt vmcnt(" #n ")" ::: "memory")
; #define PG8_WAIT_L(n) asm volatile("s_waitcnt lgkmcnt(" #n ")" ::: "memory")
; #define PG8_BAR __builtin_amdgcn_s_barrier()
; #define PG8_SCHED __builtin_amdgcn_sched_barrier(0)
; template <class Epi, class Sched, bool ALIGN_EPI = false, bool SP2 = false>
; __device__ __forceinline__ void gemm_phase(PG8_LAS unsigned char* lds, const Gemm g, const Sched& S, const Epi& E) {
;     ...
;             PG8_WAIT_V(8); PG8_WAIT_L(0); PG8_BAR; PG8_MMA(1, 0, At, B0); PG8_MMA(1, 1, At, B1); PG8_BAR; PG8_SCHED;
;             PG8_LDB(B0, 1, 0); PG8_LDB(B1, 1, 1); PG8_SCHED; PG8_LDA(At, 1, 0); PG8_STAGE(PG8_SA(0, 1), a2 + hstepA, voffA);
;             PG8_WAIT_V(8); PG8_WAIT_L(0); PG8_BAR; PG8_MMA(0, 0, At, B0); PG8_MMA(0, 1, At, B1); PG8_BAR; PG8_SCHED;
	s_setprio 1
	v_mfma_f32_16x16x32_bf16 v[60:63], v[128:131], v[176:179], v[60:63]
	v_mfma_f32_16x16x32_bf16 v[56:59], v[136:139], v[176:179], v[56:59]
	v_mfma_f32_16x16x32_bf16 v[44:47], v[128:131], v[196:199], v[44:47]
	v_mfma_f32_16x16x32_bf16 v[40:43], v[136:139], v[196:199], v[40:43]
	v_mfma_f32_16x16x32_bf16 v[28:31], v[128:131], v[204:207], v[28:31]
	v_mfma_f32_16x16x32_bf16 v[24:27], v[136:139], v[204:207], v[24:27]
	v_mfma_f32_16x16x32_bf16 v[12:15], v[128:131], v[212:215], v[12:15]
	v_mfma_f32_16x16x32_bf16 v[8:11], v[136:139], v[212:215], v[8:11]
	v_mfma_f32_16x16x32_bf16 v[60:63], v[132:135], v[180:183], v[60:63]
	v_mfma_f32_16x16x32_bf16 v[56:59], v[140:143], v[180:183], v[56:59]
	v_mfma_f32_16x16x32_bf16 v[44:47], v[132:135], v[200:203], v[44:47]
	v_mfma_f32_16x16x32_bf16 v[40:43], v[140:143], v[200:203], v[40:43]
	v_mfma_f32_16x16x32_bf16 v[28:31], v[132:135], v[208:211], v[28:31]
	v_mfma_f32_16x16x32_bf16 v[24:27], v[140:143], v[208:211], v[24:27]
	v_mfma_f32_16x16x32_bf16 v[12:15], v[132:135], v[216:219], v[12:15]
	v_mfma_f32_16x16x32_bf16 v[8:11], v[140:143], v[216:219], v[8:11]
	s_setprio 0
	s_setprio 1
	v_mfma_f32_16x16x32_bf16 v[52:55], v[144:147], v[176:179], v[52:55]
	v_mfma_f32_16x16x32_bf16 v[48:51], v[168:171], v[176:179], v[48:51]
	v_mfma_f32_16x16x32_bf16 v[36:39], v[144:147], v[196:199], v[36:39]
	v_mfma_f32_16x16x32_bf16 v[32:35], v[168:171], v[196:199], v[32:35]
	v_mfma_f32_16x16x32_bf16 v[20:23], v[144:147], v[204:207], v[20:23]
	v_mfma_f32_16x16x32_bf16 v[16:19], v[168:171], v[204:207], v[16:19]
	v_mfma_f32_16x16x32_bf16 v[4:7], v[144:147], v[212:215], v[4:7]
	v_mfma_f32_16x16x32_bf16 v[0:3], v[168:171], v[212:215], v[0:3]
	v_mfma_f32_16x16x32_bf16 v[52:55], v[148:151], v[180:183], v[52:55]
	v_mfma_f32_16x16x32_bf16 v[48:51], v[172:175], v[180:183], v[48:51]
	v_mfma_f32_16x16x32_bf16 v[36:39], v[148:151], v[200:203], v[36:39]
	v_mfma_f32_16x16x32_bf16 v[32:35], v[172:175], v[200:203], v[32:35]
	v_mfma_f32_16x16x32_bf16 v[20:23], v[148:151], v[208:211], v[20:23]
	v_mfma_f32_16x16x32_bf16 v[16:19], v[172:175], v[208:211], v[16:19]
	v_mfma_f32_16x16x32_bf16 v[4:7], v[148:151], v[216:219], v[4:7]
	v_mfma_f32_16x16x32_bf16 v[0:3], v[172:175], v[216:219], v[0:3]
	s_barrier
	s_setprio 0
	s_add_i32 s58, 0, 0x18000
	s_add_i32 s59, 0, 0x1c000
	v_add_u32_e32 v140, s58, v189
	v_add_u32_e32 v172, s59, v189
	ds_read_b128 v[128:131], v140
	ds_read_b128 v[132:135], v140 offset:1024
	ds_read_b128 v[136:139], v140 offset:2048
	ds_read_b128 v[140:143], v140 offset:3072
	ds_read_b128 v[144:147], v172
	ds_read_b128 v[148:151], v172 offset:1024
	ds_read_b128 v[168:171], v172 offset:2048
	ds_read_b128 v[172:175], v172 offset:3072
	s_add_u32 s26, s34, 0xb0000
	s_addc_u32 s27, s35, 0
	s_mov_b32 m0, s41
	v_lshl_add_u64 v[226:227], s[26:27], 0, v[152:153]
	ds_read_b128 v[176:179], v193 offset:32768
	ds_read_b128 v[180:183], v193 offset:33792
	ds_read_b128 v[196:199], v193 offset:34816
	ds_read_b128 v[200:203], v193 offset:35840
	ds_read_b128 v[204:207], v193 offset:36864
	ds_read_b128 v[208:211], v193 offset:37888
	ds_read_b128 v[212:215], v193 offset:38912
	ds_read_b128 v[216:219], v193 offset:39936
	global_load_lds_dwordx4 v[226:227], off
	s_mov_b32 m0, s42
	v_lshl_add_u64 v[226:227], s[26:27], 0, v[156:157]
	global_load_lds_dwordx4 v[226:227], off
	s_waitcnt vmcnt(8) lgkmcnt(0)
	s_barrier
	s_setprio 1
	v_mfma_f32_16x16x32_bf16 v[124:127], v[128:131], v[176:179], v[124:127]
	v_mfma_f32_16x16x32_bf16 v[120:123], v[136:139], v[176:179], v[120:123]
	v_mfma_f32_16x16x32_bf16 v[108:111], v[128:131], v[196:199], v[108:111]
	v_mfma_f32_16x16x32_bf16 v[104:107], v[136:139], v[196:199], v[104:107]
	v_mfma_f32_16x16x32_bf16 v[92:95], v[128:131], v[204:207], v[92:95]
	v_mfma_f32_16x16x32_bf16 v[88:91], v[136:139], v[204:207], v[88:91]
	v_mfma_f32_16x16x32_bf16 v[76:79], v[128:131], v[212:215], v[76:79]
	v_mfma_f32_16x16x32_bf16 v[72:75], v[136:139], v[212:215], v[72:75]
	v_mfma_f32_16x16x32_bf16 v[124:127], v[132:135], v[180:183], v[124:127]
	v_mfma_f32_16x16x32_bf16 v[120:123], v[140:143], v[180:183], v[120:123]
	v_mfma_f32_16x16x32_bf16 v[108:111], v[132:135], v[200:203], v[108:111]
	v_mfma_f32_16x16x32_bf16 v[104:107], v[140:143], v[200:203], v[104:107]
	v_mfma_f32_16x16x32_bf16 v[92:95], v[132:135], v[208:211], v[92:95]
	v_mfma_f32_16x16x32_bf16 v[88:91], v[140:143], v[208:211], v[88:91]
	v_mfma_f32_16x16x32_bf16 v[76:79], v[132:135], v[216:219], v[76:79]
	v_mfma_f32_16x16x32_bf16 v[72:75], v[140:143], v[216:219], v[72:75]
	s_setprio 0
	s_setprio 1
	v_mfma_f32_16x16x32_bf16 v[116:119], v[144:147], v[176:179], v[116:119]
	v_mfma_f32_16x16x32_bf16 v[112:115], v[168:171], v[176:179], v[112:115]
	v_mfma_f32_16x16x32_bf16 v[100:103], v[144:147], v[196:199], v[100:103]
	v_mfma_f32_16x16x32_bf16 v[96:99], v[168:171], v[196:199], v[96:99]
	v_mfma_f32_16x16x32_bf16 v[84:87], v[144:147], v[204:207], v[84:87]
	v_mfma_f32_16x16x32_bf16 v[80:83], v[168:171], v[204:207], v[80:83]
	v_mfma_f32_16x16x32_bf16 v[68:71], v[144:147], v[212:215], v[68:71]
	v_mfma_f32_16x16x32_bf16 v[64:67], v[168:171], v[212:215], v[64:67]
	v_mfma_f32_16x16x32_bf16 v[116:119], v[148:151], v[180:183], v[116:119]
	v_mfma_f32_16x16x32_bf16 v[112:115], v[172:175], v[180:183], v[112:115]
	v_mfma_f32_16x16x32_bf16 v[100:103], v[148:151], v[200:203], v[100:103]
	v_mfma_f32_16x16x32_bf16 v[96:99], v[172:175], v[200:203], v[96:99]
	v_mfma_f32_16x16x32_bf16 v[84:87], v[148:151], v[208:211], v[84:87]
	v_mfma_f32_16x16x32_bf16 v[80:83], v[172:175], v[208:211], v[80:83]
	v_mfma_f32_16x16x32_bf16 v[68:71], v[148:151], v[216:219], v[68:71]
	v_mfma_f32_16x16x32_bf16 v[64:67], v[172:175], v[216:219], v[64:67]
	s_barrier
; #define PG8_STAGE(bufoff, gbase, voff) do { _Pragma("unroll") for (int _i = 0; _i < 2; ++_i) \
;         __builtin_amdgcn_global_load_lds((const unsigned*)((const char*)(gbase) + (voff)[_i]), (PG8_LAS unsigned*)(lds + (bufoff) + ldsw + _i * 8192), 16, 0, 0); } while (0)
; #define PG8_LDA(dst, b, h) do { _Pragma("unroll") for (int m = 0; m < 4; ++m) _Pragma("unroll") for (int k = 0; k < 2; ++k) dst[m][k] = *(const PG8_LAS bf16x8*)(lds + PG8_SA(b, h) + aoff + m * 2048 + k * 1024); } while (0)
; #define PG8_MMA(ai, bj, At, Bt) do { __builtin_amdgcn_s_setprio(1); _Pragma("unroll") for (int m = 0; m < 4; ++m) _Pragma("unroll") for (int n = 0; n < 2; ++n) _Pragma("unroll") for (int k = 0; k < 2; ++k) \
;         acc[ai][bj][m][n] = __builtin_amdgcn_mfma_f32_16x16x32_bf16(Bt[n][k], At[m][k], acc[ai][bj][m][n], 0, 0, 0); __builtin_amdgcn_s_setprio(0); } while (0)
; #define PG8_WAIT_V(n) asm volatile("s_waitcnt vmcnt(" #n ")" ::: "memory")
; #define PG8_WAIT_L(n) asm volatile("s_waitcnt lgkmcnt(" #n ")" ::: "memory")
; #define PG8_BAR __builtin_amdgcn_s_barrier()
; #define PG8_SCHED __builtin_amdgcn_sched_barrier(0)
; template <class Epi, class Sched, bool ALIGN_EPI = false, bool SP2 = false>
; __device__ __forceinline__ void gemm_phase(PG8_LAS unsigned char* lds, const Gemm g, const Sched& S, const Epi& E) {
;     ...
;             PG8_LDA(At, 1, 1); PG8_STAGE(PG8_SB(1, 0), b3, voffB); PG8_STAGE(PG8_SB(1, 1), b3 + hstepB, voffB); PG8_STAGE(PG8_SA(1, 0), a3, voffA);
;             PG8_WAIT_V(8); PG8_WAIT_L(0); PG8_BAR; PG8_MMA(1, 0, At, B0); PG8_MMA(1, 1, At, B1); PG8_BAR; PG8_SCHED;
;     ...
;         if constexpr (ALIGN_EPI) { if (wr == 0) PG8_BAR; }
	s_setprio 0
	s_add_i32 s26, s58, s38
	v_lshl_add_u64 v[184:185], v[184:185], 0, s[14:15]
	s_mov_b32 m0, s26
	ds_read_b128 v[176:179], v193 offset:49152
	ds_read_b128 v[180:183], v193 offset:50176
	ds_read_b128 v[196:199], v193 offset:51200
	ds_read_b128 v[200:203], v193 offset:52224
	ds_read_b128 v[204:207], v193 offset:53248
	ds_read_b128 v[208:211], v193 offset:54272
	ds_read_b128 v[212:215], v193 offset:55296
	ds_read_b128 v[216:219], v193 offset:56320
	global_load_lds_dwordx4 v[184:185], off
	s_add_i32 m0, s26, 0x2000
	s_add_u32 s26, s30, 0xb0080
	v_lshl_add_u64 v[184:185], v[220:221], 0, s[14:15]
	s_addc_u32 s27, s31, 0
	s_add_i32 s30, s59, s38
	global_load_lds_dwordx4 v[184:185], off
	s_mov_b32 m0, s30
	v_lshl_add_u64 v[184:185], s[26:27], 0, v[154:155]
	global_load_lds_dwordx4 v[184:185], off
	s_add_i32 m0, s30, 0x2000
	v_lshl_add_u64 v[184:185], s[26:27], 0, v[158:159]
	global_load_lds_dwordx4 v[184:185], off
	s_mov_b32 m0, s44
	v_lshl_add_u64 v[184:185], v[222:223], 0, s[14:15]
	global_load_lds_dwordx4 v[184:185], off
	s_mov_b32 m0, s45
	v_lshl_add_u64 v[184:185], v[224:225], 0, s[14:15]
	global_load_lds_dwordx4 v[184:185], off
	s_waitcnt vmcnt(8) lgkmcnt(0)
	s_barrier
	s_setprio 1
	v_mfma_f32_16x16x32_bf16 v[60:63], v[128:131], v[176:179], v[60:63]
	v_mfma_f32_16x16x32_bf16 v[56:59], v[136:139], v[176:179], v[56:59]
	v_mfma_f32_16x16x32_bf16 v[44:47], v[128:131], v[196:199], v[44:47]
	v_mfma_f32_16x16x32_bf16 v[40:43], v[136:139], v[196:199], v[40:43]
	v_mfma_f32_16x16x32_bf16 v[28:31], v[128:131], v[204:207], v[28:31]
	v_mfma_f32_16x16x32_bf16 v[24:27], v[136:139], v[204:207], v[24:27]
	v_mfma_f32_16x16x32_bf16 v[12:15], v[128:131], v[212:215], v[12:15]
	v_mfma_f32_16x16x32_bf16 v[8:11], v[136:139], v[212:215], v[8:11]
	v_mfma_f32_16x16x32_bf16 v[60:63], v[132:135], v[180:183], v[60:63]
	v_mfma_f32_16x16x32_bf16 v[56:59], v[140:143], v[180:183], v[56:59]
	v_mfma_f32_16x16x32_bf16 v[44:47], v[132:135], v[200:203], v[44:47]
	v_mfma_f32_16x16x32_bf16 v[40:43], v[140:143], v[200:203], v[40:43]
	v_mfma_f32_16x16x32_bf16 v[28:31], v[132:135], v[208:211], v[28:31]
	v_mfma_f32_16x16x32_bf16 v[24:27], v[140:143], v[208:211], v[24:27]
	v_mfma_f32_16x16x32_bf16 v[12:15], v[132:135], v[216:219], v[12:15]
	v_mfma_f32_16x16x32_bf16 v[8:11], v[140:143], v[216:219], v[8:11]
	s_setprio 0
	s_setprio 1
	v_mfma_f32_16x16x32_bf16 v[52:55], v[144:147], v[176:179], v[52:55]
	v_mfma_f32_16x16x32_bf16 v[48:51], v[168:171], v[176:179], v[48:51]
	v_mfma_f32_16x16x32_bf16 v[36:39], v[144:147], v[196:199], v[36:39]
	v_mfma_f32_16x16x32_bf16 v[32:35], v[168:171], v[196:199], v[32:35]
	v_mfma_f32_16x16x32_bf16 v[20:23], v[144:147], v[204:207], v[20:23]
	v_mfma_f32_16x16x32_bf16 v[16:19], v[168:171], v[204:207], v[16:19]
	v_mfma_f32_16x16x32_bf16 v[4:7], v[144:147], v[212:215], v[4:7]
	v_mfma_f32_16x16x32_bf16 v[0:3], v[168:171], v[212:215], v[0:3]
	v_mfma_f32_16x16x32_bf16 v[52:55], v[148:151], v[180:183], v[52:55]
	v_mfma_f32_16x16x32_bf16 v[48:51], v[172:175], v[180:183], v[48:51]
	v_mfma_f32_16x16x32_bf16 v[36:39], v[148:151], v[200:203], v[36:39]
	v_mfma_f32_16x16x32_bf16 v[32:35], v[172:175], v[200:203], v[32:35]
	v_mfma_f32_16x16x32_bf16 v[20:23], v[148:151], v[208:211], v[20:23]
	v_mfma_f32_16x16x32_bf16 v[16:19], v[172:175], v[208:211], v[16:19]
	v_mfma_f32_16x16x32_bf16 v[4:7], v[148:151], v[216:219], v[4:7]
	v_mfma_f32_16x16x32_bf16 v[0:3], v[172:175], v[216:219], v[0:3]
	s_barrier
	s_setprio 0
	s_add_i32 s72, s72, 2
	s_add_u32 s70, s70, 0x100
	s_addc_u32 s71, s71, 0
	s_cmp_gt_u32 s72, 41
	s_mov_b64 s[26:27], s[28:29]
	s_cbranch_scc0 .LBB0_318
	s_and_b64 vcc, exec, s[20:21]
	s_cbranch_vccz .LBB0_321
	s_barrier

; #define PG8_STAGE(bufoff, gbase, voff) do { _Pragma("unroll") for (int _i = 0; _i < 2; ++_i) \
;         __builtin_amdgcn_global_load_lds((const unsigned*)((const char*)(gbase) + (voff)[_i]), (PG8_LAS unsigned*)(lds + (bufoff) + ldsw + _i * 8192), 16, 0, 0); } while (0)
; #define PG8_LDA(dst, b, h) do { _Pragma("unroll") for (int m = 0; m < 4; ++m) _Pragma("unroll") for (int k = 0; k < 2; ++k) dst[m][k] = *(const PG8_LAS bf16x8*)(lds + PG8_SA(b, h) + aoff + m * 2048 + k * 1024); } while (0)
; #define PG8_LDB(dst, b, h) do { _Pragma("unroll") for (int n = 0; n < 2; ++n) _Pragma("unroll") for (int k = 0; k < 2; ++k) dst[n][k] = *(const PG8_LAS bf16x8*)(lds + PG8_SB(b, h) + boff + n * 2048 + k * 1024); } while (0)
; #define PG8_MMA(ai, bj, At, Bt) do { __builtin_amdgcn_s_setprio(1); _Pragma("unroll") for (int m = 0; m < 4; ++m) _Pragma("unroll") for (int n = 0; n < 2; ++n) _Pragma("unroll") for (int k = 0; k < 2; ++k) \
;         acc[ai][bj][m][n] = __builtin_amdgcn_mfma_f32_16x16x32_bf16(Bt[n][k], At[m][k], acc[ai][bj][m][n], 0, 0, 0); __builtin_amdgcn_s_setprio(0); } while (0)
; #define PG8_WAIT_V(n) asm volatile("s_waitcnt vmcnt(" #n ")" ::: "memory")
; #define PG8_WAIT_L(n) asm volatile("s_waitcnt lgkmcnt(" #n ")" ::: "memory")
; #define PG8_BAR __builtin_amdgcn_s_barrier()
; #define PG8_SCHED __builtin_amdgcn_sched_barrier(0)
; template <class Epi, class Sched, bool ALIGN_EPI = false, bool SP2 = false>
; __device__ __forceinline__ void gemm_phase(PG8_LAS unsigned char* lds, const Gemm g, const Sched& S, const Epi& E) {
;     ...
;             const bool last = (t == nt - 2);
;             const char* a1 = cA + (size_t)(t + 1) * kstep;
;             const char* a2 = last ? nA : cA + (size_t)(t + 2) * kstep; const char* b2 = last ? nB : cB + (size_t)(t + 2) * kstep;
;             const char* a3 = a2 + kstep; const char* b3 = b2 + kstep;
;             if (last && has_next) S.a_ready(nxt);
;             if constexpr (SP2) {
;             PG8_LDB(B0, 0, 0); PG8_LDB(B1, 0, 1); PG8_SCHED; PG8_LDA(At, 0, 0); PG8_STAGE(PG8_SA(1, 1), a1 + hstepA, voffA);
;             PG8_WAIT_V(8); PG8_WAIT_L(0); PG8_BAR; PG8_MMA(0, 0, At, B0); PG8_MMA(0, 1, At, B1); PG8_BAR; PG8_SCHED;
;             PG8_LDA(At, 0, 1); PG8_STAGE(PG8_SB(0, 0), b2, voffB); PG8_STAGE(PG8_SB(0, 1), b2 + hstepB, voffB); PG8_STAGE(PG8_SA(0, 0), a2, voffA);
.LBB0_404:
	ds_read_b128 v[152:155], v165
	ds_read_b128 v[156:159], v165 offset:1024
	ds_read_b128 v[178:181], v165 offset:2048
	ds_read_b128 v[182:185], v165 offset:3072
	ds_read_b128 v[188:191], v166
	ds_read_b128 v[192:195], v166 offset:1024
	ds_read_b128 v[196:199], v166 offset:2048
	ds_read_b128 v[200:203], v166 offset:3072
	s_add_u32 s46, s14, 0xfffc0080
	s_addc_u32 s47, s15, -1
	s_cmp_eq_u32 s91, 12
	s_cselect_b32 s49, s11, s47
	s_cselect_b32 s48, s13, s46
	s_cselect_b32 s47, s39, s67
	s_cselect_b32 s46, s41, s66
	v_lshl_add_u64 v[160:161], s[14:15], 0, v[144:145]
	s_add_i32 m0, s71, 0xc000
	ds_read_b128 v[204:207], v167
	ds_read_b128 v[208:211], v167 offset:1024
	ds_read_b128 v[212:215], v167 offset:2048
	ds_read_b128 v[216:219], v167 offset:3072
	ds_read_b128 v[220:223], v167 offset:4096
	ds_read_b128 v[224:227], v167 offset:5120
	ds_read_b128 v[228:231], v167 offset:6144
	ds_read_b128 v[232:235], v167 offset:7168
	global_load_lds_dwordx4 v[160:161], off
	s_add_i32 m0, s71, 0xe000
	v_lshl_add_u64 v[160:161], s[14:15], 0, v[146:147]
	global_load_lds_dwordx4 v[160:161], off
	s_waitcnt vmcnt(8) lgkmcnt(0)
	s_barrier
	s_setprio 1
	v_mfma_f32_16x16x32_bf16 v[124:127], v[152:155], v[204:207], v[124:127]
	v_mfma_f32_16x16x32_bf16 v[120:123], v[178:181], v[204:207], v[120:123]
	v_mfma_f32_16x16x32_bf16 v[108:111], v[152:155], v[212:215], v[108:111]
	v_mfma_f32_16x16x32_bf16 v[104:107], v[178:181], v[212:215], v[104:107]
	v_mfma_f32_16x16x32_bf16 v[92:95], v[152:155], v[220:223], v[92:95]
	v_mfma_f32_16x16x32_bf16 v[88:91], v[178:181], v[220:223], v[88:91]
	v_mfma_f32_16x16x32_bf16 v[76:79], v[152:155], v[228:231], v[76:79]
	v_mfma_f32_16x16x32_bf16 v[72:75], v[178:181], v[228:231], v[72:75]
	v_mfma_f32_16x16x32_bf16 v[124:127], v[156:159], v[208:211], v[124:127]
	v_mfma_f32_16x16x32_bf16 v[120:123], v[182:185], v[208:211], v[120:123]
	v_mfma_f32_16x16x32_bf16 v[108:111], v[156:159], v[216:219], v[108:111]
	v_mfma_f32_16x16x32_bf16 v[104:107], v[182:185], v[216:219], v[104:107]
	v_mfma_f32_16x16x32_bf16 v[92:95], v[156:159], v[224:227], v[92:95]
	v_mfma_f32_16x16x32_bf16 v[88:91], v[182:185], v[224:227], v[88:91]
	v_mfma_f32_16x16x32_bf16 v[76:79], v[156:159], v[232:235], v[76:79]
	v_mfma_f32_16x16x32_bf16 v[72:75], v[182:185], v[232:235], v[72:75]
	s_setprio 0
	s_setprio 1
	v_mfma_f32_16x16x32_bf16 v[116:119], v[188:191], v[204:207], v[116:119]
	v_mfma_f32_16x16x32_bf16 v[112:115], v[196:199], v[204:207], v[112:115]
	v_mfma_f32_16x16x32_bf16 v[100:103], v[188:191], v[212:215], v[100:103]
	v_mfma_f32_16x16x32_bf16 v[96:99], v[196:199], v[212:215], v[96:99]
	v_mfma_f32_16x16x32_bf16 v[84:87], v[188:191], v[220:223], v[84:87]
	v_mfma_f32_16x16x32_bf16 v[80:83], v[196:199], v[220:223], v[80:83]
	v_mfma_f32_16x16x32_bf16 v[68:71], v[188:191], v[228:231], v[68:71]
	v_mfma_f32_16x16x32_bf16 v[64:67], v[196:199], v[228:231], v[64:67]
	v_mfma_f32_16x16x32_bf16 v[116:119], v[192:195], v[208:211], v[116:119]
	v_mfma_f32_16x16x32_bf16 v[112:115], v[200:203], v[208:211], v[112:115]
	v_mfma_f32_16x16x32_bf16 v[100:103], v[192:195], v[216:219], v[100:103]
	v_mfma_f32_16x16x32_bf16 v[96:99], v[200:203], v[216:219], v[96:99]
	v_mfma_f32_16x16x32_bf16 v[84:87], v[192:195], v[224:227], v[84:87]
	v_mfma_f32_16x16x32_bf16 v[80:83], v[200:203], v[224:227], v[80:83]
	v_mfma_f32_16x16x32_bf16 v[68:71], v[192:195], v[232:235], v[68:71]
	v_mfma_f32_16x16x32_bf16 v[64:67], v[200:203], v[232:235], v[64:67]
	s_barrier
	s_setprio 0
	s_add_i32 s58, s83, s70
	v_lshl_add_u64 v[160:161], s[46:47], 0, v[130:131]
	s_mov_b32 m0, s58
	ds_read_b128 v[204:207], v167 offset:16384
	ds_read_b128 v[208:211], v167 offset:17408
	ds_read_b128 v[212:215], v167 offset:18432
	ds_read_b128 v[216:219], v167 offset:19456
	ds_read_b128 v[220:223], v167 offset:20480
	ds_read_b128 v[224:227], v167 offset:21504
	ds_read_b128 v[228:231], v167 offset:22528
	ds_read_b128 v[232:235], v167 offset:23552
	global_load_lds_dwordx4 v[160:161], off
	s_add_i32 m0, s58, 0x2000
	s_add_u32 s58, s46, 0x40000
	v_lshl_add_u64 v[236:237], s[46:47], 0, v[134:135]
	s_addc_u32 s59, s47, 0
	s_add_i32 s92, s84, s70
	global_load_lds_dwordx4 v[236:237], off
	v_lshl_add_u64 v[238:239], s[58:59], 0, v[130:131]
	s_mov_b32 m0, s92
	v_lshl_add_u64 v[240:241], s[48:49], 0, v[132:133]
	global_load_lds_dwordx4 v[238:239], off
	s_add_i32 m0, s92, 0x2000
	v_lshl_add_u64 v[238:239], s[58:59], 0, v[134:135]
	global_load_lds_dwordx4 v[238:239], off
	s_mov_b32 m0, s71
	v_lshl_add_u64 v[238:239], s[48:49], 0, v[128:129]
	global_load_lds_dwordx4 v[238:239], off
	s_mov_b32 m0, s72
	s_nop 0
	global_load_lds_dwordx4 v[240:241], off
	s_waitcnt vmcnt(8) lgkmcnt(0)
	s_barrier
; #define PG8_STAGE(bufoff, gbase, voff) do { _Pragma("unroll") for (int _i = 0; _i < 2; ++_i) \
;         __builtin_amdgcn_global_load_lds((const unsigned*)((const char*)(gbase) + (voff)[_i]), (PG8_LAS unsigned*)(lds + (bufoff) + ldsw + _i * 8192), 16, 0, 0); } while (0)
; #define PG8_LDA(dst, b, h) do { _Pragma("unroll") for (int m = 0; m < 4; ++m) _Pragma("unroll") for (int k = 0; k < 2; ++k) dst[m][k] = *(const PG8_LAS bf16x8*)(lds + PG8_SA(b, h) + aoff + m * 2048 + k * 1024); } while (0)
; #define PG8_LDB(dst, b, h) do { _Pragma("unroll") for (int n = 0; n < 2; ++n) _Pragma("unroll") for (int k = 0; k < 2; ++k) dst[n][k] = *(const PG8_LAS bf16x8*)(lds + PG8_SB(b, h) + boff + n * 2048 + k * 1024); } while (0)
; #define PG8_MMA(ai, bj, At, Bt) do { __builtin_amdgcn_s_setprio(1); _Pragma("unroll") for (int m = 0; m < 4; ++m) _Pragma("unroll") for (int n = 0; n < 2; ++n) _Pragma("unroll") for (int k = 0; k < 2; ++k) \
;         acc[ai][bj][m][n] = __builtin_amdgcn_mfma_f32_16x16x32_bf16(Bt[n][k], At[m][k], acc[ai][bj][m][n], 0, 0, 0); __builtin_amdgcn_s_setprio(0); } while (0)
; #define PG8_WAIT_V(n) asm volatile("s_waitcnt vmcnt(" #n ")" ::: "memory")
; #define PG8_WAIT_L(n) asm volatile("s_waitcnt lgkmcnt(" #n ")" ::: "memory")
; #define PG8_BAR __builtin_amdgcn_s_barrier()
; #define PG8_SCHED __builtin_amdgcn_sched_barrier(0)
; template <class Epi, class Sched, bool ALIGN_EPI = false, bool SP2 = false>
; __device__ __forceinline__ void gemm_phase(PG8_LAS unsigned char* lds, const Gemm g, const Sched& S, const Epi& E) {
;     ...
;             PG8_WAIT_V(8); PG8_WAIT_L(0); PG8_BAR; PG8_MMA(1, 0, At, B0); PG8_MMA(1, 1, At, B1); PG8_BAR; PG8_SCHED;
;             PG8_LDB(B0, 1, 0); PG8_LDB(B1, 1, 1); PG8_SCHED; PG8_LDA(At, 1, 0); PG8_STAGE(PG8_SA(0, 1), a2 + hstepA, voffA);
;             PG8_WAIT_V(8); PG8_WAIT_L(0); PG8_BAR; PG8_MMA(0, 0, At, B0); PG8_MMA(0, 1, At, B1); PG8_BAR; PG8_SCHED;
	s_setprio 1
	v_mfma_f32_16x16x32_bf16 v[60:63], v[152:155], v[204:207], v[60:63]
	v_mfma_f32_16x16x32_bf16 v[56:59], v[178:181], v[204:207], v[56:59]
	v_mfma_f32_16x16x32_bf16 v[44:47], v[152:155], v[212:215], v[44:47]
	v_mfma_f32_16x16x32_bf16 v[40:43], v[178:181], v[212:215], v[40:43]
	v_mfma_f32_16x16x32_bf16 v[28:31], v[152:155], v[220:223], v[28:31]
	v_mfma_f32_16x16x32_bf16 v[24:27], v[178:181], v[220:223], v[24:27]
	v_mfma_f32_16x16x32_bf16 v[12:15], v[152:155], v[228:231], v[12:15]
	v_mfma_f32_16x16x32_bf16 v[8:11], v[178:181], v[228:231], v[8:11]
	v_mfma_f32_16x16x32_bf16 v[60:63], v[156:159], v[208:211], v[60:63]
	v_mfma_f32_16x16x32_bf16 v[56:59], v[182:185], v[208:211], v[56:59]
	v_mfma_f32_16x16x32_bf16 v[44:47], v[156:159], v[216:219], v[44:47]
	v_mfma_f32_16x16x32_bf16 v[40:43], v[182:185], v[216:219], v[40:43]
	v_mfma_f32_16x16x32_bf16 v[28:31], v[156:159], v[224:227], v[28:31]
	v_mfma_f32_16x16x32_bf16 v[24:27], v[182:185], v[224:227], v[24:27]
	v_mfma_f32_16x16x32_bf16 v[12:15], v[156:159], v[232:235], v[12:15]
	v_mfma_f32_16x16x32_bf16 v[8:11], v[182:185], v[232:235], v[8:11]
	s_setprio 0
	s_setprio 1
	v_mfma_f32_16x16x32_bf16 v[52:55], v[188:191], v[204:207], v[52:55]
	v_mfma_f32_16x16x32_bf16 v[48:51], v[196:199], v[204:207], v[48:51]
	v_mfma_f32_16x16x32_bf16 v[36:39], v[188:191], v[212:215], v[36:39]
	v_mfma_f32_16x16x32_bf16 v[32:35], v[196:199], v[212:215], v[32:35]
	v_mfma_f32_16x16x32_bf16 v[20:23], v[188:191], v[220:223], v[20:23]
	v_mfma_f32_16x16x32_bf16 v[16:19], v[196:199], v[220:223], v[16:19]
	v_mfma_f32_16x16x32_bf16 v[4:7], v[188:191], v[228:231], v[4:7]
	v_mfma_f32_16x16x32_bf16 v[0:3], v[196:199], v[228:231], v[0:3]
	v_mfma_f32_16x16x32_bf16 v[52:55], v[192:195], v[208:211], v[52:55]
	v_mfma_f32_16x16x32_bf16 v[48:51], v[200:203], v[208:211], v[48:51]
	v_mfma_f32_16x16x32_bf16 v[36:39], v[192:195], v[216:219], v[36:39]
	v_mfma_f32_16x16x32_bf16 v[32:35], v[200:203], v[216:219], v[32:35]
	v_mfma_f32_16x16x32_bf16 v[20:23], v[192:195], v[224:227], v[20:23]
	v_mfma_f32_16x16x32_bf16 v[16:19], v[200:203], v[224:227], v[16:19]
	v_mfma_f32_16x16x32_bf16 v[4:7], v[192:195], v[232:235], v[4:7]
	v_mfma_f32_16x16x32_bf16 v[0:3], v[200:203], v[232:235], v[0:3]
	s_barrier
	s_setprio 0
	s_add_i32 s58, 0, 0x18000
	v_add_u32_e32 v136, s58, v163
	s_add_i32 s59, 0, 0x1c000
	ds_read_b128 v[152:155], v136
	ds_read_b128 v[156:159], v136 offset:1024
	ds_read_b128 v[178:181], v136 offset:2048
	ds_read_b128 v[182:185], v136 offset:3072
	v_add_u32_e32 v136, s59, v163
	ds_read_b128 v[188:191], v136
	ds_read_b128 v[192:195], v136 offset:1024
	ds_read_b128 v[196:199], v136 offset:2048
	ds_read_b128 v[200:203], v136 offset:3072
	s_add_u32 s48, s48, 0x40000
	s_addc_u32 s49, s49, 0
	s_mov_b32 m0, s73
	v_lshl_add_u64 v[242:243], s[48:49], 0, v[128:129]
	ds_read_b128 v[204:207], v167 offset:32768
	ds_read_b128 v[208:211], v167 offset:33792
	ds_read_b128 v[212:215], v167 offset:34816
	ds_read_b128 v[216:219], v167 offset:35840
	ds_read_b128 v[220:223], v167 offset:36864
	ds_read_b128 v[224:227], v167 offset:37888
	ds_read_b128 v[228:231], v167 offset:38912
	ds_read_b128 v[232:235], v167 offset:39936
	global_load_lds_dwordx4 v[242:243], off
	s_mov_b32 m0, s74
	v_lshl_add_u64 v[242:243], s[48:49], 0, v[132:133]
	global_load_lds_dwordx4 v[242:243], off
	s_waitcnt vmcnt(8) lgkmcnt(0)
	s_barrier
	s_setprio 1
	v_mfma_f32_16x16x32_bf16 v[124:127], v[152:155], v[204:207], v[124:127]
	v_mfma_f32_16x16x32_bf16 v[120:123], v[178:181], v[204:207], v[120:123]
	v_mfma_f32_16x16x32_bf16 v[108:111], v[152:155], v[212:215], v[108:111]
	v_mfma_f32_16x16x32_bf16 v[104:107], v[178:181], v[212:215], v[104:107]
	v_mfma_f32_16x16x32_bf16 v[92:95], v[152:155], v[220:223], v[92:95]
	v_mfma_f32_16x16x32_bf16 v[88:91], v[178:181], v[220:223], v[88:91]
	v_mfma_f32_16x16x32_bf16 v[76:79], v[152:155], v[228:231], v[76:79]
	v_mfma_f32_16x16x32_bf16 v[72:75], v[178:181], v[228:231], v[72:75]
	v_mfma_f32_16x16x32_bf16 v[124:127], v[156:159], v[208:211], v[124:127]
	v_mfma_f32_16x16x32_bf16 v[120:123], v[182:185], v[208:211], v[120:123]
	v_mfma_f32_16x16x32_bf16 v[108:111], v[156:159], v[216:219], v[108:111]
	v_mfma_f32_16x16x32_bf16 v[104:107], v[182:185], v[216:219], v[104:107]
	v_mfma_f32_16x16x32_bf16 v[92:95], v[156:159], v[224:227], v[92:95]
	v_mfma_f32_16x16x32_bf16 v[88:91], v[182:185], v[224:227], v[88:91]
	v_mfma_f32_16x16x32_bf16 v[76:79], v[156:159], v[232:235], v[76:79]
	v_mfma_f32_16x16x32_bf16 v[72:75], v[182:185], v[232:235], v[72:75]
	s_setprio 0
	s_setprio 1
	v_mfma_f32_16x16x32_bf16 v[116:119], v[188:191], v[204:207], v[116:119]
	v_mfma_f32_16x16x32_bf16 v[112:115], v[196:199], v[204:207], v[112:115]
	v_mfma_f32_16x16x32_bf16 v[100:103], v[188:191], v[212:215], v[100:103]
	v_mfma_f32_16x16x32_bf16 v[96:99], v[196:199], v[212:215], v[96:99]
	v_mfma_f32_16x16x32_bf16 v[84:87], v[188:191], v[220:223], v[84:87]
	v_mfma_f32_16x16x32_bf16 v[80:83], v[196:199], v[220:223], v[80:83]
	v_mfma_f32_16x16x32_bf16 v[68:71], v[188:191], v[228:231], v[68:71]
	v_mfma_f32_16x16x32_bf16 v[64:67], v[196:199], v[228:231], v[64:67]
	v_mfma_f32_16x16x32_bf16 v[116:119], v[192:195], v[208:211], v[116:119]
	v_mfma_f32_16x16x32_bf16 v[112:115], v[200:203], v[208:211], v[112:115]
	v_mfma_f32_16x16x32_bf16 v[100:103], v[192:195], v[216:219], v[100:103]
	v_mfma_f32_16x16x32_bf16 v[96:99], v[200:203], v[216:219], v[96:99]
	v_mfma_f32_16x16x32_bf16 v[84:87], v[192:195], v[224:227], v[84:87]
	v_mfma_f32_16x16x32_bf16 v[80:83], v[200:203], v[224:227], v[80:83]
	v_mfma_f32_16x16x32_bf16 v[68:71], v[192:195], v[232:235], v[68:71]
	v_mfma_f32_16x16x32_bf16 v[64:67], v[200:203], v[232:235], v[64:67]
	s_barrier
; #define PG8_STAGE(bufoff, gbase, voff) do { _Pragma("unroll") for (int _i = 0; _i < 2; ++_i) \
;         __builtin_amdgcn_global_load_lds((const unsigned*)((const char*)(gbase) + (voff)[_i]), (PG8_LAS unsigned*)(lds + (bufoff) + ldsw + _i * 8192), 16, 0, 0); } while (0)
; #define PG8_LDA(dst, b, h) do { _Pragma("unroll") for (int m = 0; m < 4; ++m) _Pragma("unroll") for (int k = 0; k < 2; ++k) dst[m][k] = *(const PG8_LAS bf16x8*)(lds + PG8_SA(b, h) + aoff + m * 2048 + k * 1024); } while (0)
; #define PG8_MMA(ai, bj, At, Bt) do { __builtin_amdgcn_s_setprio(1); _Pragma("unroll") for (int m = 0; m < 4; ++m) _Pragma("unroll") for (int n = 0; n < 2; ++n) _Pragma("unroll") for (int k = 0; k < 2; ++k) \
;         acc[ai][bj][m][n] = __builtin_amdgcn_mfma_f32_16x16x32_bf16(Bt[n][k], At[m][k], acc[ai][bj][m][n], 0, 0, 0); __builtin_amdgcn_s_setprio(0); } while (0)
; #define PG8_WAIT_V(n) asm volatile("s_waitcnt vmcnt(" #n ")" ::: "memory")
; #define PG8_WAIT_L(n) asm volatile("s_waitcnt lgkmcnt(" #n ")" ::: "memory")
; #define PG8_BAR __builtin_amdgcn_s_barrier()
; #define PG8_SCHED __builtin_amdgcn_sched_barrier(0)
; template <class Epi, class Sched, bool ALIGN_EPI = false, bool SP2 = false>
; __device__ __forceinline__ void gemm_phase(PG8_LAS unsigned char* lds, const Gemm g, const Sched& S, const Epi& E) {
;     ...
;             PG8_LDA(At, 1, 1); PG8_STAGE(PG8_SB(1, 0), b3, voffB); PG8_STAGE(PG8_SB(1, 1), b3 + hstepB, voffB); PG8_STAGE(PG8_SA(1, 0), a3, voffA);
;             PG8_WAIT_V(8); PG8_WAIT_L(0); PG8_BAR; PG8_MMA(1, 0, At, B0); PG8_MMA(1, 1, At, B1); PG8_BAR; PG8_SCHED;
;     ...
;         if constexpr (ALIGN_EPI) { if (wr == 0) PG8_BAR; }
	s_setprio 0
	s_add_i32 s48, s58, s70
	v_lshl_add_u64 v[160:161], v[160:161], 0, s[30:31]
	s_mov_b32 m0, s48
	ds_read_b128 v[204:207], v167 offset:49152
	ds_read_b128 v[208:211], v167 offset:50176
	ds_read_b128 v[212:215], v167 offset:51200
	ds_read_b128 v[216:219], v167 offset:52224
	ds_read_b128 v[220:223], v167 offset:53248
	ds_read_b128 v[224:227], v167 offset:54272
	ds_read_b128 v[228:231], v167 offset:55296
	ds_read_b128 v[232:235], v167 offset:56320
	global_load_lds_dwordx4 v[160:161], off
	s_add_i32 m0, s48, 0x2000
	s_add_u32 s46, s46, 0x40080
	v_lshl_add_u64 v[160:161], v[236:237], 0, s[30:31]
	s_addc_u32 s47, s47, 0
	s_add_i32 s48, s59, s70
	global_load_lds_dwordx4 v[160:161], off
	s_mov_b32 m0, s48
	v_lshl_add_u64 v[160:161], s[46:47], 0, v[130:131]
	global_load_lds_dwordx4 v[160:161], off
	s_add_i32 m0, s48, 0x2000
	v_lshl_add_u64 v[160:161], s[46:47], 0, v[134:135]
	global_load_lds_dwordx4 v[160:161], off
	s_mov_b32 m0, s76
	v_lshl_add_u64 v[160:161], v[238:239], 0, s[30:31]
	global_load_lds_dwordx4 v[160:161], off
	s_mov_b32 m0, s77
	v_lshl_add_u64 v[160:161], v[240:241], 0, s[30:31]
	global_load_lds_dwordx4 v[160:161], off
	s_waitcnt vmcnt(8) lgkmcnt(0)
	s_barrier
	s_setprio 1
	v_mfma_f32_16x16x32_bf16 v[60:63], v[152:155], v[204:207], v[60:63]
	v_mfma_f32_16x16x32_bf16 v[56:59], v[178:181], v[204:207], v[56:59]
	v_mfma_f32_16x16x32_bf16 v[44:47], v[152:155], v[212:215], v[44:47]
	v_mfma_f32_16x16x32_bf16 v[40:43], v[178:181], v[212:215], v[40:43]
	v_mfma_f32_16x16x32_bf16 v[28:31], v[152:155], v[220:223], v[28:31]
	v_mfma_f32_16x16x32_bf16 v[24:27], v[178:181], v[220:223], v[24:27]
	v_mfma_f32_16x16x32_bf16 v[12:15], v[152:155], v[228:231], v[12:15]
	v_mfma_f32_16x16x32_bf16 v[8:11], v[178:181], v[228:231], v[8:11]
	v_mfma_f32_16x16x32_bf16 v[60:63], v[156:159], v[208:211], v[60:63]
	v_mfma_f32_16x16x32_bf16 v[56:59], v[182:185], v[208:211], v[56:59]
	v_mfma_f32_16x16x32_bf16 v[44:47], v[156:159], v[216:219], v[44:47]
	v_mfma_f32_16x16x32_bf16 v[40:43], v[182:185], v[216:219], v[40:43]
	v_mfma_f32_16x16x32_bf16 v[28:31], v[156:159], v[224:227], v[28:31]
	v_mfma_f32_16x16x32_bf16 v[24:27], v[182:185], v[224:227], v[24:27]
	v_mfma_f32_16x16x32_bf16 v[12:15], v[156:159], v[232:235], v[12:15]
	v_mfma_f32_16x16x32_bf16 v[8:11], v[182:185], v[232:235], v[8:11]
	s_setprio 0
	s_setprio 1
	v_mfma_f32_16x16x32_bf16 v[52:55], v[188:191], v[204:207], v[52:55]
	v_mfma_f32_16x16x32_bf16 v[48:51], v[196:199], v[204:207], v[48:51]
	v_mfma_f32_16x16x32_bf16 v[36:39], v[188:191], v[212:215], v[36:39]
	v_mfma_f32_16x16x32_bf16 v[32:35], v[196:199], v[212:215], v[32:35]
	v_mfma_f32_16x16x32_bf16 v[20:23], v[188:191], v[220:223], v[20:23]
	v_mfma_f32_16x16x32_bf16 v[16:19], v[196:199], v[220:223], v[16:19]
	v_mfma_f32_16x16x32_bf16 v[4:7], v[188:191], v[228:231], v[4:7]
	v_mfma_f32_16x16x32_bf16 v[0:3], v[196:199], v[228:231], v[0:3]
	v_mfma_f32_16x16x32_bf16 v[52:55], v[192:195], v[208:211], v[52:55]
	v_mfma_f32_16x16x32_bf16 v[48:51], v[200:203], v[208:211], v[48:51]
	v_mfma_f32_16x16x32_bf16 v[36:39], v[192:195], v[216:219], v[36:39]
	v_mfma_f32_16x16x32_bf16 v[32:35], v[200:203], v[216:219], v[32:35]
	v_mfma_f32_16x16x32_bf16 v[20:23], v[192:195], v[224:227], v[20:23]
	v_mfma_f32_16x16x32_bf16 v[16:19], v[200:203], v[224:227], v[16:19]
	v_mfma_f32_16x16x32_bf16 v[4:7], v[192:195], v[232:235], v[4:7]
	v_mfma_f32_16x16x32_bf16 v[0:3], v[200:203], v[232:235], v[0:3]
	s_barrier
	s_setprio 0
	s_add_i32 s91, s91, 2
	s_add_u32 s14, s14, 0x100
	s_addc_u32 s15, s15, 0
	s_add_u32 s66, s66, 0x100
	s_addc_u32 s67, s67, 0
	s_cmp_gt_u32 s91, 13
	s_cbranch_scc0 .LBB0_404
	s_and_b64 vcc, exec, s[34:35]
	s_cbranch_vccz .LBB0_407
	s_barrier

; #define PG8_STAGE(bufoff, gbase, voff) do { _Pragma("unroll") for (int _i = 0; _i < 2; ++_i) \
;         __builtin_amdgcn_global_load_lds((const unsigned*)((const char*)(gbase) + (voff)[_i]), (PG8_LAS unsigned*)(lds + (bufoff) + ldsw + _i * 8192), 16, 0, 0); } while (0)
; #define PG8_LDA(dst, b, h) do { _Pragma("unroll") for (int m = 0; m < 4; ++m) _Pragma("unroll") for (int k = 0; k < 2; ++k) dst[m][k] = *(const PG8_LAS bf16x8*)(lds + PG8_SA(b, h) + aoff + m * 2048 + k * 1024); } while (0)
; #define PG8_LDB(dst, b, h) do { _Pragma("unroll") for (int n = 0; n < 2; ++n) _Pragma("unroll") for (int k = 0; k < 2; ++k) dst[n][k] = *(const PG8_LAS bf16x8*)(lds + PG8_SB(b, h) + boff + n * 2048 + k * 1024); } while (0)
; #define PG8_MMA(ai, bj, At, Bt) do { __builtin_amdgcn_s_setprio(1); _Pragma("unroll") for (int m = 0; m < 4; ++m) _Pragma("unroll") for (int n = 0; n < 2; ++n) _Pragma("unroll") for (int k = 0; k < 2; ++k) \
;         acc[ai][bj][m][n] = __builtin_amdgcn_mfma_f32_16x16x32_bf16(Bt[n][k], At[m][k], acc[ai][bj][m][n], 0, 0, 0); __builtin_amdgcn_s_setprio(0); } while (0)
; #define PG8_WAIT_V(n) asm volatile("s_waitcnt vmcnt(" #n ")" ::: "memory")
; #define PG8_WAIT_L(n) asm volatile("s_waitcnt lgkmcnt(" #n ")" ::: "memory")
; #define PG8_BAR __builtin_amdgcn_s_barrier()
; #define PG8_SCHED __builtin_amdgcn_sched_barrier(0)
; template <class Epi, class Sched, bool ALIGN_EPI = false, bool SP2 = false>
; __device__ __forceinline__ void gemm_phase(PG8_LAS unsigned char* lds, const Gemm g, const Sched& S, const Epi& E) {
;     ...
;             const bool last = (t == nt - 2);
;             const char* a1 = cA + (size_t)(t + 1) * kstep;
;             const char* a2 = last ? nA : cA + (size_t)(t + 2) * kstep; const char* b2 = last ? nB : cB + (size_t)(t + 2) * kstep;
;             const char* a3 = a2 + kstep; const char* b3 = b2 + kstep;
;             if (last && has_next) S.a_ready(nxt);
;             if constexpr (SP2) {
;             PG8_LDB(B0, 0, 0); PG8_LDB(B1, 0, 1); PG8_SCHED; PG8_LDA(At, 0, 0); PG8_STAGE(PG8_SA(1, 1), a1 + hstepA, voffA);
;             PG8_WAIT_V(8); PG8_WAIT_L(0); PG8_BAR; PG8_MMA(0, 0, At, B0); PG8_MMA(0, 1, At, B1); PG8_BAR; PG8_SCHED;
;             PG8_LDA(At, 0, 1); PG8_STAGE(PG8_SB(0, 0), b2, voffB); PG8_STAGE(PG8_SB(0, 1), b2 + hstepB, voffB); PG8_STAGE(PG8_SA(0, 0), a2, voffA);
.LBB0_524:
	ds_read_b128 v[144:147], v153
	ds_read_b128 v[158:161], v153 offset:1024
	ds_read_b128 v[162:165], v153 offset:2048
	ds_read_b128 v[166:169], v153 offset:3072
	ds_read_b128 v[170:173], v154
	ds_read_b128 v[174:177], v154 offset:1024
	ds_read_b128 v[178:181], v154 offset:2048
	ds_read_b128 v[182:185], v154 offset:3072
	s_add_u32 s30, s28, 0x100
	s_addc_u32 s31, s29, 0
	s_cmp_eq_u32 s76, 2
	s_cselect_b32 s37, s9, s31
	s_cselect_b32 s36, s8, s30
	s_cselect_b32 s35, s25, s75
	s_cselect_b32 s34, s24, s74
	v_lshl_add_u64 v[148:149], s[28:29], 0, v[136:137]
	s_add_i32 m0, s42, 0xc000
	ds_read_b128 v[188:191], v155
	ds_read_b128 v[192:195], v155 offset:1024
	ds_read_b128 v[196:199], v155 offset:2048
	ds_read_b128 v[200:203], v155 offset:3072
	ds_read_b128 v[204:207], v155 offset:4096
	ds_read_b128 v[208:211], v155 offset:5120
	ds_read_b128 v[212:215], v155 offset:6144
	ds_read_b128 v[216:219], v155 offset:7168
	global_load_lds_dwordx4 v[148:149], off
	s_add_i32 m0, s42, 0xe000
	v_lshl_add_u64 v[148:149], s[28:29], 0, v[138:139]
	global_load_lds_dwordx4 v[148:149], off
	s_waitcnt vmcnt(8) lgkmcnt(0)
	s_barrier
	s_setprio 1
	v_mfma_f32_16x16x32_bf16 v[124:127], v[144:147], v[188:191], v[124:127]
	v_mfma_f32_16x16x32_bf16 v[120:123], v[162:165], v[188:191], v[120:123]
	v_mfma_f32_16x16x32_bf16 v[108:111], v[144:147], v[196:199], v[108:111]
	v_mfma_f32_16x16x32_bf16 v[104:107], v[162:165], v[196:199], v[104:107]
	v_mfma_f32_16x16x32_bf16 v[92:95], v[144:147], v[204:207], v[92:95]
	v_mfma_f32_16x16x32_bf16 v[88:91], v[162:165], v[204:207], v[88:91]
	v_mfma_f32_16x16x32_bf16 v[76:79], v[144:147], v[212:215], v[76:79]
	v_mfma_f32_16x16x32_bf16 v[72:75], v[162:165], v[212:215], v[72:75]
	v_mfma_f32_16x16x32_bf16 v[124:127], v[158:161], v[192:195], v[124:127]
	v_mfma_f32_16x16x32_bf16 v[120:123], v[166:169], v[192:195], v[120:123]
	v_mfma_f32_16x16x32_bf16 v[108:111], v[158:161], v[200:203], v[108:111]
	v_mfma_f32_16x16x32_bf16 v[104:107], v[166:169], v[200:203], v[104:107]
	v_mfma_f32_16x16x32_bf16 v[92:95], v[158:161], v[208:211], v[92:95]
	v_mfma_f32_16x16x32_bf16 v[88:91], v[166:169], v[208:211], v[88:91]
	v_mfma_f32_16x16x32_bf16 v[76:79], v[158:161], v[216:219], v[76:79]
	v_mfma_f32_16x16x32_bf16 v[72:75], v[166:169], v[216:219], v[72:75]
	s_setprio 0
	s_setprio 1
	v_mfma_f32_16x16x32_bf16 v[116:119], v[170:173], v[188:191], v[116:119]
	v_mfma_f32_16x16x32_bf16 v[112:115], v[178:181], v[188:191], v[112:115]
	v_mfma_f32_16x16x32_bf16 v[100:103], v[170:173], v[196:199], v[100:103]
	v_mfma_f32_16x16x32_bf16 v[96:99], v[178:181], v[196:199], v[96:99]
	v_mfma_f32_16x16x32_bf16 v[84:87], v[170:173], v[204:207], v[84:87]
	v_mfma_f32_16x16x32_bf16 v[80:83], v[178:181], v[204:207], v[80:83]
	v_mfma_f32_16x16x32_bf16 v[68:71], v[170:173], v[212:215], v[68:71]
	v_mfma_f32_16x16x32_bf16 v[64:67], v[178:181], v[212:215], v[64:67]
	v_mfma_f32_16x16x32_bf16 v[116:119], v[174:177], v[192:195], v[116:119]
	v_mfma_f32_16x16x32_bf16 v[112:115], v[182:185], v[192:195], v[112:115]
	v_mfma_f32_16x16x32_bf16 v[100:103], v[174:177], v[200:203], v[100:103]
	v_mfma_f32_16x16x32_bf16 v[96:99], v[182:185], v[200:203], v[96:99]
	v_mfma_f32_16x16x32_bf16 v[84:87], v[174:177], v[208:211], v[84:87]
	v_mfma_f32_16x16x32_bf16 v[80:83], v[182:185], v[208:211], v[80:83]
	v_mfma_f32_16x16x32_bf16 v[68:71], v[174:177], v[216:219], v[68:71]
	v_mfma_f32_16x16x32_bf16 v[64:67], v[182:185], v[216:219], v[64:67]
	s_barrier
	s_setprio 0
	s_add_i32 s28, s66, s40
	v_lshl_add_u64 v[148:149], s[34:35], 0, v[132:133]
	s_mov_b32 m0, s28
	ds_read_b128 v[188:191], v155 offset:16384
	ds_read_b128 v[192:195], v155 offset:17408
	ds_read_b128 v[196:199], v155 offset:18432
	ds_read_b128 v[200:203], v155 offset:19456
	ds_read_b128 v[204:207], v155 offset:20480
	ds_read_b128 v[208:211], v155 offset:21504
	ds_read_b128 v[212:215], v155 offset:22528
	ds_read_b128 v[216:219], v155 offset:23552
	global_load_lds_dwordx4 v[148:149], off
	s_add_i32 m0, s28, 0x2000
	s_add_u32 s28, s34, 0x18000
	v_lshl_add_u64 v[220:221], s[34:35], 0, v[128:129]
	s_addc_u32 s29, s35, 0
	s_add_i32 s58, s67, s40
	global_load_lds_dwordx4 v[220:221], off
	v_lshl_add_u64 v[222:223], s[28:29], 0, v[132:133]
	s_mov_b32 m0, s58
	v_lshl_add_u64 v[224:225], s[36:37], 0, v[130:131]
	global_load_lds_dwordx4 v[222:223], off
	s_add_i32 m0, s58, 0x2000
	v_lshl_add_u64 v[222:223], s[28:29], 0, v[128:129]
	global_load_lds_dwordx4 v[222:223], off
	s_mov_b32 m0, s42
	v_lshl_add_u64 v[222:223], s[36:37], 0, v[134:135]
	global_load_lds_dwordx4 v[222:223], off
	s_mov_b32 m0, s43
	s_nop 0
	global_load_lds_dwordx4 v[224:225], off
	s_waitcnt vmcnt(8) lgkmcnt(0)
	s_barrier
; #define PG8_STAGE(bufoff, gbase, voff) do { _Pragma("unroll") for (int _i = 0; _i < 2; ++_i) \
;         __builtin_amdgcn_global_load_lds((const unsigned*)((const char*)(gbase) + (voff)[_i]), (PG8_LAS unsigned*)(lds + (bufoff) + ldsw + _i * 8192), 16, 0, 0); } while (0)
; #define PG8_LDA(dst, b, h) do { _Pragma("unroll") for (int m = 0; m < 4; ++m) _Pragma("unroll") for (int k = 0; k < 2; ++k) dst[m][k] = *(const PG8_LAS bf16x8*)(lds + PG8_SA(b, h) + aoff + m * 2048 + k * 1024); } while (0)
; #define PG8_LDB(dst, b, h) do { _Pragma("unroll") for (int n = 0; n < 2; ++n) _Pragma("unroll") for (int k = 0; k < 2; ++k) dst[n][k] = *(const PG8_LAS bf16x8*)(lds + PG8_SB(b, h) + boff + n * 2048 + k * 1024); } while (0)
; #define PG8_MMA(ai, bj, At, Bt) do { __builtin_amdgcn_s_setprio(1); _Pragma("unroll") for (int m = 0; m < 4; ++m) _Pragma("unroll") for (int n = 0; n < 2; ++n) _Pragma("unroll") for (int k = 0; k < 2; ++k) \
;         acc[ai][bj][m][n] = __builtin_amdgcn_mfma_f32_16x16x32_bf16(Bt[n][k], At[m][k], acc[ai][bj][m][n], 0, 0, 0); __builtin_amdgcn_s_setprio(0); } while (0)
; #define PG8_WAIT_V(n) asm volatile("s_waitcnt vmcnt(" #n ")" ::: "memory")
; #define PG8_WAIT_L(n) asm volatile("s_waitcnt lgkmcnt(" #n ")" ::: "memory")
; #define PG8_BAR __builtin_amdgcn_s_barrier()
; #define PG8_SCHED __builtin_amdgcn_sched_barrier(0)
; template <class Epi, class Sched, bool ALIGN_EPI = false, bool SP2 = false>
; __device__ __forceinline__ void gemm_phase(PG8_LAS unsigned char* lds, const Gemm g, const Sched& S, const Epi& E) {
;     ...
;             PG8_WAIT_V(8); PG8_WAIT_L(0); PG8_BAR; PG8_MMA(1, 0, At, B0); PG8_MMA(1, 1, At, B1); PG8_BAR; PG8_SCHED;
;             PG8_LDB(B0, 1, 0); PG8_LDB(B1, 1, 1); PG8_SCHED; PG8_LDA(At, 1, 0); PG8_STAGE(PG8_SA(0, 1), a2 + hstepA, voffA);
;             PG8_WAIT_V(8); PG8_WAIT_L(0); PG8_BAR; PG8_MMA(0, 0, At, B0); PG8_MMA(0, 1, At, B1); PG8_BAR; PG8_SCHED;
	s_setprio 1
	v_mfma_f32_16x16x32_bf16 v[60:63], v[144:147], v[188:191], v[60:63]
	v_mfma_f32_16x16x32_bf16 v[56:59], v[162:165], v[188:191], v[56:59]
	v_mfma_f32_16x16x32_bf16 v[44:47], v[144:147], v[196:199], v[44:47]
	v_mfma_f32_16x16x32_bf16 v[40:43], v[162:165], v[196:199], v[40:43]
	v_mfma_f32_16x16x32_bf16 v[28:31], v[144:147], v[204:207], v[28:31]
	v_mfma_f32_16x16x32_bf16 v[24:27], v[162:165], v[204:207], v[24:27]
	v_mfma_f32_16x16x32_bf16 v[12:15], v[144:147], v[212:215], v[12:15]
	v_mfma_f32_16x16x32_bf16 v[8:11], v[162:165], v[212:215], v[8:11]
	v_mfma_f32_16x16x32_bf16 v[60:63], v[158:161], v[192:195], v[60:63]
	v_mfma_f32_16x16x32_bf16 v[56:59], v[166:169], v[192:195], v[56:59]
	v_mfma_f32_16x16x32_bf16 v[44:47], v[158:161], v[200:203], v[44:47]
	v_mfma_f32_16x16x32_bf16 v[40:43], v[166:169], v[200:203], v[40:43]
	v_mfma_f32_16x16x32_bf16 v[28:31], v[158:161], v[208:211], v[28:31]
	v_mfma_f32_16x16x32_bf16 v[24:27], v[166:169], v[208:211], v[24:27]
	v_mfma_f32_16x16x32_bf16 v[12:15], v[158:161], v[216:219], v[12:15]
	v_mfma_f32_16x16x32_bf16 v[8:11], v[166:169], v[216:219], v[8:11]
	s_setprio 0
	s_setprio 1
	v_mfma_f32_16x16x32_bf16 v[52:55], v[170:173], v[188:191], v[52:55]
	v_mfma_f32_16x16x32_bf16 v[48:51], v[178:181], v[188:191], v[48:51]
	v_mfma_f32_16x16x32_bf16 v[36:39], v[170:173], v[196:199], v[36:39]
	v_mfma_f32_16x16x32_bf16 v[32:35], v[178:181], v[196:199], v[32:35]
	v_mfma_f32_16x16x32_bf16 v[20:23], v[170:173], v[204:207], v[20:23]
	v_mfma_f32_16x16x32_bf16 v[16:19], v[178:181], v[204:207], v[16:19]
	v_mfma_f32_16x16x32_bf16 v[4:7], v[170:173], v[212:215], v[4:7]
	v_mfma_f32_16x16x32_bf16 v[0:3], v[178:181], v[212:215], v[0:3]
	v_mfma_f32_16x16x32_bf16 v[52:55], v[174:177], v[192:195], v[52:55]
	v_mfma_f32_16x16x32_bf16 v[48:51], v[182:185], v[192:195], v[48:51]
	v_mfma_f32_16x16x32_bf16 v[36:39], v[174:177], v[200:203], v[36:39]
	v_mfma_f32_16x16x32_bf16 v[32:35], v[182:185], v[200:203], v[32:35]
	v_mfma_f32_16x16x32_bf16 v[20:23], v[174:177], v[208:211], v[20:23]
	v_mfma_f32_16x16x32_bf16 v[16:19], v[182:185], v[208:211], v[16:19]
	v_mfma_f32_16x16x32_bf16 v[4:7], v[174:177], v[216:219], v[4:7]
	v_mfma_f32_16x16x32_bf16 v[0:3], v[182:185], v[216:219], v[0:3]
	s_barrier
	s_setprio 0
	s_add_i32 s58, 0, 0x18000
	v_add_u32_e32 v157, s58, v151
	s_add_i32 s59, 0, 0x1c000
	ds_read_b128 v[144:147], v157
	ds_read_b128 v[158:161], v157 offset:1024
	ds_read_b128 v[162:165], v157 offset:2048
	ds_read_b128 v[166:169], v157 offset:3072
	v_add_u32_e32 v157, s59, v151
	ds_read_b128 v[170:173], v157
	ds_read_b128 v[174:177], v157 offset:1024
	ds_read_b128 v[178:181], v157 offset:2048
	ds_read_b128 v[182:185], v157 offset:3072
	s_add_u32 s28, s36, 0x30000
	s_addc_u32 s29, s37, 0
	s_mov_b32 m0, s44
	v_lshl_add_u64 v[226:227], s[28:29], 0, v[134:135]
	ds_read_b128 v[188:191], v155 offset:32768
	ds_read_b128 v[192:195], v155 offset:33792
	ds_read_b128 v[196:199], v155 offset:34816
	ds_read_b128 v[200:203], v155 offset:35840
	ds_read_b128 v[204:207], v155 offset:36864
	ds_read_b128 v[208:211], v155 offset:37888
	ds_read_b128 v[212:215], v155 offset:38912
	ds_read_b128 v[216:219], v155 offset:39936
	global_load_lds_dwordx4 v[226:227], off
	s_mov_b32 m0, s45
	v_lshl_add_u64 v[226:227], s[28:29], 0, v[130:131]
	global_load_lds_dwordx4 v[226:227], off
	s_waitcnt vmcnt(8) lgkmcnt(0)
	s_barrier
	s_setprio 1
	v_mfma_f32_16x16x32_bf16 v[124:127], v[144:147], v[188:191], v[124:127]
	v_mfma_f32_16x16x32_bf16 v[120:123], v[162:165], v[188:191], v[120:123]
	v_mfma_f32_16x16x32_bf16 v[108:111], v[144:147], v[196:199], v[108:111]
	v_mfma_f32_16x16x32_bf16 v[104:107], v[162:165], v[196:199], v[104:107]
	v_mfma_f32_16x16x32_bf16 v[92:95], v[144:147], v[204:207], v[92:95]
	v_mfma_f32_16x16x32_bf16 v[88:91], v[162:165], v[204:207], v[88:91]
	v_mfma_f32_16x16x32_bf16 v[76:79], v[144:147], v[212:215], v[76:79]
	v_mfma_f32_16x16x32_bf16 v[72:75], v[162:165], v[212:215], v[72:75]
	v_mfma_f32_16x16x32_bf16 v[124:127], v[158:161], v[192:195], v[124:127]
	v_mfma_f32_16x16x32_bf16 v[120:123], v[166:169], v[192:195], v[120:123]
	v_mfma_f32_16x16x32_bf16 v[108:111], v[158:161], v[200:203], v[108:111]
	v_mfma_f32_16x16x32_bf16 v[104:107], v[166:169], v[200:203], v[104:107]
	v_mfma_f32_16x16x32_bf16 v[92:95], v[158:161], v[208:211], v[92:95]
	v_mfma_f32_16x16x32_bf16 v[88:91], v[166:169], v[208:211], v[88:91]
	v_mfma_f32_16x16x32_bf16 v[76:79], v[158:161], v[216:219], v[76:79]
	v_mfma_f32_16x16x32_bf16 v[72:75], v[166:169], v[216:219], v[72:75]
	s_setprio 0
	s_setprio 1
	v_mfma_f32_16x16x32_bf16 v[116:119], v[170:173], v[188:191], v[116:119]
	v_mfma_f32_16x16x32_bf16 v[112:115], v[178:181], v[188:191], v[112:115]
	v_mfma_f32_16x16x32_bf16 v[100:103], v[170:173], v[196:199], v[100:103]
	v_mfma_f32_16x16x32_bf16 v[96:99], v[178:181], v[196:199], v[96:99]
	v_mfma_f32_16x16x32_bf16 v[84:87], v[170:173], v[204:207], v[84:87]
	v_mfma_f32_16x16x32_bf16 v[80:83], v[178:181], v[204:207], v[80:83]
	v_mfma_f32_16x16x32_bf16 v[68:71], v[170:173], v[212:215], v[68:71]
	v_mfma_f32_16x16x32_bf16 v[64:67], v[178:181], v[212:215], v[64:67]
	v_mfma_f32_16x16x32_bf16 v[116:119], v[174:177], v[192:195], v[116:119]
	v_mfma_f32_16x16x32_bf16 v[112:115], v[182:185], v[192:195], v[112:115]
	v_mfma_f32_16x16x32_bf16 v[100:103], v[174:177], v[200:203], v[100:103]
	v_mfma_f32_16x16x32_bf16 v[96:99], v[182:185], v[200:203], v[96:99]
	v_mfma_f32_16x16x32_bf16 v[84:87], v[174:177], v[208:211], v[84:87]
	v_mfma_f32_16x16x32_bf16 v[80:83], v[182:185], v[208:211], v[80:83]
	v_mfma_f32_16x16x32_bf16 v[68:71], v[174:177], v[216:219], v[68:71]
	v_mfma_f32_16x16x32_bf16 v[64:67], v[182:185], v[216:219], v[64:67]
	s_barrier
; #define PG8_STAGE(bufoff, gbase, voff) do { _Pragma("unroll") for (int _i = 0; _i < 2; ++_i) \
;         __builtin_amdgcn_global_load_lds((const unsigned*)((const char*)(gbase) + (voff)[_i]), (PG8_LAS unsigned*)(lds + (bufoff) + ldsw + _i * 8192), 16, 0, 0); } while (0)
; #define PG8_LDA(dst, b, h) do { _Pragma("unroll") for (int m = 0; m < 4; ++m) _Pragma("unroll") for (int k = 0; k < 2; ++k) dst[m][k] = *(const PG8_LAS bf16x8*)(lds + PG8_SA(b, h) + aoff + m * 2048 + k * 1024); } while (0)
; #define PG8_MMA(ai, bj, At, Bt) do { __builtin_amdgcn_s_setprio(1); _Pragma("unroll") for (int m = 0; m < 4; ++m) _Pragma("unroll") for (int n = 0; n < 2; ++n) _Pragma("unroll") for (int k = 0; k < 2; ++k) \
;         acc[ai][bj][m][n] = __builtin_amdgcn_mfma_f32_16x16x32_bf16(Bt[n][k], At[m][k], acc[ai][bj][m][n], 0, 0, 0); __builtin_amdgcn_s_setprio(0); } while (0)
; #define PG8_WAIT_V(n) asm volatile("s_waitcnt vmcnt(" #n ")" ::: "memory")
; #define PG8_WAIT_L(n) asm volatile("s_waitcnt lgkmcnt(" #n ")" ::: "memory")
; #define PG8_BAR __builtin_amdgcn_s_barrier()
; #define PG8_SCHED __builtin_amdgcn_sched_barrier(0)
; template <class Epi, class Sched, bool ALIGN_EPI = false, bool SP2 = false>
; __device__ __forceinline__ void gemm_phase(PG8_LAS unsigned char* lds, const Gemm g, const Sched& S, const Epi& E) {
;     ...
;             PG8_LDA(At, 1, 1); PG8_STAGE(PG8_SB(1, 0), b3, voffB); PG8_STAGE(PG8_SB(1, 1), b3 + hstepB, voffB); PG8_STAGE(PG8_SA(1, 0), a3, voffA);
;             PG8_WAIT_V(8); PG8_WAIT_L(0); PG8_BAR; PG8_MMA(1, 0, At, B0); PG8_MMA(1, 1, At, B1); PG8_BAR; PG8_SCHED;
;     ...
;         if constexpr (ALIGN_EPI) { if (wr == 0) PG8_BAR; }
	s_setprio 0
	s_add_i32 s28, s58, s40
	v_lshl_add_u64 v[148:149], v[148:149], 0, s[12:13]
	s_mov_b32 m0, s28
	ds_read_b128 v[188:191], v155 offset:49152
	ds_read_b128 v[192:195], v155 offset:50176
	ds_read_b128 v[196:199], v155 offset:51200
	ds_read_b128 v[200:203], v155 offset:52224
	ds_read_b128 v[204:207], v155 offset:53248
	ds_read_b128 v[208:211], v155 offset:54272
	ds_read_b128 v[212:215], v155 offset:55296
	ds_read_b128 v[216:219], v155 offset:56320
	global_load_lds_dwordx4 v[148:149], off
	s_add_i32 m0, s28, 0x2000
	s_add_u32 s28, s34, 0x18080
	v_lshl_add_u64 v[148:149], v[220:221], 0, s[12:13]
	s_addc_u32 s29, s35, 0
	s_add_i32 s34, s59, s40
	global_load_lds_dwordx4 v[148:149], off
	s_mov_b32 m0, s34
	v_lshl_add_u64 v[148:149], s[28:29], 0, v[132:133]
	global_load_lds_dwordx4 v[148:149], off
	s_add_i32 m0, s34, 0x2000
	v_lshl_add_u64 v[148:149], s[28:29], 0, v[128:129]
	global_load_lds_dwordx4 v[148:149], off
	s_mov_b32 m0, s47
	v_lshl_add_u64 v[148:149], v[222:223], 0, s[12:13]
	global_load_lds_dwordx4 v[148:149], off
	s_mov_b32 m0, s48
	v_lshl_add_u64 v[148:149], v[224:225], 0, s[12:13]
	global_load_lds_dwordx4 v[148:149], off
	s_waitcnt vmcnt(8) lgkmcnt(0)
	s_barrier
	s_setprio 1
	v_mfma_f32_16x16x32_bf16 v[60:63], v[144:147], v[188:191], v[60:63]
	v_mfma_f32_16x16x32_bf16 v[56:59], v[162:165], v[188:191], v[56:59]
	v_mfma_f32_16x16x32_bf16 v[44:47], v[144:147], v[196:199], v[44:47]
	v_mfma_f32_16x16x32_bf16 v[40:43], v[162:165], v[196:199], v[40:43]
	v_mfma_f32_16x16x32_bf16 v[28:31], v[144:147], v[204:207], v[28:31]
	v_mfma_f32_16x16x32_bf16 v[24:27], v[162:165], v[204:207], v[24:27]
	v_mfma_f32_16x16x32_bf16 v[12:15], v[144:147], v[212:215], v[12:15]
	v_mfma_f32_16x16x32_bf16 v[8:11], v[162:165], v[212:215], v[8:11]
	v_mfma_f32_16x16x32_bf16 v[60:63], v[158:161], v[192:195], v[60:63]
	v_mfma_f32_16x16x32_bf16 v[56:59], v[166:169], v[192:195], v[56:59]
	v_mfma_f32_16x16x32_bf16 v[44:47], v[158:161], v[200:203], v[44:47]
	v_mfma_f32_16x16x32_bf16 v[40:43], v[166:169], v[200:203], v[40:43]
	v_mfma_f32_16x16x32_bf16 v[28:31], v[158:161], v[208:211], v[28:31]
	v_mfma_f32_16x16x32_bf16 v[24:27], v[166:169], v[208:211], v[24:27]
	v_mfma_f32_16x16x32_bf16 v[12:15], v[158:161], v[216:219], v[12:15]
	v_mfma_f32_16x16x32_bf16 v[8:11], v[166:169], v[216:219], v[8:11]
	s_setprio 0
	s_setprio 1
	v_mfma_f32_16x16x32_bf16 v[52:55], v[170:173], v[188:191], v[52:55]
	v_mfma_f32_16x16x32_bf16 v[48:51], v[178:181], v[188:191], v[48:51]
	v_mfma_f32_16x16x32_bf16 v[36:39], v[170:173], v[196:199], v[36:39]
	v_mfma_f32_16x16x32_bf16 v[32:35], v[178:181], v[196:199], v[32:35]
	v_mfma_f32_16x16x32_bf16 v[20:23], v[170:173], v[204:207], v[20:23]
	v_mfma_f32_16x16x32_bf16 v[16:19], v[178:181], v[204:207], v[16:19]
	v_mfma_f32_16x16x32_bf16 v[4:7], v[170:173], v[212:215], v[4:7]
	v_mfma_f32_16x16x32_bf16 v[0:3], v[178:181], v[212:215], v[0:3]
	v_mfma_f32_16x16x32_bf16 v[52:55], v[174:177], v[192:195], v[52:55]
	v_mfma_f32_16x16x32_bf16 v[48:51], v[182:185], v[192:195], v[48:51]
	v_mfma_f32_16x16x32_bf16 v[36:39], v[174:177], v[200:203], v[36:39]
	v_mfma_f32_16x16x32_bf16 v[32:35], v[182:185], v[200:203], v[32:35]
	v_mfma_f32_16x16x32_bf16 v[20:23], v[174:177], v[208:211], v[20:23]
	v_mfma_f32_16x16x32_bf16 v[16:19], v[182:185], v[208:211], v[16:19]
	v_mfma_f32_16x16x32_bf16 v[4:7], v[174:177], v[216:219], v[4:7]
	v_mfma_f32_16x16x32_bf16 v[0:3], v[182:185], v[216:219], v[0:3]
	s_barrier
	s_setprio 0
	s_add_i32 s76, s76, 2
	s_add_u32 s74, s74, 0x100
	s_addc_u32 s75, s75, 0
	s_cmp_gt_u32 s76, 3
	s_mov_b64 s[28:29], s[30:31]
	s_cbranch_scc0 .LBB0_524
	s_and_b64 vcc, exec, s[14:15]
	s_cbranch_vccz .LBB0_527
	s_barrier

; #define PG8_STAGE(bufoff, gbase, voff) do { _Pragma("unroll") for (int _i = 0; _i < 2; ++_i) \
;         __builtin_amdgcn_global_load_lds((const unsigned*)((const char*)(gbase) + (voff)[_i]), (PG8_LAS unsigned*)(lds + (bufoff) + ldsw + _i * 8192), 16, 0, 0); } while (0)
; #define PG8_LDA(dst, b, h) do { _Pragma("unroll") for (int m = 0; m < 4; ++m) _Pragma("unroll") for (int k = 0; k < 2; ++k) dst[m][k] = *(const PG8_LAS bf16x8*)(lds + PG8_SA(b, h) + aoff + m * 2048 + k * 1024); } while (0)
; #define PG8_LDB(dst, b, h) do { _Pragma("unroll") for (int n = 0; n < 2; ++n) _Pragma("unroll") for (int k = 0; k < 2; ++k) dst[n][k] = *(const PG8_LAS bf16x8*)(lds + PG8_SB(b, h) + boff + n * 2048 + k * 1024); } while (0)
; #define PG8_MMA(ai, bj, At, Bt) do { __builtin_amdgcn_s_setprio(1); _Pragma("unroll") for (int m = 0; m < 4; ++m) _Pragma("unroll") for (int n = 0; n < 2; ++n) _Pragma("unroll") for (int k = 0; k < 2; ++k) \
;         acc[ai][bj][m][n] = __builtin_amdgcn_mfma_f32_16x16x32_bf16(Bt[n][k], At[m][k], acc[ai][bj][m][n], 0, 0, 0); __builtin_amdgcn_s_setprio(0); } while (0)
; #define PG8_WAIT_V(n) asm volatile("s_waitcnt vmcnt(" #n ")" ::: "memory")
; #define PG8_WAIT_L(n) asm volatile("s_waitcnt lgkmcnt(" #n ")" ::: "memory")
; #define PG8_BAR __builtin_amdgcn_s_barrier()
; #define PG8_SCHED __builtin_amdgcn_sched_barrier(0)
; template <class Epi, class Sched, bool ALIGN_EPI = false, bool SP2 = false>
; __device__ __forceinline__ void gemm_phase(PG8_LAS unsigned char* lds, const Gemm g, const Sched& S, const Epi& E) {
;     ...
;             const bool last = (t == nt - 2);
;             const char* a1 = cA + (size_t)(t + 1) * kstep;
;             const char* a2 = last ? nA : cA + (size_t)(t + 2) * kstep; const char* b2 = last ? nB : cB + (size_t)(t + 2) * kstep;
;             const char* a3 = a2 + kstep; const char* b3 = b2 + kstep;
;             if (last && has_next) S.a_ready(nxt);
;             if constexpr (SP2) {
;             PG8_LDB(B0, 0, 0); PG8_LDB(B1, 0, 1); PG8_SCHED; PG8_LDA(At, 0, 0); PG8_STAGE(PG8_SA(1, 1), a1 + hstepA, voffA);
;             PG8_WAIT_V(8); PG8_WAIT_L(0); PG8_BAR; PG8_MMA(0, 0, At, B0); PG8_MMA(0, 1, At, B1); PG8_BAR; PG8_SCHED;
;             PG8_LDA(At, 0, 1); PG8_STAGE(PG8_SB(0, 0), b2, voffB); PG8_STAGE(PG8_SB(0, 1), b2 + hstepB, voffB); PG8_STAGE(PG8_SA(0, 0), a2, voffA);
.LBB0_542:
	s_add_u32 s39, s34, s38
	s_addc_u32 s44, s35, 0
	s_add_u32 s42, s39, 0x100
	s_addc_u32 s43, s44, 0
	s_and_b64 s[40:41], s[36:37], exec
	s_cselect_b32 s41, s27, s43
	s_cselect_b32 s40, s26, s42
	s_add_u32 s38, s30, s38
	s_addc_u32 s42, s31, 0
	s_add_u32 s38, s38, 0x100
	s_addc_u32 s42, s42, 0
	s_and_b64 s[36:37], s[36:37], exec
	s_cselect_b32 s43, s25, s42
	s_cselect_b32 s42, s89, s38
	s_add_u32 s46, s39, 0x30080
	ds_read_b128 v[140:143], v149
	ds_read_b128 v[154:157], v149 offset:1024
	ds_read_b128 v[158:161], v149 offset:2048
	ds_read_b128 v[162:165], v149 offset:3072
	ds_read_b128 v[166:169], v150
	ds_read_b128 v[170:173], v150 offset:1024
	ds_read_b128 v[174:177], v150 offset:2048
	ds_read_b128 v[178:181], v150 offset:3072
	s_addc_u32 s47, s44, 0
	s_add_i32 vcc_hi, s78, s68
	s_add_i32 m0, s70, 0xc000
	s_add_i32 s58, s70, 0xe000
	s_add_i32 s96, vcc_hi, 0x2000
	s_add_u32 s44, s42, 0x10000
	s_addc_u32 s45, s43, 0
	s_add_i32 vcc_lo, s79, s68
	s_add_i32 s97, vcc_lo, 0x2000
	s_add_i32 s95, 0, 0x18000
	s_add_i32 s94, 0, 0x1c000
	s_add_u32 s38, s40, 0x30000
	s_addc_u32 s39, s41, 0
	s_add_i32 s93, s95, s68
	s_add_i32 s91, s93, 0x2000
	s_add_u32 s36, s42, 0x10080
	s_addc_u32 s37, s43, 0
	s_add_i32 s92, s94, s68
	s_add_i32 s90, s92, 0x2000
	v_lshl_add_u64 v[144:145], s[46:47], 0, v[134:135]
	ds_read_b128 v[182:185], v151
	ds_read_b128 v[188:191], v151 offset:1024
	ds_read_b128 v[192:195], v151 offset:2048
	ds_read_b128 v[196:199], v151 offset:3072
	ds_read_b128 v[200:203], v151 offset:4096
	ds_read_b128 v[204:207], v151 offset:5120
	ds_read_b128 v[208:211], v151 offset:6144
	ds_read_b128 v[212:215], v151 offset:7168
	global_load_lds_dwordx4 v[144:145], off
	s_mov_b32 m0, s58
	v_lshl_add_u64 v[144:145], s[46:47], 0, v[130:131]
	global_load_lds_dwordx4 v[144:145], off
	s_waitcnt vmcnt(8) lgkmcnt(0)
	s_barrier
	s_setprio 1
	v_mfma_f32_16x16x32_bf16 v[124:127], v[140:143], v[182:185], v[124:127]
	v_mfma_f32_16x16x32_bf16 v[120:123], v[158:161], v[182:185], v[120:123]
	v_mfma_f32_16x16x32_bf16 v[108:111], v[140:143], v[192:195], v[108:111]
	v_mfma_f32_16x16x32_bf16 v[104:107], v[158:161], v[192:195], v[104:107]
	v_mfma_f32_16x16x32_bf16 v[92:95], v[140:143], v[200:203], v[92:95]
	v_mfma_f32_16x16x32_bf16 v[88:91], v[158:161], v[200:203], v[88:91]
	v_mfma_f32_16x16x32_bf16 v[76:79], v[140:143], v[208:211], v[76:79]
	v_mfma_f32_16x16x32_bf16 v[72:75], v[158:161], v[208:211], v[72:75]
	v_mfma_f32_16x16x32_bf16 v[124:127], v[154:157], v[188:191], v[124:127]
	v_mfma_f32_16x16x32_bf16 v[120:123], v[162:165], v[188:191], v[120:123]
	v_mfma_f32_16x16x32_bf16 v[108:111], v[154:157], v[196:199], v[108:111]
	v_mfma_f32_16x16x32_bf16 v[104:107], v[162:165], v[196:199], v[104:107]
	v_mfma_f32_16x16x32_bf16 v[92:95], v[154:157], v[204:207], v[92:95]
	v_mfma_f32_16x16x32_bf16 v[88:91], v[162:165], v[204:207], v[88:91]
	v_mfma_f32_16x16x32_bf16 v[76:79], v[154:157], v[212:215], v[76:79]
	v_mfma_f32_16x16x32_bf16 v[72:75], v[162:165], v[212:215], v[72:75]
	s_setprio 0
	s_setprio 1
	v_mfma_f32_16x16x32_bf16 v[116:119], v[166:169], v[182:185], v[116:119]
	v_mfma_f32_16x16x32_bf16 v[112:115], v[174:177], v[182:185], v[112:115]
	v_mfma_f32_16x16x32_bf16 v[100:103], v[166:169], v[192:195], v[100:103]
	v_mfma_f32_16x16x32_bf16 v[96:99], v[174:177], v[192:195], v[96:99]
	v_mfma_f32_16x16x32_bf16 v[84:87], v[166:169], v[200:203], v[84:87]
	v_mfma_f32_16x16x32_bf16 v[80:83], v[174:177], v[200:203], v[80:83]
	v_mfma_f32_16x16x32_bf16 v[68:71], v[166:169], v[208:211], v[68:71]
	v_mfma_f32_16x16x32_bf16 v[64:67], v[174:177], v[208:211], v[64:67]
	v_mfma_f32_16x16x32_bf16 v[116:119], v[170:173], v[188:191], v[116:119]
	v_mfma_f32_16x16x32_bf16 v[112:115], v[178:181], v[188:191], v[112:115]
	v_mfma_f32_16x16x32_bf16 v[100:103], v[170:173], v[196:199], v[100:103]
	v_mfma_f32_16x16x32_bf16 v[96:99], v[178:181], v[196:199], v[96:99]
	v_mfma_f32_16x16x32_bf16 v[84:87], v[170:173], v[204:207], v[84:87]
	v_mfma_f32_16x16x32_bf16 v[80:83], v[178:181], v[204:207], v[80:83]
	v_mfma_f32_16x16x32_bf16 v[68:71], v[170:173], v[212:215], v[68:71]
	v_mfma_f32_16x16x32_bf16 v[64:67], v[178:181], v[212:215], v[64:67]
	s_barrier
	s_setprio 0
	s_mov_b32 m0, vcc_hi
	v_lshl_add_u64 v[144:145], s[42:43], 0, v[132:133]
	ds_read_b128 v[182:185], v151 offset:16384
	ds_read_b128 v[188:191], v151 offset:17408
	ds_read_b128 v[192:195], v151 offset:18432
	ds_read_b128 v[196:199], v151 offset:19456
	ds_read_b128 v[200:203], v151 offset:20480
	ds_read_b128 v[204:207], v151 offset:21504
	ds_read_b128 v[208:211], v151 offset:22528
	ds_read_b128 v[212:215], v151 offset:23552
	global_load_lds_dwordx4 v[144:145], off
	v_lshl_add_u64 v[216:217], s[42:43], 0, v[128:129]
	s_mov_b32 m0, s96
	v_lshl_add_u64 v[218:219], s[44:45], 0, v[132:133]
	global_load_lds_dwordx4 v[216:217], off
	s_mov_b32 m0, vcc_lo
	v_lshl_add_u64 v[220:221], s[40:41], 0, v[130:131]
	global_load_lds_dwordx4 v[218:219], off
	s_mov_b32 m0, s97
	v_lshl_add_u64 v[218:219], s[44:45], 0, v[128:129]
	global_load_lds_dwordx4 v[218:219], off
	s_mov_b32 m0, s70
	v_lshl_add_u64 v[218:219], s[40:41], 0, v[134:135]
	global_load_lds_dwordx4 v[218:219], off
	s_mov_b32 m0, s71
	s_nop 0
	global_load_lds_dwordx4 v[220:221], off
	s_waitcnt vmcnt(8) lgkmcnt(0)
	s_barrier
; #define PG8_STAGE(bufoff, gbase, voff) do { _Pragma("unroll") for (int _i = 0; _i < 2; ++_i) \
;         __builtin_amdgcn_global_load_lds((const unsigned*)((const char*)(gbase) + (voff)[_i]), (PG8_LAS unsigned*)(lds + (bufoff) + ldsw + _i * 8192), 16, 0, 0); } while (0)
; #define PG8_LDA(dst, b, h) do { _Pragma("unroll") for (int m = 0; m < 4; ++m) _Pragma("unroll") for (int k = 0; k < 2; ++k) dst[m][k] = *(const PG8_LAS bf16x8*)(lds + PG8_SA(b, h) + aoff + m * 2048 + k * 1024); } while (0)
; #define PG8_LDB(dst, b, h) do { _Pragma("unroll") for (int n = 0; n < 2; ++n) _Pragma("unroll") for (int k = 0; k < 2; ++k) dst[n][k] = *(const PG8_LAS bf16x8*)(lds + PG8_SB(b, h) + boff + n * 2048 + k * 1024); } while (0)
; #define PG8_MMA(ai, bj, At, Bt) do { __builtin_amdgcn_s_setprio(1); _Pragma("unroll") for (int m = 0; m < 4; ++m) _Pragma("unroll") for (int n = 0; n < 2; ++n) _Pragma("unroll") for (int k = 0; k < 2; ++k) \
;         acc[ai][bj][m][n] = __builtin_amdgcn_mfma_f32_16x16x32_bf16(Bt[n][k], At[m][k], acc[ai][bj][m][n], 0, 0, 0); __builtin_amdgcn_s_setprio(0); } while (0)
; #define PG8_WAIT_V(n) asm volatile("s_waitcnt vmcnt(" #n ")" ::: "memory")
; #define PG8_WAIT_L(n) asm volatile("s_waitcnt lgkmcnt(" #n ")" ::: "memory")
; #define PG8_BAR __builtin_amdgcn_s_barrier()
; #define PG8_SCHED __builtin_amdgcn_sched_barrier(0)
; template <class Epi, class Sched, bool ALIGN_EPI = false, bool SP2 = false>
; __device__ __forceinline__ void gemm_phase(PG8_LAS unsigned char* lds, const Gemm g, const Sched& S, const Epi& E) {
;     ...
;             PG8_WAIT_V(8); PG8_WAIT_L(0); PG8_BAR; PG8_MMA(1, 0, At, B0); PG8_MMA(1, 1, At, B1); PG8_BAR; PG8_SCHED;
;             PG8_LDB(B0, 1, 0); PG8_LDB(B1, 1, 1); PG8_SCHED; PG8_LDA(At, 1, 0); PG8_STAGE(PG8_SA(0, 1), a2 + hstepA, voffA);
;             PG8_WAIT_V(8); PG8_WAIT_L(0); PG8_BAR; PG8_MMA(0, 0, At, B0); PG8_MMA(0, 1, At, B1); PG8_BAR; PG8_SCHED;
	s_setprio 1
	v_mfma_f32_16x16x32_bf16 v[60:63], v[140:143], v[182:185], v[60:63]
	v_mfma_f32_16x16x32_bf16 v[56:59], v[158:161], v[182:185], v[56:59]
	v_mfma_f32_16x16x32_bf16 v[44:47], v[140:143], v[192:195], v[44:47]
	v_mfma_f32_16x16x32_bf16 v[40:43], v[158:161], v[192:195], v[40:43]
	v_mfma_f32_16x16x32_bf16 v[28:31], v[140:143], v[200:203], v[28:31]
	v_mfma_f32_16x16x32_bf16 v[24:27], v[158:161], v[200:203], v[24:27]
	v_mfma_f32_16x16x32_bf16 v[12:15], v[140:143], v[208:211], v[12:15]
	v_mfma_f32_16x16x32_bf16 v[8:11], v[158:161], v[208:211], v[8:11]
	v_mfma_f32_16x16x32_bf16 v[60:63], v[154:157], v[188:191], v[60:63]
	v_mfma_f32_16x16x32_bf16 v[56:59], v[162:165], v[188:191], v[56:59]
	v_mfma_f32_16x16x32_bf16 v[44:47], v[154:157], v[196:199], v[44:47]
	v_mfma_f32_16x16x32_bf16 v[40:43], v[162:165], v[196:199], v[40:43]
	v_mfma_f32_16x16x32_bf16 v[28:31], v[154:157], v[204:207], v[28:31]
	v_mfma_f32_16x16x32_bf16 v[24:27], v[162:165], v[204:207], v[24:27]
	v_mfma_f32_16x16x32_bf16 v[12:15], v[154:157], v[212:215], v[12:15]
	v_mfma_f32_16x16x32_bf16 v[8:11], v[162:165], v[212:215], v[8:11]
	s_setprio 0
	s_setprio 1
	v_mfma_f32_16x16x32_bf16 v[52:55], v[166:169], v[182:185], v[52:55]
	v_mfma_f32_16x16x32_bf16 v[48:51], v[174:177], v[182:185], v[48:51]
	v_mfma_f32_16x16x32_bf16 v[36:39], v[166:169], v[192:195], v[36:39]
	v_mfma_f32_16x16x32_bf16 v[32:35], v[174:177], v[192:195], v[32:35]
	v_mfma_f32_16x16x32_bf16 v[20:23], v[166:169], v[200:203], v[20:23]
	v_mfma_f32_16x16x32_bf16 v[16:19], v[174:177], v[200:203], v[16:19]
	v_mfma_f32_16x16x32_bf16 v[4:7], v[166:169], v[208:211], v[4:7]
	v_mfma_f32_16x16x32_bf16 v[0:3], v[174:177], v[208:211], v[0:3]
	v_mfma_f32_16x16x32_bf16 v[52:55], v[170:173], v[188:191], v[52:55]
	v_mfma_f32_16x16x32_bf16 v[48:51], v[178:181], v[188:191], v[48:51]
	v_mfma_f32_16x16x32_bf16 v[36:39], v[170:173], v[196:199], v[36:39]
	v_mfma_f32_16x16x32_bf16 v[32:35], v[178:181], v[196:199], v[32:35]
	v_mfma_f32_16x16x32_bf16 v[20:23], v[170:173], v[204:207], v[20:23]
	v_mfma_f32_16x16x32_bf16 v[16:19], v[178:181], v[204:207], v[16:19]
	v_mfma_f32_16x16x32_bf16 v[4:7], v[170:173], v[212:215], v[4:7]
	v_mfma_f32_16x16x32_bf16 v[0:3], v[178:181], v[212:215], v[0:3]
	s_barrier
	s_setprio 0
	v_add_u32_e32 v153, s95, v147
	ds_read_b128 v[140:143], v153
	ds_read_b128 v[154:157], v153 offset:1024
	ds_read_b128 v[158:161], v153 offset:2048
	ds_read_b128 v[162:165], v153 offset:3072
	v_add_u32_e32 v153, s94, v147
	ds_read_b128 v[166:169], v153
	ds_read_b128 v[170:173], v153 offset:1024
	ds_read_b128 v[174:177], v153 offset:2048
	ds_read_b128 v[178:181], v153 offset:3072
	s_mov_b32 m0, s72
	v_lshl_add_u64 v[222:223], s[38:39], 0, v[134:135]
	ds_read_b128 v[182:185], v151 offset:32768
	ds_read_b128 v[188:191], v151 offset:33792
	ds_read_b128 v[192:195], v151 offset:34816
	ds_read_b128 v[196:199], v151 offset:35840
	ds_read_b128 v[200:203], v151 offset:36864
	ds_read_b128 v[204:207], v151 offset:37888
	ds_read_b128 v[208:211], v151 offset:38912
	ds_read_b128 v[212:215], v151 offset:39936
	global_load_lds_dwordx4 v[222:223], off
	s_mov_b32 m0, s73
	v_lshl_add_u64 v[222:223], s[38:39], 0, v[130:131]
	global_load_lds_dwordx4 v[222:223], off
	s_waitcnt vmcnt(8) lgkmcnt(0)
	s_barrier
	s_setprio 1
	v_mfma_f32_16x16x32_bf16 v[124:127], v[140:143], v[182:185], v[124:127]
	v_mfma_f32_16x16x32_bf16 v[120:123], v[158:161], v[182:185], v[120:123]
	v_mfma_f32_16x16x32_bf16 v[108:111], v[140:143], v[192:195], v[108:111]
	v_mfma_f32_16x16x32_bf16 v[104:107], v[158:161], v[192:195], v[104:107]
	v_mfma_f32_16x16x32_bf16 v[92:95], v[140:143], v[200:203], v[92:95]
	v_mfma_f32_16x16x32_bf16 v[88:91], v[158:161], v[200:203], v[88:91]
	v_mfma_f32_16x16x32_bf16 v[76:79], v[140:143], v[208:211], v[76:79]
	v_mfma_f32_16x16x32_bf16 v[72:75], v[158:161], v[208:211], v[72:75]
	v_mfma_f32_16x16x32_bf16 v[124:127], v[154:157], v[188:191], v[124:127]
	v_mfma_f32_16x16x32_bf16 v[120:123], v[162:165], v[188:191], v[120:123]
	v_mfma_f32_16x16x32_bf16 v[108:111], v[154:157], v[196:199], v[108:111]
	v_mfma_f32_16x16x32_bf16 v[104:107], v[162:165], v[196:199], v[104:107]
	v_mfma_f32_16x16x32_bf16 v[92:95], v[154:157], v[204:207], v[92:95]
	v_mfma_f32_16x16x32_bf16 v[88:91], v[162:165], v[204:207], v[88:91]
	v_mfma_f32_16x16x32_bf16 v[76:79], v[154:157], v[212:215], v[76:79]
	v_mfma_f32_16x16x32_bf16 v[72:75], v[162:165], v[212:215], v[72:75]
	s_setprio 0
	s_setprio 1
	v_mfma_f32_16x16x32_bf16 v[116:119], v[166:169], v[182:185], v[116:119]
	v_mfma_f32_16x16x32_bf16 v[112:115], v[174:177], v[182:185], v[112:115]
	v_mfma_f32_16x16x32_bf16 v[100:103], v[166:169], v[192:195], v[100:103]
	v_mfma_f32_16x16x32_bf16 v[96:99], v[174:177], v[192:195], v[96:99]
	v_mfma_f32_16x16x32_bf16 v[84:87], v[166:169], v[200:203], v[84:87]
	v_mfma_f32_16x16x32_bf16 v[80:83], v[174:177], v[200:203], v[80:83]
	v_mfma_f32_16x16x32_bf16 v[68:71], v[166:169], v[208:211], v[68:71]
	v_mfma_f32_16x16x32_bf16 v[64:67], v[174:177], v[208:211], v[64:67]
	v_mfma_f32_16x16x32_bf16 v[116:119], v[170:173], v[188:191], v[116:119]
	v_mfma_f32_16x16x32_bf16 v[112:115], v[178:181], v[188:191], v[112:115]
	v_mfma_f32_16x16x32_bf16 v[100:103], v[170:173], v[196:199], v[100:103]
	v_mfma_f32_16x16x32_bf16 v[96:99], v[178:181], v[196:199], v[96:99]
	v_mfma_f32_16x16x32_bf16 v[84:87], v[170:173], v[204:207], v[84:87]
	v_mfma_f32_16x16x32_bf16 v[80:83], v[178:181], v[204:207], v[80:83]
	v_mfma_f32_16x16x32_bf16 v[68:71], v[170:173], v[212:215], v[68:71]
	v_mfma_f32_16x16x32_bf16 v[64:67], v[178:181], v[212:215], v[64:67]
	s_barrier
; #define PG8_STAGE(bufoff, gbase, voff) do { _Pragma("unroll") for (int _i = 0; _i < 2; ++_i) \
;         __builtin_amdgcn_global_load_lds((const unsigned*)((const char*)(gbase) + (voff)[_i]), (PG8_LAS unsigned*)(lds + (bufoff) + ldsw + _i * 8192), 16, 0, 0); } while (0)
; #define PG8_LDA(dst, b, h) do { _Pragma("unroll") for (int m = 0; m < 4; ++m) _Pragma("unroll") for (int k = 0; k < 2; ++k) dst[m][k] = *(const PG8_LAS bf16x8*)(lds + PG8_SA(b, h) + aoff + m * 2048 + k * 1024); } while (0)
; #define PG8_MMA(ai, bj, At, Bt) do { __builtin_amdgcn_s_setprio(1); _Pragma("unroll") for (int m = 0; m < 4; ++m) _Pragma("unroll") for (int n = 0; n < 2; ++n) _Pragma("unroll") for (int k = 0; k < 2; ++k) \
;         acc[ai][bj][m][n] = __builtin_amdgcn_mfma_f32_16x16x32_bf16(Bt[n][k], At[m][k], acc[ai][bj][m][n], 0, 0, 0); __builtin_amdgcn_s_setprio(0); } while (0)
; #define PG8_WAIT_V(n) asm volatile("s_waitcnt vmcnt(" #n ")" ::: "memory")
; #define PG8_WAIT_L(n) asm volatile("s_waitcnt lgkmcnt(" #n ")" ::: "memory")
; #define PG8_BAR __builtin_amdgcn_s_barrier()
; #define PG8_SCHED __builtin_amdgcn_sched_barrier(0)
; template <class Epi, class Sched, bool ALIGN_EPI = false, bool SP2 = false>
; __device__ __forceinline__ void gemm_phase(PG8_LAS unsigned char* lds, const Gemm g, const Sched& S, const Epi& E) {
;     ...
;             PG8_LDA(At, 1, 1); PG8_STAGE(PG8_SB(1, 0), b3, voffB); PG8_STAGE(PG8_SB(1, 1), b3 + hstepB, voffB); PG8_STAGE(PG8_SA(1, 0), a3, voffA);
;             PG8_WAIT_V(8); PG8_WAIT_L(0); PG8_BAR; PG8_MMA(1, 0, At, B0); PG8_MMA(1, 1, At, B1); PG8_BAR; PG8_SCHED;
	s_setprio 0
	s_mov_b32 m0, s93
	v_lshl_add_u64 v[144:145], v[144:145], 0, s[12:13]
	ds_read_b128 v[182:185], v151 offset:49152
	ds_read_b128 v[188:191], v151 offset:50176
	ds_read_b128 v[192:195], v151 offset:51200
	ds_read_b128 v[196:199], v151 offset:52224
	ds_read_b128 v[200:203], v151 offset:53248
	ds_read_b128 v[204:207], v151 offset:54272
	ds_read_b128 v[208:211], v151 offset:55296
	ds_read_b128 v[212:215], v151 offset:56320
	global_load_lds_dwordx4 v[144:145], off
	s_mov_b32 m0, s91
	v_lshl_add_u64 v[144:145], v[216:217], 0, s[12:13]
	global_load_lds_dwordx4 v[144:145], off
	s_mov_b32 m0, s92
	v_lshl_add_u64 v[144:145], s[36:37], 0, v[132:133]
	global_load_lds_dwordx4 v[144:145], off
	s_mov_b32 m0, s90
	v_lshl_add_u64 v[144:145], s[36:37], 0, v[128:129]
	global_load_lds_dwordx4 v[144:145], off
	s_mov_b32 m0, s75
	v_lshl_add_u64 v[144:145], v[218:219], 0, s[12:13]
	global_load_lds_dwordx4 v[144:145], off
	s_mov_b32 m0, s76
	v_lshl_add_u64 v[144:145], v[220:221], 0, s[12:13]
	global_load_lds_dwordx4 v[144:145], off
	s_waitcnt vmcnt(8) lgkmcnt(0)
	s_barrier
	s_setprio 1
	v_mfma_f32_16x16x32_bf16 v[60:63], v[140:143], v[182:185], v[60:63]
	v_mfma_f32_16x16x32_bf16 v[56:59], v[158:161], v[182:185], v[56:59]
	v_mfma_f32_16x16x32_bf16 v[44:47], v[140:143], v[192:195], v[44:47]
	v_mfma_f32_16x16x32_bf16 v[40:43], v[158:161], v[192:195], v[40:43]
	v_mfma_f32_16x16x32_bf16 v[28:31], v[140:143], v[200:203], v[28:31]
	v_mfma_f32_16x16x32_bf16 v[24:27], v[158:161], v[200:203], v[24:27]
	v_mfma_f32_16x16x32_bf16 v[12:15], v[140:143], v[208:211], v[12:15]
	v_mfma_f32_16x16x32_bf16 v[8:11], v[158:161], v[208:211], v[8:11]
	v_mfma_f32_16x16x32_bf16 v[60:63], v[154:157], v[188:191], v[60:63]
	v_mfma_f32_16x16x32_bf16 v[56:59], v[162:165], v[188:191], v[56:59]
	v_mfma_f32_16x16x32_bf16 v[44:47], v[154:157], v[196:199], v[44:47]
	v_mfma_f32_16x16x32_bf16 v[40:43], v[162:165], v[196:199], v[40:43]
	v_mfma_f32_16x16x32_bf16 v[28:31], v[154:157], v[204:207], v[28:31]
	v_mfma_f32_16x16x32_bf16 v[24:27], v[162:165], v[204:207], v[24:27]
	v_mfma_f32_16x16x32_bf16 v[12:15], v[154:157], v[212:215], v[12:15]
	v_mfma_f32_16x16x32_bf16 v[8:11], v[162:165], v[212:215], v[8:11]
	s_setprio 0
	s_setprio 1
	v_mfma_f32_16x16x32_bf16 v[52:55], v[166:169], v[182:185], v[52:55]
	v_mfma_f32_16x16x32_bf16 v[48:51], v[174:177], v[182:185], v[48:51]
	v_mfma_f32_16x16x32_bf16 v[36:39], v[166:169], v[192:195], v[36:39]
	v_mfma_f32_16x16x32_bf16 v[32:35], v[174:177], v[192:195], v[32:35]
	v_mfma_f32_16x16x32_bf16 v[20:23], v[166:169], v[200:203], v[20:23]
	v_mfma_f32_16x16x32_bf16 v[16:19], v[174:177], v[200:203], v[16:19]
	v_mfma_f32_16x16x32_bf16 v[4:7], v[166:169], v[208:211], v[4:7]
	v_mfma_f32_16x16x32_bf16 v[0:3], v[174:177], v[208:211], v[0:3]
	v_mfma_f32_16x16x32_bf16 v[52:55], v[170:173], v[188:191], v[52:55]
	v_mfma_f32_16x16x32_bf16 v[48:51], v[178:181], v[188:191], v[48:51]
	v_mfma_f32_16x16x32_bf16 v[36:39], v[170:173], v[196:199], v[36:39]
	v_mfma_f32_16x16x32_bf16 v[32:35], v[178:181], v[196:199], v[32:35]
	v_mfma_f32_16x16x32_bf16 v[20:23], v[170:173], v[204:207], v[20:23]
	v_mfma_f32_16x16x32_bf16 v[16:19], v[178:181], v[204:207], v[16:19]
	v_mfma_f32_16x16x32_bf16 v[4:7], v[170:173], v[212:215], v[4:7]
	v_mfma_f32_16x16x32_bf16 v[0:3], v[178:181], v[212:215], v[0:3]
	s_barrier
	s_setprio 0
	s_movk_i32 s38, 0x100
	s_andn2_b64 vcc, exec, s[8:9]
	s_mov_b64 s[36:37], -1
	s_mov_b64 s[8:9], 0
	s_cbranch_vccz .LBB0_542
	s_and_b64 vcc, exec, s[14:15]
	s_cbranch_vccz .LBB0_545
	s_barrier

; #define PG8_STAGE(bufoff, gbase, voff) do { _Pragma("unroll") for (int _i = 0; _i < 2; ++_i) \
;         __builtin_amdgcn_global_load_lds((const unsigned*)((const char*)(gbase) + (voff)[_i]), (PG8_LAS unsigned*)(lds + (bufoff) + ldsw + _i * 8192), 16, 0, 0); } while (0)
; #define PG8_LDA(dst, b, h) do { _Pragma("unroll") for (int m = 0; m < 4; ++m) _Pragma("unroll") for (int k = 0; k < 2; ++k) dst[m][k] = *(const PG8_LAS bf16x8*)(lds + PG8_SA(b, h) + aoff + m * 2048 + k * 1024); } while (0)
; #define PG8_LDB(dst, b, h) do { _Pragma("unroll") for (int n = 0; n < 2; ++n) _Pragma("unroll") for (int k = 0; k < 2; ++k) dst[n][k] = *(const PG8_LAS bf16x8*)(lds + PG8_SB(b, h) + boff + n * 2048 + k * 1024); } while (0)
; #define PG8_MMA(ai, bj, At, Bt) do { __builtin_amdgcn_s_setprio(1); _Pragma("unroll") for (int m = 0; m < 4; ++m) _Pragma("unroll") for (int n = 0; n < 2; ++n) _Pragma("unroll") for (int k = 0; k < 2; ++k) \
;         acc[ai][bj][m][n] = __builtin_amdgcn_mfma_f32_16x16x32_bf16(Bt[n][k], At[m][k], acc[ai][bj][m][n], 0, 0, 0); __builtin_amdgcn_s_setprio(0); } while (0)
; #define PG8_WAIT_V(n) asm volatile("s_waitcnt vmcnt(" #n ")" ::: "memory")
; #define PG8_WAIT_L(n) asm volatile("s_waitcnt lgkmcnt(" #n ")" ::: "memory")
; template <class Epi, class Sched, bool ALIGN_EPI = false, bool SP2 = false>
; __device__ __forceinline__ void gemm_phase(PG8_LAS unsigned char* lds, const Gemm g, const Sched& S, const Epi& E) {
;     ...
;             const bool last = (t == nt - 2);
;             const char* a1 = cA + (size_t)(t + 1) * kstep;
;             const char* a2 = last ? nA : cA + (size_t)(t + 2) * kstep; const char* b2 = last ? nB : cB + (size_t)(t + 2) * kstep;
;             const char* a3 = a2 + kstep; const char* b3 = b2 + kstep;
;             if (last && has_next) S.a_ready(nxt);
;             if constexpr (SP2) {
;             PG8_LDB(B0, 0, 0); PG8_LDB(B1, 0, 1); PG8_SCHED; PG8_LDA(At, 0, 0); PG8_STAGE(PG8_SA(1, 1), a1 + hstepA, voffA);
;             PG8_WAIT_V(8); PG8_WAIT_L(0); PG8_BAR; PG8_MMA(0, 0, At, B0); PG8_MMA(0, 1, At, B1); PG8_BAR; PG8_SCHED;
;             PG8_LDA(At, 0, 1); PG8_STAGE(PG8_SB(0, 0), b2, voffB); PG8_STAGE(PG8_SB(0, 1), b2 + hstepB, voffB); PG8_STAGE(PG8_SA(0, 0), a2, voffA);
;             PG8_WAIT_V(8); PG8_WAIT_L(0); PG8_BAR; PG8_MMA(1, 0, At, B0); PG8_MMA(1, 1, At, B1); PG8_BAR; PG8_SCHED;
.LBB0_971:
	ds_read_b128 v[128:131], v191
	ds_read_b128 v[132:135], v191 offset:1024
	ds_read_b128 v[136:139], v191 offset:2048
	ds_read_b128 v[140:143], v191 offset:3072
	ds_read_b128 v[144:147], v192
	ds_read_b128 v[148:151], v192 offset:1024
	ds_read_b128 v[168:171], v192 offset:2048
	ds_read_b128 v[172:175], v192 offset:3072
	s_add_u32 s34, s30, 0xfffc0080
	s_addc_u32 s35, s31, -1
	s_cmp_eq_u32 s74, 12
	s_cselect_b32 s37, s21, s35
	s_cselect_b32 s36, s27, s34
	s_cselect_b32 s35, s19, s73
	s_cselect_b32 s34, s68, s69
	v_lshl_add_u64 v[184:185], s[30:31], 0, v[160:161]
	s_add_i32 m0, s29, 0xc000
	ds_read_b128 v[176:179], v193
	ds_read_b128 v[180:183], v193 offset:1024
	ds_read_b128 v[196:199], v193 offset:2048
	ds_read_b128 v[200:203], v193 offset:3072
	ds_read_b128 v[204:207], v193 offset:4096
	ds_read_b128 v[208:211], v193 offset:5120
	ds_read_b128 v[212:215], v193 offset:6144
	ds_read_b128 v[216:219], v193 offset:7168
	global_load_lds_dwordx4 v[184:185], off
	s_add_i32 m0, s29, 0xe000
	v_lshl_add_u64 v[184:185], s[30:31], 0, v[162:163]
	global_load_lds_dwordx4 v[184:185], off
	s_waitcnt vmcnt(8) lgkmcnt(0)
	s_barrier
	s_setprio 1
	v_mfma_f32_16x16x32_bf16 v[124:127], v[128:131], v[176:179], v[124:127]
	v_mfma_f32_16x16x32_bf16 v[120:123], v[136:139], v[176:179], v[120:123]
	v_mfma_f32_16x16x32_bf16 v[108:111], v[128:131], v[196:199], v[108:111]
	v_mfma_f32_16x16x32_bf16 v[104:107], v[136:139], v[196:199], v[104:107]
	v_mfma_f32_16x16x32_bf16 v[92:95], v[128:131], v[204:207], v[92:95]
	v_mfma_f32_16x16x32_bf16 v[88:91], v[136:139], v[204:207], v[88:91]
	v_mfma_f32_16x16x32_bf16 v[76:79], v[128:131], v[212:215], v[76:79]
	v_mfma_f32_16x16x32_bf16 v[72:75], v[136:139], v[212:215], v[72:75]
	v_mfma_f32_16x16x32_bf16 v[124:127], v[132:135], v[180:183], v[124:127]
	v_mfma_f32_16x16x32_bf16 v[120:123], v[140:143], v[180:183], v[120:123]
	v_mfma_f32_16x16x32_bf16 v[108:111], v[132:135], v[200:203], v[108:111]
	v_mfma_f32_16x16x32_bf16 v[104:107], v[140:143], v[200:203], v[104:107]
	v_mfma_f32_16x16x32_bf16 v[92:95], v[132:135], v[208:211], v[92:95]
	v_mfma_f32_16x16x32_bf16 v[88:91], v[140:143], v[208:211], v[88:91]
	v_mfma_f32_16x16x32_bf16 v[76:79], v[132:135], v[216:219], v[76:79]
	v_mfma_f32_16x16x32_bf16 v[72:75], v[140:143], v[216:219], v[72:75]
	s_setprio 0
	s_setprio 1
	v_mfma_f32_16x16x32_bf16 v[116:119], v[144:147], v[176:179], v[116:119]
	v_mfma_f32_16x16x32_bf16 v[112:115], v[168:171], v[176:179], v[112:115]
	v_mfma_f32_16x16x32_bf16 v[100:103], v[144:147], v[196:199], v[100:103]
	v_mfma_f32_16x16x32_bf16 v[96:99], v[168:171], v[196:199], v[96:99]
	v_mfma_f32_16x16x32_bf16 v[84:87], v[144:147], v[204:207], v[84:87]
	v_mfma_f32_16x16x32_bf16 v[80:83], v[168:171], v[204:207], v[80:83]
	v_mfma_f32_16x16x32_bf16 v[68:71], v[144:147], v[212:215], v[68:71]
	v_mfma_f32_16x16x32_bf16 v[64:67], v[168:171], v[212:215], v[64:67]
	v_mfma_f32_16x16x32_bf16 v[116:119], v[148:151], v[180:183], v[116:119]
	v_mfma_f32_16x16x32_bf16 v[112:115], v[172:175], v[180:183], v[112:115]
	v_mfma_f32_16x16x32_bf16 v[100:103], v[148:151], v[200:203], v[100:103]
	v_mfma_f32_16x16x32_bf16 v[96:99], v[172:175], v[200:203], v[96:99]
	v_mfma_f32_16x16x32_bf16 v[84:87], v[148:151], v[208:211], v[84:87]
	v_mfma_f32_16x16x32_bf16 v[80:83], v[172:175], v[208:211], v[80:83]
	v_mfma_f32_16x16x32_bf16 v[68:71], v[148:151], v[216:219], v[68:71]
	v_mfma_f32_16x16x32_bf16 v[64:67], v[172:175], v[216:219], v[64:67]
	s_barrier
	s_setprio 0
	s_add_i32 s58, s49, s39
	v_lshl_add_u64 v[184:185], s[34:35], 0, v[154:155]
	s_mov_b32 m0, s58
	ds_read_b128 v[176:179], v193 offset:16384
	ds_read_b128 v[180:183], v193 offset:17408
	ds_read_b128 v[196:199], v193 offset:18432
	ds_read_b128 v[200:203], v193 offset:19456
	ds_read_b128 v[204:207], v193 offset:20480
	ds_read_b128 v[208:211], v193 offset:21504
	ds_read_b128 v[212:215], v193 offset:22528
	ds_read_b128 v[216:219], v193 offset:23552
	global_load_lds_dwordx4 v[184:185], off
	s_add_i32 m0, s58, 0x2000
	s_add_u32 s58, s34, 0x40000
	v_lshl_add_u64 v[220:221], s[34:35], 0, v[158:159]
	s_addc_u32 s59, s35, 0
	s_add_i32 s75, s66, s39
	global_load_lds_dwordx4 v[220:221], off
	v_lshl_add_u64 v[222:223], s[58:59], 0, v[154:155]
	s_mov_b32 m0, s75
	v_lshl_add_u64 v[224:225], s[36:37], 0, v[156:157]
	global_load_lds_dwordx4 v[222:223], off
	s_add_i32 m0, s75, 0x2000
	v_lshl_add_u64 v[222:223], s[58:59], 0, v[158:159]
	global_load_lds_dwordx4 v[222:223], off
	s_mov_b32 m0, s29
	v_lshl_add_u64 v[222:223], s[36:37], 0, v[152:153]
	global_load_lds_dwordx4 v[222:223], off
	s_mov_b32 m0, s40
	s_nop 0
	global_load_lds_dwordx4 v[224:225], off
	s_waitcnt vmcnt(8) lgkmcnt(0)
	s_barrier
; #define PG8_STAGE(bufoff, gbase, voff) do { _Pragma("unroll") for (int _i = 0; _i < 2; ++_i) \
;         __builtin_amdgcn_global_load_lds((const unsigned*)((const char*)(gbase) + (voff)[_i]), (PG8_LAS unsigned*)(lds + (bufoff) + ldsw + _i * 8192), 16, 0, 0); } while (0)
; #define PG8_LDA(dst, b, h) do { _Pragma("unroll") for (int m = 0; m < 4; ++m) _Pragma("unroll") for (int k = 0; k < 2; ++k) dst[m][k] = *(const PG8_LAS bf16x8*)(lds + PG8_SA(b, h) + aoff + m * 2048 + k * 1024); } while (0)
; #define PG8_LDB(dst, b, h) do { _Pragma("unroll") for (int n = 0; n < 2; ++n) _Pragma("unroll") for (int k = 0; k < 2; ++k) dst[n][k] = *(const PG8_LAS bf16x8*)(lds + PG8_SB(b, h) + boff + n * 2048 + k * 1024); } while (0)
; #define PG8_MMA(ai, bj, At, Bt) do { __builtin_amdgcn_s_setprio(1); _Pragma("unroll") for (int m = 0; m < 4; ++m) _Pragma("unroll") for (int n = 0; n < 2; ++n) _Pragma("unroll") for (int k = 0; k < 2; ++k) \
;         acc[ai][bj][m][n] = __builtin_amdgcn_mfma_f32_16x16x32_bf16(Bt[n][k], At[m][k], acc[ai][bj][m][n], 0, 0, 0); __builtin_amdgcn_s_setprio(0); } while (0)
; #define PG8_WAIT_V(n) asm volatile("s_waitcnt vmcnt(" #n ")" ::: "memory")
; #define PG8_WAIT_L(n) asm volatile("s_waitcnt lgkmcnt(" #n ")" ::: "memory")
; #define PG8_BAR __builtin_amdgcn_s_barrier()
; #define PG8_SCHED __builtin_amdgcn_sched_barrier(0)
; template <class Epi, class Sched, bool ALIGN_EPI = false, bool SP2 = false>
; __device__ __forceinline__ void gemm_phase(PG8_LAS unsigned char* lds, const Gemm g, const Sched& S, const Epi& E) {
;     ...
;             PG8_WAIT_V(8); PG8_WAIT_L(0); PG8_BAR; PG8_MMA(1, 0, At, B0); PG8_MMA(1, 1, At, B1); PG8_BAR; PG8_SCHED;
;             PG8_LDB(B0, 1, 0); PG8_LDB(B1, 1, 1); PG8_SCHED; PG8_LDA(At, 1, 0); PG8_STAGE(PG8_SA(0, 1), a2 + hstepA, voffA);
;             PG8_WAIT_V(8); PG8_WAIT_L(0); PG8_BAR; PG8_MMA(0, 0, At, B0); PG8_MMA(0, 1, At, B1); PG8_BAR; PG8_SCHED;
	s_setprio 1
	v_mfma_f32_16x16x32_bf16 v[60:63], v[128:131], v[176:179], v[60:63]
	v_mfma_f32_16x16x32_bf16 v[56:59], v[136:139], v[176:179], v[56:59]
	v_mfma_f32_16x16x32_bf16 v[44:47], v[128:131], v[196:199], v[44:47]
	v_mfma_f32_16x16x32_bf16 v[40:43], v[136:139], v[196:199], v[40:43]
	v_mfma_f32_16x16x32_bf16 v[28:31], v[128:131], v[204:207], v[28:31]
	v_mfma_f32_16x16x32_bf16 v[24:27], v[136:139], v[204:207], v[24:27]
	v_mfma_f32_16x16x32_bf16 v[12:15], v[128:131], v[212:215], v[12:15]
	v_mfma_f32_16x16x32_bf16 v[8:11], v[136:139], v[212:215], v[8:11]
	v_mfma_f32_16x16x32_bf16 v[60:63], v[132:135], v[180:183], v[60:63]
	v_mfma_f32_16x16x32_bf16 v[56:59], v[140:143], v[180:183], v[56:59]
	v_mfma_f32_16x16x32_bf16 v[44:47], v[132:135], v[200:203], v[44:47]
	v_mfma_f32_16x16x32_bf16 v[40:43], v[140:143], v[200:203], v[40:43]
	v_mfma_f32_16x16x32_bf16 v[28:31], v[132:135], v[208:211], v[28:31]
	v_mfma_f32_16x16x32_bf16 v[24:27], v[140:143], v[208:211], v[24:27]
	v_mfma_f32_16x16x32_bf16 v[12:15], v[132:135], v[216:219], v[12:15]
	v_mfma_f32_16x16x32_bf16 v[8:11], v[140:143], v[216:219], v[8:11]
	s_setprio 0
	s_setprio 1
	v_mfma_f32_16x16x32_bf16 v[52:55], v[144:147], v[176:179], v[52:55]
	v_mfma_f32_16x16x32_bf16 v[48:51], v[168:171], v[176:179], v[48:51]
	v_mfma_f32_16x16x32_bf16 v[36:39], v[144:147], v[196:199], v[36:39]
	v_mfma_f32_16x16x32_bf16 v[32:35], v[168:171], v[196:199], v[32:35]
	v_mfma_f32_16x16x32_bf16 v[20:23], v[144:147], v[204:207], v[20:23]
	v_mfma_f32_16x16x32_bf16 v[16:19], v[168:171], v[204:207], v[16:19]
	v_mfma_f32_16x16x32_bf16 v[4:7], v[144:147], v[212:215], v[4:7]
	v_mfma_f32_16x16x32_bf16 v[0:3], v[168:171], v[212:215], v[0:3]
	v_mfma_f32_16x16x32_bf16 v[52:55], v[148:151], v[180:183], v[52:55]
	v_mfma_f32_16x16x32_bf16 v[48:51], v[172:175], v[180:183], v[48:51]
	v_mfma_f32_16x16x32_bf16 v[36:39], v[148:151], v[200:203], v[36:39]
	v_mfma_f32_16x16x32_bf16 v[32:35], v[172:175], v[200:203], v[32:35]
	v_mfma_f32_16x16x32_bf16 v[20:23], v[148:151], v[208:211], v[20:23]
	v_mfma_f32_16x16x32_bf16 v[16:19], v[172:175], v[208:211], v[16:19]
	v_mfma_f32_16x16x32_bf16 v[4:7], v[148:151], v[216:219], v[4:7]
	v_mfma_f32_16x16x32_bf16 v[0:3], v[172:175], v[216:219], v[0:3]
	s_barrier
	s_setprio 0
	s_add_i32 s58, 0, 0x18000
	s_add_i32 s59, 0, 0x1c000
	v_add_u32_e32 v140, s58, v189
	v_add_u32_e32 v172, s59, v189
	ds_read_b128 v[128:131], v140
	ds_read_b128 v[132:135], v140 offset:1024
	ds_read_b128 v[136:139], v140 offset:2048
	ds_read_b128 v[140:143], v140 offset:3072
	ds_read_b128 v[144:147], v172
	ds_read_b128 v[148:151], v172 offset:1024
	ds_read_b128 v[168:171], v172 offset:2048
	ds_read_b128 v[172:175], v172 offset:3072
	s_add_u32 s36, s36, 0x40000
	s_addc_u32 s37, s37, 0
	s_mov_b32 m0, s41
	v_lshl_add_u64 v[226:227], s[36:37], 0, v[152:153]
	ds_read_b128 v[176:179], v193 offset:32768
	ds_read_b128 v[180:183], v193 offset:33792
	ds_read_b128 v[196:199], v193 offset:34816
	ds_read_b128 v[200:203], v193 offset:35840
	ds_read_b128 v[204:207], v193 offset:36864
	ds_read_b128 v[208:211], v193 offset:37888
	ds_read_b128 v[212:215], v193 offset:38912
	ds_read_b128 v[216:219], v193 offset:39936
	global_load_lds_dwordx4 v[226:227], off
	s_mov_b32 m0, s42
	v_lshl_add_u64 v[226:227], s[36:37], 0, v[156:157]
	global_load_lds_dwordx4 v[226:227], off
	s_waitcnt vmcnt(8) lgkmcnt(0)
	s_barrier
	s_setprio 1
	v_mfma_f32_16x16x32_bf16 v[124:127], v[128:131], v[176:179], v[124:127]
	v_mfma_f32_16x16x32_bf16 v[120:123], v[136:139], v[176:179], v[120:123]
	v_mfma_f32_16x16x32_bf16 v[108:111], v[128:131], v[196:199], v[108:111]
	v_mfma_f32_16x16x32_bf16 v[104:107], v[136:139], v[196:199], v[104:107]
	v_mfma_f32_16x16x32_bf16 v[92:95], v[128:131], v[204:207], v[92:95]
	v_mfma_f32_16x16x32_bf16 v[88:91], v[136:139], v[204:207], v[88:91]
	v_mfma_f32_16x16x32_bf16 v[76:79], v[128:131], v[212:215], v[76:79]
	v_mfma_f32_16x16x32_bf16 v[72:75], v[136:139], v[212:215], v[72:75]
	v_mfma_f32_16x16x32_bf16 v[124:127], v[132:135], v[180:183], v[124:127]
	v_mfma_f32_16x16x32_bf16 v[120:123], v[140:143], v[180:183], v[120:123]
	v_mfma_f32_16x16x32_bf16 v[108:111], v[132:135], v[200:203], v[108:111]
	v_mfma_f32_16x16x32_bf16 v[104:107], v[140:143], v[200:203], v[104:107]
	v_mfma_f32_16x16x32_bf16 v[92:95], v[132:135], v[208:211], v[92:95]
	v_mfma_f32_16x16x32_bf16 v[88:91], v[140:143], v[208:211], v[88:91]
	v_mfma_f32_16x16x32_bf16 v[76:79], v[132:135], v[216:219], v[76:79]
	v_mfma_f32_16x16x32_bf16 v[72:75], v[140:143], v[216:219], v[72:75]
	s_setprio 0
	s_setprio 1
	v_mfma_f32_16x16x32_bf16 v[116:119], v[144:147], v[176:179], v[116:119]
	v_mfma_f32_16x16x32_bf16 v[112:115], v[168:171], v[176:179], v[112:115]
	v_mfma_f32_16x16x32_bf16 v[100:103], v[144:147], v[196:199], v[100:103]
	v_mfma_f32_16x16x32_bf16 v[96:99], v[168:171], v[196:199], v[96:99]
	v_mfma_f32_16x16x32_bf16 v[84:87], v[144:147], v[204:207], v[84:87]
	v_mfma_f32_16x16x32_bf16 v[80:83], v[168:171], v[204:207], v[80:83]
	v_mfma_f32_16x16x32_bf16 v[68:71], v[144:147], v[212:215], v[68:71]
	v_mfma_f32_16x16x32_bf16 v[64:67], v[168:171], v[212:215], v[64:67]
	v_mfma_f32_16x16x32_bf16 v[116:119], v[148:151], v[180:183], v[116:119]
	v_mfma_f32_16x16x32_bf16 v[112:115], v[172:175], v[180:183], v[112:115]
	v_mfma_f32_16x16x32_bf16 v[100:103], v[148:151], v[200:203], v[100:103]
	v_mfma_f32_16x16x32_bf16 v[96:99], v[172:175], v[200:203], v[96:99]
	v_mfma_f32_16x16x32_bf16 v[84:87], v[148:151], v[208:211], v[84:87]
	v_mfma_f32_16x16x32_bf16 v[80:83], v[172:175], v[208:211], v[80:83]
	v_mfma_f32_16x16x32_bf16 v[68:71], v[148:151], v[216:219], v[68:71]
	v_mfma_f32_16x16x32_bf16 v[64:67], v[172:175], v[216:219], v[64:67]
	s_barrier
; #define PG8_STAGE(bufoff, gbase, voff) do { _Pragma("unroll") for (int _i = 0; _i < 2; ++_i) \
;         __builtin_amdgcn_global_load_lds((const unsigned*)((const char*)(gbase) + (voff)[_i]), (PG8_LAS unsigned*)(lds + (bufoff) + ldsw + _i * 8192), 16, 0, 0); } while (0)
; #define PG8_LDA(dst, b, h) do { _Pragma("unroll") for (int m = 0; m < 4; ++m) _Pragma("unroll") for (int k = 0; k < 2; ++k) dst[m][k] = *(const PG8_LAS bf16x8*)(lds + PG8_SA(b, h) + aoff + m * 2048 + k * 1024); } while (0)
; #define PG8_MMA(ai, bj, At, Bt) do { __builtin_amdgcn_s_setprio(1); _Pragma("unroll") for (int m = 0; m < 4; ++m) _Pragma("unroll") for (int n = 0; n < 2; ++n) _Pragma("unroll") for (int k = 0; k < 2; ++k) \
;         acc[ai][bj][m][n] = __builtin_amdgcn_mfma_f32_16x16x32_bf16(Bt[n][k], At[m][k], acc[ai][bj][m][n], 0, 0, 0); __builtin_amdgcn_s_setprio(0); } while (0)
; #define PG8_WAIT_V(n) asm volatile("s_waitcnt vmcnt(" #n ")" ::: "memory")
; #define PG8_WAIT_L(n) asm volatile("s_waitcnt lgkmcnt(" #n ")" ::: "memory")
; #define PG8_BAR __builtin_amdgcn_s_barrier()
; #define PG8_SCHED __builtin_amdgcn_sched_barrier(0)
; template <class Epi, class Sched, bool ALIGN_EPI = false, bool SP2 = false>
; __device__ __forceinline__ void gemm_phase(PG8_LAS unsigned char* lds, const Gemm g, const Sched& S, const Epi& E) {
;     ...
;             PG8_LDA(At, 1, 1); PG8_STAGE(PG8_SB(1, 0), b3, voffB); PG8_STAGE(PG8_SB(1, 1), b3 + hstepB, voffB); PG8_STAGE(PG8_SA(1, 0), a3, voffA);
;             PG8_WAIT_V(8); PG8_WAIT_L(0); PG8_BAR; PG8_MMA(1, 0, At, B0); PG8_MMA(1, 1, At, B1); PG8_BAR; PG8_SCHED;
	s_setprio 0
	s_add_i32 s36, s58, s39
	v_lshl_add_u64 v[184:185], v[184:185], 0, s[14:15]
	s_mov_b32 m0, s36
	ds_read_b128 v[176:179], v193 offset:49152
	ds_read_b128 v[180:183], v193 offset:50176
	ds_read_b128 v[196:199], v193 offset:51200
	ds_read_b128 v[200:203], v193 offset:52224
	ds_read_b128 v[204:207], v193 offset:53248
	ds_read_b128 v[208:211], v193 offset:54272
	ds_read_b128 v[212:215], v193 offset:55296
	ds_read_b128 v[216:219], v193 offset:56320
	global_load_lds_dwordx4 v[184:185], off
	s_add_i32 m0, s36, 0x2000
	s_add_u32 s34, s34, 0x40080
	v_lshl_add_u64 v[184:185], v[220:221], 0, s[14:15]
	s_addc_u32 s35, s35, 0
	s_add_i32 s36, s59, s39
	global_load_lds_dwordx4 v[184:185], off
	s_mov_b32 m0, s36
	v_lshl_add_u64 v[184:185], s[34:35], 0, v[154:155]
	global_load_lds_dwordx4 v[184:185], off
	s_add_i32 m0, s36, 0x2000
	v_lshl_add_u64 v[184:185], s[34:35], 0, v[158:159]
	global_load_lds_dwordx4 v[184:185], off
	s_mov_b32 m0, s44
	v_lshl_add_u64 v[184:185], v[222:223], 0, s[14:15]
	global_load_lds_dwordx4 v[184:185], off
	s_mov_b32 m0, s45
	v_lshl_add_u64 v[184:185], v[224:225], 0, s[14:15]
	global_load_lds_dwordx4 v[184:185], off
	s_waitcnt vmcnt(8) lgkmcnt(0)
	s_barrier
	s_setprio 1
	v_mfma_f32_16x16x32_bf16 v[60:63], v[128:131], v[176:179], v[60:63]
	v_mfma_f32_16x16x32_bf16 v[56:59], v[136:139], v[176:179], v[56:59]
	v_mfma_f32_16x16x32_bf16 v[44:47], v[128:131], v[196:199], v[44:47]
	v_mfma_f32_16x16x32_bf16 v[40:43], v[136:139], v[196:199], v[40:43]
	v_mfma_f32_16x16x32_bf16 v[28:31], v[128:131], v[204:207], v[28:31]
	v_mfma_f32_16x16x32_bf16 v[24:27], v[136:139], v[204:207], v[24:27]
	v_mfma_f32_16x16x32_bf16 v[12:15], v[128:131], v[212:215], v[12:15]
	v_mfma_f32_16x16x32_bf16 v[8:11], v[136:139], v[212:215], v[8:11]
	v_mfma_f32_16x16x32_bf16 v[60:63], v[132:135], v[180:183], v[60:63]
	v_mfma_f32_16x16x32_bf16 v[56:59], v[140:143], v[180:183], v[56:59]
	v_mfma_f32_16x16x32_bf16 v[44:47], v[132:135], v[200:203], v[44:47]
	v_mfma_f32_16x16x32_bf16 v[40:43], v[140:143], v[200:203], v[40:43]
	v_mfma_f32_16x16x32_bf16 v[28:31], v[132:135], v[208:211], v[28:31]
	v_mfma_f32_16x16x32_bf16 v[24:27], v[140:143], v[208:211], v[24:27]
	v_mfma_f32_16x16x32_bf16 v[12:15], v[132:135], v[216:219], v[12:15]
	v_mfma_f32_16x16x32_bf16 v[8:11], v[140:143], v[216:219], v[8:11]
	s_setprio 0
	s_setprio 1
	v_mfma_f32_16x16x32_bf16 v[52:55], v[144:147], v[176:179], v[52:55]
	v_mfma_f32_16x16x32_bf16 v[48:51], v[168:171], v[176:179], v[48:51]
	v_mfma_f32_16x16x32_bf16 v[36:39], v[144:147], v[196:199], v[36:39]
	v_mfma_f32_16x16x32_bf16 v[32:35], v[168:171], v[196:199], v[32:35]
	v_mfma_f32_16x16x32_bf16 v[20:23], v[144:147], v[204:207], v[20:23]
	v_mfma_f32_16x16x32_bf16 v[16:19], v[168:171], v[204:207], v[16:19]
	v_mfma_f32_16x16x32_bf16 v[4:7], v[144:147], v[212:215], v[4:7]
	v_mfma_f32_16x16x32_bf16 v[0:3], v[168:171], v[212:215], v[0:3]
	v_mfma_f32_16x16x32_bf16 v[52:55], v[148:151], v[180:183], v[52:55]
	v_mfma_f32_16x16x32_bf16 v[48:51], v[172:175], v[180:183], v[48:51]
	v_mfma_f32_16x16x32_bf16 v[36:39], v[148:151], v[200:203], v[36:39]
	v_mfma_f32_16x16x32_bf16 v[32:35], v[172:175], v[200:203], v[32:35]
	v_mfma_f32_16x16x32_bf16 v[20:23], v[148:151], v[208:211], v[20:23]
	v_mfma_f32_16x16x32_bf16 v[16:19], v[172:175], v[208:211], v[16:19]
	v_mfma_f32_16x16x32_bf16 v[4:7], v[148:151], v[216:219], v[4:7]
	v_mfma_f32_16x16x32_bf16 v[0:3], v[172:175], v[216:219], v[0:3]
	s_barrier
	s_setprio 0
	s_add_i32 s74, s74, 2
	s_add_u32 s30, s30, 0x100
	s_addc_u32 s31, s31, 0
	s_add_u32 s69, s69, 0x100
	s_addc_u32 s73, s73, 0
	s_cmp_gt_u32 s74, 13
	s_cbranch_scc0 .LBB0_971
	s_and_b64 vcc, exec, s[16:17]
	s_cbranch_vccz .LBB0_974
	s_barrier

; #define PG8_STAGE(bufoff, gbase, voff) do { _Pragma("unroll") for (int _i = 0; _i < 2; ++_i) \
;         __builtin_amdgcn_global_load_lds((const unsigned*)((const char*)(gbase) + (voff)[_i]), (PG8_LAS unsigned*)(lds + (bufoff) + ldsw + _i * 8192), 16, 0, 0); } while (0)
; #define PG8_LDA(dst, b, h) do { _Pragma("unroll") for (int m = 0; m < 4; ++m) _Pragma("unroll") for (int k = 0; k < 2; ++k) dst[m][k] = *(const PG8_LAS bf16x8*)(lds + PG8_SA(b, h) + aoff + m * 2048 + k * 1024); } while (0)
; #define PG8_LDB(dst, b, h) do { _Pragma("unroll") for (int n = 0; n < 2; ++n) _Pragma("unroll") for (int k = 0; k < 2; ++k) dst[n][k] = *(const PG8_LAS bf16x8*)(lds + PG8_SB(b, h) + boff + n * 2048 + k * 1024); } while (0)
; #define PG8_MMA(ai, bj, At, Bt) do { __builtin_amdgcn_s_setprio(1); _Pragma("unroll") for (int m = 0; m < 4; ++m) _Pragma("unroll") for (int n = 0; n < 2; ++n) _Pragma("unroll") for (int k = 0; k < 2; ++k) \
;         acc[ai][bj][m][n] = __builtin_amdgcn_mfma_f32_16x16x32_bf16(Bt[n][k], At[m][k], acc[ai][bj][m][n], 0, 0, 0); __builtin_amdgcn_s_setprio(0); } while (0)
; #define PG8_WAIT_V(n) asm volatile("s_waitcnt vmcnt(" #n ")" ::: "memory")
; #define PG8_WAIT_L(n) asm volatile("s_waitcnt lgkmcnt(" #n ")" ::: "memory")
; template <class Epi, class Sched, bool ALIGN_EPI = false, bool SP2 = false>
; __device__ __forceinline__ void gemm_phase(PG8_LAS unsigned char* lds, const Gemm g, const Sched& S, const Epi& E) {
;     ...
;             const bool last = (t == nt - 2);
;             const char* a1 = cA + (size_t)(t + 1) * kstep;
;             const char* a2 = last ? nA : cA + (size_t)(t + 2) * kstep; const char* b2 = last ? nB : cB + (size_t)(t + 2) * kstep;
;             const char* a3 = a2 + kstep; const char* b3 = b2 + kstep;
;             if (last && has_next) S.a_ready(nxt);
;             if constexpr (SP2) {
;             PG8_LDB(B0, 0, 0); PG8_LDB(B1, 0, 1); PG8_SCHED; PG8_LDA(At, 0, 0); PG8_STAGE(PG8_SA(1, 1), a1 + hstepA, voffA);
;             PG8_WAIT_V(8); PG8_WAIT_L(0); PG8_BAR; PG8_MMA(0, 0, At, B0); PG8_MMA(0, 1, At, B1); PG8_BAR; PG8_SCHED;
;             PG8_LDA(At, 0, 1); PG8_STAGE(PG8_SB(0, 0), b2, voffB); PG8_STAGE(PG8_SB(0, 1), b2 + hstepB, voffB); PG8_STAGE(PG8_SA(0, 0), a2, voffA);
;             PG8_WAIT_V(8); PG8_WAIT_L(0); PG8_BAR; PG8_MMA(1, 0, At, B0); PG8_MMA(1, 1, At, B1); PG8_BAR; PG8_SCHED;
.LBB0_1055:
	ds_read_b128 v[144:147], v153
	ds_read_b128 v[158:161], v153 offset:1024
	ds_read_b128 v[162:165], v153 offset:2048
	ds_read_b128 v[166:169], v153 offset:3072
	ds_read_b128 v[170:173], v154
	ds_read_b128 v[174:177], v154 offset:1024
	ds_read_b128 v[178:181], v154 offset:2048
	ds_read_b128 v[182:185], v154 offset:3072
	s_add_u32 s28, s26, 0xfffc0080
	s_addc_u32 s29, s27, -1
	s_cmp_eq_u32 s69, 12
	s_cselect_b32 s31, s19, s29
	s_cselect_b32 s30, s49, s28
	s_cselect_b32 s29, s17, s68
	s_cselect_b32 s28, s66, s67
	v_lshl_add_u64 v[148:149], s[26:27], 0, v[136:137]
	s_add_i32 m0, s25, 0xc000
	ds_read_b128 v[188:191], v155
	ds_read_b128 v[192:195], v155 offset:1024
	ds_read_b128 v[196:199], v155 offset:2048
	ds_read_b128 v[200:203], v155 offset:3072
	ds_read_b128 v[204:207], v155 offset:4096
	ds_read_b128 v[208:211], v155 offset:5120
	ds_read_b128 v[212:215], v155 offset:6144
	ds_read_b128 v[216:219], v155 offset:7168
	global_load_lds_dwordx4 v[148:149], off
	s_add_i32 m0, s25, 0xe000
	v_lshl_add_u64 v[148:149], s[26:27], 0, v[138:139]
	global_load_lds_dwordx4 v[148:149], off
	s_waitcnt vmcnt(8) lgkmcnt(0)
	s_barrier
	s_setprio 1
	v_mfma_f32_16x16x32_bf16 v[116:119], v[144:147], v[188:191], v[116:119]
	v_mfma_f32_16x16x32_bf16 v[112:115], v[162:165], v[188:191], v[112:115]
	v_mfma_f32_16x16x32_bf16 v[108:111], v[144:147], v[196:199], v[108:111]
	v_mfma_f32_16x16x32_bf16 v[100:103], v[162:165], v[196:199], v[100:103]
	v_mfma_f32_16x16x32_bf16 v[92:95], v[144:147], v[204:207], v[92:95]
	v_mfma_f32_16x16x32_bf16 v[84:87], v[162:165], v[204:207], v[84:87]
	v_mfma_f32_16x16x32_bf16 v[76:79], v[144:147], v[212:215], v[76:79]
	v_mfma_f32_16x16x32_bf16 v[68:71], v[162:165], v[212:215], v[68:71]
	v_mfma_f32_16x16x32_bf16 v[116:119], v[158:161], v[192:195], v[116:119]
	v_mfma_f32_16x16x32_bf16 v[112:115], v[166:169], v[192:195], v[112:115]
	v_mfma_f32_16x16x32_bf16 v[108:111], v[158:161], v[200:203], v[108:111]
	v_mfma_f32_16x16x32_bf16 v[100:103], v[166:169], v[200:203], v[100:103]
	v_mfma_f32_16x16x32_bf16 v[92:95], v[158:161], v[208:211], v[92:95]
	v_mfma_f32_16x16x32_bf16 v[84:87], v[166:169], v[208:211], v[84:87]
	v_mfma_f32_16x16x32_bf16 v[76:79], v[158:161], v[216:219], v[76:79]
	v_mfma_f32_16x16x32_bf16 v[68:71], v[166:169], v[216:219], v[68:71]
	s_setprio 0
	s_setprio 1
	v_mfma_f32_16x16x32_bf16 v[124:127], v[170:173], v[188:191], v[124:127]
	v_mfma_f32_16x16x32_bf16 v[120:123], v[178:181], v[188:191], v[120:123]
	v_mfma_f32_16x16x32_bf16 v[104:107], v[170:173], v[196:199], v[104:107]
	v_mfma_f32_16x16x32_bf16 v[96:99], v[178:181], v[196:199], v[96:99]
	v_mfma_f32_16x16x32_bf16 v[88:91], v[170:173], v[204:207], v[88:91]
	v_mfma_f32_16x16x32_bf16 v[80:83], v[178:181], v[204:207], v[80:83]
	v_mfma_f32_16x16x32_bf16 v[72:75], v[170:173], v[212:215], v[72:75]
	v_mfma_f32_16x16x32_bf16 v[64:67], v[178:181], v[212:215], v[64:67]
	v_mfma_f32_16x16x32_bf16 v[124:127], v[174:177], v[192:195], v[124:127]
	v_mfma_f32_16x16x32_bf16 v[120:123], v[182:185], v[192:195], v[120:123]
	v_mfma_f32_16x16x32_bf16 v[104:107], v[174:177], v[200:203], v[104:107]
	v_mfma_f32_16x16x32_bf16 v[96:99], v[182:185], v[200:203], v[96:99]
	v_mfma_f32_16x16x32_bf16 v[88:91], v[174:177], v[208:211], v[88:91]
	v_mfma_f32_16x16x32_bf16 v[80:83], v[182:185], v[208:211], v[80:83]
	v_mfma_f32_16x16x32_bf16 v[72:75], v[174:177], v[216:219], v[72:75]
	v_mfma_f32_16x16x32_bf16 v[64:67], v[182:185], v[216:219], v[64:67]
	s_barrier
	s_setprio 0
	s_add_i32 s58, s45, s35
	v_lshl_add_u64 v[148:149], s[28:29], 0, v[132:133]
	s_mov_b32 m0, s58
	ds_read_b128 v[188:191], v155 offset:16384
	ds_read_b128 v[192:195], v155 offset:17408
	ds_read_b128 v[196:199], v155 offset:18432
	ds_read_b128 v[200:203], v155 offset:19456
	ds_read_b128 v[204:207], v155 offset:20480
	ds_read_b128 v[208:211], v155 offset:21504
	ds_read_b128 v[212:215], v155 offset:22528
	ds_read_b128 v[216:219], v155 offset:23552
	global_load_lds_dwordx4 v[148:149], off
	s_add_i32 m0, s58, 0x2000
	s_add_u32 s58, s28, 0x40000
	v_lshl_add_u64 v[220:221], s[28:29], 0, v[128:129]
	s_addc_u32 s59, s29, 0
	s_add_i32 s73, s46, s35
	global_load_lds_dwordx4 v[220:221], off
	v_lshl_add_u64 v[222:223], s[58:59], 0, v[132:133]
	s_mov_b32 m0, s73
	v_lshl_add_u64 v[224:225], s[30:31], 0, v[130:131]
	global_load_lds_dwordx4 v[222:223], off
	s_add_i32 m0, s73, 0x2000
	v_lshl_add_u64 v[222:223], s[58:59], 0, v[128:129]
	global_load_lds_dwordx4 v[222:223], off
	s_mov_b32 m0, s25
	v_lshl_add_u64 v[222:223], s[30:31], 0, v[134:135]
	global_load_lds_dwordx4 v[222:223], off
	s_mov_b32 m0, s38
	s_nop 0
	global_load_lds_dwordx4 v[224:225], off
	s_waitcnt vmcnt(8) lgkmcnt(0)
	s_barrier
; #define PG8_STAGE(bufoff, gbase, voff) do { _Pragma("unroll") for (int _i = 0; _i < 2; ++_i) \
;         __builtin_amdgcn_global_load_lds((const unsigned*)((const char*)(gbase) + (voff)[_i]), (PG8_LAS unsigned*)(lds + (bufoff) + ldsw + _i * 8192), 16, 0, 0); } while (0)
; #define PG8_LDA(dst, b, h) do { _Pragma("unroll") for (int m = 0; m < 4; ++m) _Pragma("unroll") for (int k = 0; k < 2; ++k) dst[m][k] = *(const PG8_LAS bf16x8*)(lds + PG8_SA(b, h) + aoff + m * 2048 + k * 1024); } while (0)
; #define PG8_LDB(dst, b, h) do { _Pragma("unroll") for (int n = 0; n < 2; ++n) _Pragma("unroll") for (int k = 0; k < 2; ++k) dst[n][k] = *(const PG8_LAS bf16x8*)(lds + PG8_SB(b, h) + boff + n * 2048 + k * 1024); } while (0)
; #define PG8_MMA(ai, bj, At, Bt) do { __builtin_amdgcn_s_setprio(1); _Pragma("unroll") for (int m = 0; m < 4; ++m) _Pragma("unroll") for (int n = 0; n < 2; ++n) _Pragma("unroll") for (int k = 0; k < 2; ++k) \
;         acc[ai][bj][m][n] = __builtin_amdgcn_mfma_f32_16x16x32_bf16(Bt[n][k], At[m][k], acc[ai][bj][m][n], 0, 0, 0); __builtin_amdgcn_s_setprio(0); } while (0)
; #define PG8_WAIT_V(n) asm volatile("s_waitcnt vmcnt(" #n ")" ::: "memory")
; #define PG8_WAIT_L(n) asm volatile("s_waitcnt lgkmcnt(" #n ")" ::: "memory")
; #define PG8_BAR __builtin_amdgcn_s_barrier()
; #define PG8_SCHED __builtin_amdgcn_sched_barrier(0)
; template <class Epi, class Sched, bool ALIGN_EPI = false, bool SP2 = false>
; __device__ __forceinline__ void gemm_phase(PG8_LAS unsigned char* lds, const Gemm g, const Sched& S, const Epi& E) {
;     ...
;             PG8_WAIT_V(8); PG8_WAIT_L(0); PG8_BAR; PG8_MMA(1, 0, At, B0); PG8_MMA(1, 1, At, B1); PG8_BAR; PG8_SCHED;
;             PG8_LDB(B0, 1, 0); PG8_LDB(B1, 1, 1); PG8_SCHED; PG8_LDA(At, 1, 0); PG8_STAGE(PG8_SA(0, 1), a2 + hstepA, voffA);
;             PG8_WAIT_V(8); PG8_WAIT_L(0); PG8_BAR; PG8_MMA(0, 0, At, B0); PG8_MMA(0, 1, At, B1); PG8_BAR; PG8_SCHED;
	s_setprio 1
	v_mfma_f32_16x16x32_bf16 v[60:63], v[144:147], v[188:191], v[60:63]
	v_mfma_f32_16x16x32_bf16 v[52:55], v[162:165], v[188:191], v[52:55]
	v_mfma_f32_16x16x32_bf16 v[44:47], v[144:147], v[196:199], v[44:47]
	v_mfma_f32_16x16x32_bf16 v[36:39], v[162:165], v[196:199], v[36:39]
	v_mfma_f32_16x16x32_bf16 v[28:31], v[144:147], v[204:207], v[28:31]
	v_mfma_f32_16x16x32_bf16 v[20:23], v[162:165], v[204:207], v[20:23]
	v_mfma_f32_16x16x32_bf16 v[12:15], v[144:147], v[212:215], v[12:15]
	v_mfma_f32_16x16x32_bf16 v[4:7], v[162:165], v[212:215], v[4:7]
	v_mfma_f32_16x16x32_bf16 v[60:63], v[158:161], v[192:195], v[60:63]
	v_mfma_f32_16x16x32_bf16 v[52:55], v[166:169], v[192:195], v[52:55]
	v_mfma_f32_16x16x32_bf16 v[44:47], v[158:161], v[200:203], v[44:47]
	v_mfma_f32_16x16x32_bf16 v[36:39], v[166:169], v[200:203], v[36:39]
	v_mfma_f32_16x16x32_bf16 v[28:31], v[158:161], v[208:211], v[28:31]
	v_mfma_f32_16x16x32_bf16 v[20:23], v[166:169], v[208:211], v[20:23]
	v_mfma_f32_16x16x32_bf16 v[12:15], v[158:161], v[216:219], v[12:15]
	v_mfma_f32_16x16x32_bf16 v[4:7], v[166:169], v[216:219], v[4:7]
	s_setprio 0
	s_setprio 1
	v_mfma_f32_16x16x32_bf16 v[56:59], v[170:173], v[188:191], v[56:59]
	v_mfma_f32_16x16x32_bf16 v[48:51], v[178:181], v[188:191], v[48:51]
	v_mfma_f32_16x16x32_bf16 v[40:43], v[170:173], v[196:199], v[40:43]
	v_mfma_f32_16x16x32_bf16 v[32:35], v[178:181], v[196:199], v[32:35]
	v_mfma_f32_16x16x32_bf16 v[24:27], v[170:173], v[204:207], v[24:27]
	v_mfma_f32_16x16x32_bf16 v[16:19], v[178:181], v[204:207], v[16:19]
	v_mfma_f32_16x16x32_bf16 v[8:11], v[170:173], v[212:215], v[8:11]
	v_mfma_f32_16x16x32_bf16 v[0:3], v[178:181], v[212:215], v[0:3]
	v_mfma_f32_16x16x32_bf16 v[56:59], v[174:177], v[192:195], v[56:59]
	v_mfma_f32_16x16x32_bf16 v[48:51], v[182:185], v[192:195], v[48:51]
	v_mfma_f32_16x16x32_bf16 v[40:43], v[174:177], v[200:203], v[40:43]
	v_mfma_f32_16x16x32_bf16 v[32:35], v[182:185], v[200:203], v[32:35]
	v_mfma_f32_16x16x32_bf16 v[24:27], v[174:177], v[208:211], v[24:27]
	v_mfma_f32_16x16x32_bf16 v[16:19], v[182:185], v[208:211], v[16:19]
	v_mfma_f32_16x16x32_bf16 v[8:11], v[174:177], v[216:219], v[8:11]
	v_mfma_f32_16x16x32_bf16 v[0:3], v[182:185], v[216:219], v[0:3]
	s_barrier
	s_setprio 0
	s_add_i32 s58, 0, 0x18000
	v_add_u32_e32 v157, s58, v151
	s_add_i32 s59, 0, 0x1c000
	ds_read_b128 v[144:147], v157
	ds_read_b128 v[158:161], v157 offset:1024
	ds_read_b128 v[162:165], v157 offset:2048
	ds_read_b128 v[166:169], v157 offset:3072
	v_add_u32_e32 v157, s59, v151
	ds_read_b128 v[170:173], v157
	ds_read_b128 v[174:177], v157 offset:1024
	ds_read_b128 v[178:181], v157 offset:2048
	ds_read_b128 v[182:185], v157 offset:3072
	s_add_u32 s30, s30, 0x40000
	s_addc_u32 s31, s31, 0
	s_mov_b32 m0, s39
	v_lshl_add_u64 v[226:227], s[30:31], 0, v[134:135]
	ds_read_b128 v[188:191], v155 offset:32768
	ds_read_b128 v[192:195], v155 offset:33792
	ds_read_b128 v[196:199], v155 offset:34816
	ds_read_b128 v[200:203], v155 offset:35840
	ds_read_b128 v[204:207], v155 offset:36864
	ds_read_b128 v[208:211], v155 offset:37888
	ds_read_b128 v[212:215], v155 offset:38912
	ds_read_b128 v[216:219], v155 offset:39936
	global_load_lds_dwordx4 v[226:227], off
	s_mov_b32 m0, s40
	v_lshl_add_u64 v[226:227], s[30:31], 0, v[130:131]
	global_load_lds_dwordx4 v[226:227], off
	s_waitcnt vmcnt(8) lgkmcnt(0)
	s_barrier
	s_setprio 1
	v_mfma_f32_16x16x32_bf16 v[116:119], v[144:147], v[188:191], v[116:119]
	v_mfma_f32_16x16x32_bf16 v[112:115], v[162:165], v[188:191], v[112:115]
	v_mfma_f32_16x16x32_bf16 v[108:111], v[144:147], v[196:199], v[108:111]
	v_mfma_f32_16x16x32_bf16 v[100:103], v[162:165], v[196:199], v[100:103]
	v_mfma_f32_16x16x32_bf16 v[92:95], v[144:147], v[204:207], v[92:95]
	v_mfma_f32_16x16x32_bf16 v[84:87], v[162:165], v[204:207], v[84:87]
	v_mfma_f32_16x16x32_bf16 v[76:79], v[144:147], v[212:215], v[76:79]
	v_mfma_f32_16x16x32_bf16 v[68:71], v[162:165], v[212:215], v[68:71]
	v_mfma_f32_16x16x32_bf16 v[116:119], v[158:161], v[192:195], v[116:119]
	v_mfma_f32_16x16x32_bf16 v[112:115], v[166:169], v[192:195], v[112:115]
	v_mfma_f32_16x16x32_bf16 v[108:111], v[158:161], v[200:203], v[108:111]
	v_mfma_f32_16x16x32_bf16 v[100:103], v[166:169], v[200:203], v[100:103]
	v_mfma_f32_16x16x32_bf16 v[92:95], v[158:161], v[208:211], v[92:95]
	v_mfma_f32_16x16x32_bf16 v[84:87], v[166:169], v[208:211], v[84:87]
	v_mfma_f32_16x16x32_bf16 v[76:79], v[158:161], v[216:219], v[76:79]
	v_mfma_f32_16x16x32_bf16 v[68:71], v[166:169], v[216:219], v[68:71]
	s_setprio 0
	s_setprio 1
	v_mfma_f32_16x16x32_bf16 v[124:127], v[170:173], v[188:191], v[124:127]
	v_mfma_f32_16x16x32_bf16 v[120:123], v[178:181], v[188:191], v[120:123]
	v_mfma_f32_16x16x32_bf16 v[104:107], v[170:173], v[196:199], v[104:107]
	v_mfma_f32_16x16x32_bf16 v[96:99], v[178:181], v[196:199], v[96:99]
	v_mfma_f32_16x16x32_bf16 v[88:91], v[170:173], v[204:207], v[88:91]
	v_mfma_f32_16x16x32_bf16 v[80:83], v[178:181], v[204:207], v[80:83]
	v_mfma_f32_16x16x32_bf16 v[72:75], v[170:173], v[212:215], v[72:75]
	v_mfma_f32_16x16x32_bf16 v[64:67], v[178:181], v[212:215], v[64:67]
	v_mfma_f32_16x16x32_bf16 v[124:127], v[174:177], v[192:195], v[124:127]
	v_mfma_f32_16x16x32_bf16 v[120:123], v[182:185], v[192:195], v[120:123]
	v_mfma_f32_16x16x32_bf16 v[104:107], v[174:177], v[200:203], v[104:107]
	v_mfma_f32_16x16x32_bf16 v[96:99], v[182:185], v[200:203], v[96:99]
	v_mfma_f32_16x16x32_bf16 v[88:91], v[174:177], v[208:211], v[88:91]
	v_mfma_f32_16x16x32_bf16 v[80:83], v[182:185], v[208:211], v[80:83]
	v_mfma_f32_16x16x32_bf16 v[72:75], v[174:177], v[216:219], v[72:75]
	v_mfma_f32_16x16x32_bf16 v[64:67], v[182:185], v[216:219], v[64:67]
	s_barrier
; #define PG8_STAGE(bufoff, gbase, voff) do { _Pragma("unroll") for (int _i = 0; _i < 2; ++_i) \
;         __builtin_amdgcn_global_load_lds((const unsigned*)((const char*)(gbase) + (voff)[_i]), (PG8_LAS unsigned*)(lds + (bufoff) + ldsw + _i * 8192), 16, 0, 0); } while (0)
; #define PG8_LDA(dst, b, h) do { _Pragma("unroll") for (int m = 0; m < 4; ++m) _Pragma("unroll") for (int k = 0; k < 2; ++k) dst[m][k] = *(const PG8_LAS bf16x8*)(lds + PG8_SA(b, h) + aoff + m * 2048 + k * 1024); } while (0)
; #define PG8_MMA(ai, bj, At, Bt) do { __builtin_amdgcn_s_setprio(1); _Pragma("unroll") for (int m = 0; m < 4; ++m) _Pragma("unroll") for (int n = 0; n < 2; ++n) _Pragma("unroll") for (int k = 0; k < 2; ++k) \
;         acc[ai][bj][m][n] = __builtin_amdgcn_mfma_f32_16x16x32_bf16(Bt[n][k], At[m][k], acc[ai][bj][m][n], 0, 0, 0); __builtin_amdgcn_s_setprio(0); } while (0)
; #define PG8_WAIT_V(n) asm volatile("s_waitcnt vmcnt(" #n ")" ::: "memory")
; #define PG8_WAIT_L(n) asm volatile("s_waitcnt lgkmcnt(" #n ")" ::: "memory")
; #define PG8_BAR __builtin_amdgcn_s_barrier()
; #define PG8_SCHED __builtin_amdgcn_sched_barrier(0)
; template <class Epi, class Sched, bool ALIGN_EPI = false, bool SP2 = false>
; __device__ __forceinline__ void gemm_phase(PG8_LAS unsigned char* lds, const Gemm g, const Sched& S, const Epi& E) {
;     ...
;             PG8_LDA(At, 1, 1); PG8_STAGE(PG8_SB(1, 0), b3, voffB); PG8_STAGE(PG8_SB(1, 1), b3 + hstepB, voffB); PG8_STAGE(PG8_SA(1, 0), a3, voffA);
;             PG8_WAIT_V(8); PG8_WAIT_L(0); PG8_BAR; PG8_MMA(1, 0, At, B0); PG8_MMA(1, 1, At, B1); PG8_BAR; PG8_SCHED;
	s_setprio 0
	s_add_i32 s30, s58, s35
	v_lshl_add_u64 v[148:149], v[148:149], 0, s[12:13]
	s_mov_b32 m0, s30
	ds_read_b128 v[188:191], v155 offset:49152
	ds_read_b128 v[192:195], v155 offset:50176
	ds_read_b128 v[196:199], v155 offset:51200
	ds_read_b128 v[200:203], v155 offset:52224
	ds_read_b128 v[204:207], v155 offset:53248
	ds_read_b128 v[208:211], v155 offset:54272
	ds_read_b128 v[212:215], v155 offset:55296
	ds_read_b128 v[216:219], v155 offset:56320
	global_load_lds_dwordx4 v[148:149], off
	s_add_i32 m0, s30, 0x2000
	s_add_u32 s28, s28, 0x40080
	v_lshl_add_u64 v[148:149], v[220:221], 0, s[12:13]
	s_addc_u32 s29, s29, 0
	s_add_i32 s30, s59, s35
	global_load_lds_dwordx4 v[148:149], off
	s_mov_b32 m0, s30
	v_lshl_add_u64 v[148:149], s[28:29], 0, v[132:133]
	global_load_lds_dwordx4 v[148:149], off
	s_add_i32 m0, s30, 0x2000
	v_lshl_add_u64 v[148:149], s[28:29], 0, v[128:129]
	global_load_lds_dwordx4 v[148:149], off
	s_mov_b32 m0, s42
	v_lshl_add_u64 v[148:149], v[222:223], 0, s[12:13]
	global_load_lds_dwordx4 v[148:149], off
	s_mov_b32 m0, s43
	v_lshl_add_u64 v[148:149], v[224:225], 0, s[12:13]
	global_load_lds_dwordx4 v[148:149], off
	s_waitcnt vmcnt(8) lgkmcnt(0)
	s_barrier
	s_setprio 1
	v_mfma_f32_16x16x32_bf16 v[60:63], v[144:147], v[188:191], v[60:63]
	v_mfma_f32_16x16x32_bf16 v[52:55], v[162:165], v[188:191], v[52:55]
	v_mfma_f32_16x16x32_bf16 v[44:47], v[144:147], v[196:199], v[44:47]
	v_mfma_f32_16x16x32_bf16 v[36:39], v[162:165], v[196:199], v[36:39]
	v_mfma_f32_16x16x32_bf16 v[28:31], v[144:147], v[204:207], v[28:31]
	v_mfma_f32_16x16x32_bf16 v[20:23], v[162:165], v[204:207], v[20:23]
	v_mfma_f32_16x16x32_bf16 v[12:15], v[144:147], v[212:215], v[12:15]
	v_mfma_f32_16x16x32_bf16 v[4:7], v[162:165], v[212:215], v[4:7]
	v_mfma_f32_16x16x32_bf16 v[60:63], v[158:161], v[192:195], v[60:63]
	v_mfma_f32_16x16x32_bf16 v[52:55], v[166:169], v[192:195], v[52:55]
	v_mfma_f32_16x16x32_bf16 v[44:47], v[158:161], v[200:203], v[44:47]
	v_mfma_f32_16x16x32_bf16 v[36:39], v[166:169], v[200:203], v[36:39]
	v_mfma_f32_16x16x32_bf16 v[28:31], v[158:161], v[208:211], v[28:31]
	v_mfma_f32_16x16x32_bf16 v[20:23], v[166:169], v[208:211], v[20:23]
	v_mfma_f32_16x16x32_bf16 v[12:15], v[158:161], v[216:219], v[12:15]
	v_mfma_f32_16x16x32_bf16 v[4:7], v[166:169], v[216:219], v[4:7]
	s_setprio 0
	s_setprio 1
	v_mfma_f32_16x16x32_bf16 v[56:59], v[170:173], v[188:191], v[56:59]
	v_mfma_f32_16x16x32_bf16 v[48:51], v[178:181], v[188:191], v[48:51]
	v_mfma_f32_16x16x32_bf16 v[40:43], v[170:173], v[196:199], v[40:43]
	v_mfma_f32_16x16x32_bf16 v[32:35], v[178:181], v[196:199], v[32:35]
	v_mfma_f32_16x16x32_bf16 v[24:27], v[170:173], v[204:207], v[24:27]
	v_mfma_f32_16x16x32_bf16 v[16:19], v[178:181], v[204:207], v[16:19]
	v_mfma_f32_16x16x32_bf16 v[8:11], v[170:173], v[212:215], v[8:11]
	v_mfma_f32_16x16x32_bf16 v[0:3], v[178:181], v[212:215], v[0:3]
	v_mfma_f32_16x16x32_bf16 v[56:59], v[174:177], v[192:195], v[56:59]
	v_mfma_f32_16x16x32_bf16 v[48:51], v[182:185], v[192:195], v[48:51]
	v_mfma_f32_16x16x32_bf16 v[40:43], v[174:177], v[200:203], v[40:43]
	v_mfma_f32_16x16x32_bf16 v[32:35], v[182:185], v[200:203], v[32:35]
	v_mfma_f32_16x16x32_bf16 v[24:27], v[174:177], v[208:211], v[24:27]
	v_mfma_f32_16x16x32_bf16 v[16:19], v[182:185], v[208:211], v[16:19]
	v_mfma_f32_16x16x32_bf16 v[8:11], v[174:177], v[216:219], v[8:11]
	v_mfma_f32_16x16x32_bf16 v[0:3], v[182:185], v[216:219], v[0:3]
	s_barrier
	s_setprio 0
	s_add_i32 s69, s69, 2
	s_add_u32 s26, s26, 0x100
	s_addc_u32 s27, s27, 0
	s_add_u32 s67, s67, 0x100
	s_addc_u32 s68, s68, 0
	s_cmp_gt_u32 s69, 13
	s_cbranch_scc0 .LBB0_1055
	s_and_b64 vcc, exec, s[14:15]
	s_cbranch_vccz .LBB0_1058
	s_barrier

; #define PG8_STAGE(bufoff, gbase, voff) do { _Pragma("unroll") for (int _i = 0; _i < 2; ++_i) \
;         __builtin_amdgcn_global_load_lds((const unsigned*)((const char*)(gbase) + (voff)[_i]), (PG8_LAS unsigned*)(lds + (bufoff) + ldsw + _i * 8192), 16, 0, 0); } while (0)
; #define PG8_LDA(dst, b, h) do { _Pragma("unroll") for (int m = 0; m < 4; ++m) _Pragma("unroll") for (int k = 0; k < 2; ++k) dst[m][k] = *(const PG8_LAS bf16x8*)(lds + PG8_SA(b, h) + aoff + m * 2048 + k * 1024); } while (0)
; #define PG8_LDB(dst, b, h) do { _Pragma("unroll") for (int n = 0; n < 2; ++n) _Pragma("unroll") for (int k = 0; k < 2; ++k) dst[n][k] = *(const PG8_LAS bf16x8*)(lds + PG8_SB(b, h) + boff + n * 2048 + k * 1024); } while (0)
; #define PG8_MMA(ai, bj, At, Bt) do { __builtin_amdgcn_s_setprio(1); _Pragma("unroll") for (int m = 0; m < 4; ++m) _Pragma("unroll") for (int n = 0; n < 2; ++n) _Pragma("unroll") for (int k = 0; k < 2; ++k) \
;         acc[ai][bj][m][n] = __builtin_amdgcn_mfma_f32_16x16x32_bf16(Bt[n][k], At[m][k], acc[ai][bj][m][n], 0, 0, 0); __builtin_amdgcn_s_setprio(0); } while (0)
; #define PG8_WAIT_V(n) asm volatile("s_waitcnt vmcnt(" #n ")" ::: "memory")
; #define PG8_WAIT_L(n) asm volatile("s_waitcnt lgkmcnt(" #n ")" ::: "memory")
; template <class Epi, class Sched, bool ALIGN_EPI = false, bool SP2 = false>
; __device__ __forceinline__ void gemm_phase(PG8_LAS unsigned char* lds, const Gemm g, const Sched& S, const Epi& E) {
;     ...
;             const bool last = (t == nt - 2);
;             const char* a1 = cA + (size_t)(t + 1) * kstep;
;             const char* a2 = last ? nA : cA + (size_t)(t + 2) * kstep; const char* b2 = last ? nB : cB + (size_t)(t + 2) * kstep;
;             const char* a3 = a2 + kstep; const char* b3 = b2 + kstep;
;             if (last && has_next) S.a_ready(nxt);
;             if constexpr (SP2) {
;             PG8_LDB(B0, 0, 0); PG8_LDB(B1, 0, 1); PG8_SCHED; PG8_LDA(At, 0, 0); PG8_STAGE(PG8_SA(1, 1), a1 + hstepA, voffA);
;             PG8_WAIT_V(8); PG8_WAIT_L(0); PG8_BAR; PG8_MMA(0, 0, At, B0); PG8_MMA(0, 1, At, B1); PG8_BAR; PG8_SCHED;
;             PG8_LDA(At, 0, 1); PG8_STAGE(PG8_SB(0, 0), b2, voffB); PG8_STAGE(PG8_SB(0, 1), b2 + hstepB, voffB); PG8_STAGE(PG8_SA(0, 0), a2, voffA);
;             PG8_WAIT_V(8); PG8_WAIT_L(0); PG8_BAR; PG8_MMA(1, 0, At, B0); PG8_MMA(1, 1, At, B1); PG8_BAR; PG8_SCHED;
.LBB0_1129:
	ds_read_b128 v[128:131], v191
	ds_read_b128 v[132:135], v191 offset:1024
	ds_read_b128 v[136:139], v191 offset:2048
	ds_read_b128 v[140:143], v191 offset:3072
	ds_read_b128 v[144:147], v192
	ds_read_b128 v[148:151], v192 offset:1024
	ds_read_b128 v[168:171], v192 offset:2048
	ds_read_b128 v[172:175], v192 offset:3072
	s_add_u32 s24, s22, 0x100
	s_addc_u32 s25, s23, 0
	s_cmp_eq_u32 s69, 40
	s_cselect_b32 s29, s11, s25
	s_cselect_b32 s28, s10, s24
	s_cselect_b32 s27, s21, s68
	s_cselect_b32 s26, s20, s67
	v_lshl_add_u64 v[184:185], s[22:23], 0, v[160:161]
	s_add_i32 m0, s34, 0xc000
	ds_read_b128 v[176:179], v193
	ds_read_b128 v[180:183], v193 offset:1024
	ds_read_b128 v[196:199], v193 offset:2048
	ds_read_b128 v[200:203], v193 offset:3072
	ds_read_b128 v[204:207], v193 offset:4096
	ds_read_b128 v[208:211], v193 offset:5120
	ds_read_b128 v[212:215], v193 offset:6144
	ds_read_b128 v[216:219], v193 offset:7168
	global_load_lds_dwordx4 v[184:185], off
	s_add_i32 m0, s34, 0xe000
	v_lshl_add_u64 v[184:185], s[22:23], 0, v[162:163]
	global_load_lds_dwordx4 v[184:185], off
	s_waitcnt vmcnt(8) lgkmcnt(0)
	s_barrier
	s_setprio 1
	v_mfma_f32_16x16x32_bf16 v[124:127], v[128:131], v[176:179], v[124:127]
	v_mfma_f32_16x16x32_bf16 v[120:123], v[136:139], v[176:179], v[120:123]
	v_mfma_f32_16x16x32_bf16 v[108:111], v[128:131], v[196:199], v[108:111]
	v_mfma_f32_16x16x32_bf16 v[104:107], v[136:139], v[196:199], v[104:107]
	v_mfma_f32_16x16x32_bf16 v[92:95], v[128:131], v[204:207], v[92:95]
	v_mfma_f32_16x16x32_bf16 v[88:91], v[136:139], v[204:207], v[88:91]
	v_mfma_f32_16x16x32_bf16 v[76:79], v[128:131], v[212:215], v[76:79]
	v_mfma_f32_16x16x32_bf16 v[72:75], v[136:139], v[212:215], v[72:75]
	v_mfma_f32_16x16x32_bf16 v[124:127], v[132:135], v[180:183], v[124:127]
	v_mfma_f32_16x16x32_bf16 v[120:123], v[140:143], v[180:183], v[120:123]
	v_mfma_f32_16x16x32_bf16 v[108:111], v[132:135], v[200:203], v[108:111]
	v_mfma_f32_16x16x32_bf16 v[104:107], v[140:143], v[200:203], v[104:107]
	v_mfma_f32_16x16x32_bf16 v[92:95], v[132:135], v[208:211], v[92:95]
	v_mfma_f32_16x16x32_bf16 v[88:91], v[140:143], v[208:211], v[88:91]
	v_mfma_f32_16x16x32_bf16 v[76:79], v[132:135], v[216:219], v[76:79]
	v_mfma_f32_16x16x32_bf16 v[72:75], v[140:143], v[216:219], v[72:75]
	s_setprio 0
	s_setprio 1
	v_mfma_f32_16x16x32_bf16 v[116:119], v[144:147], v[176:179], v[116:119]
	v_mfma_f32_16x16x32_bf16 v[112:115], v[168:171], v[176:179], v[112:115]
	v_mfma_f32_16x16x32_bf16 v[100:103], v[144:147], v[196:199], v[100:103]
	v_mfma_f32_16x16x32_bf16 v[96:99], v[168:171], v[196:199], v[96:99]
	v_mfma_f32_16x16x32_bf16 v[84:87], v[144:147], v[204:207], v[84:87]
	v_mfma_f32_16x16x32_bf16 v[80:83], v[168:171], v[204:207], v[80:83]
	v_mfma_f32_16x16x32_bf16 v[68:71], v[144:147], v[212:215], v[68:71]
	v_mfma_f32_16x16x32_bf16 v[64:67], v[168:171], v[212:215], v[64:67]
	v_mfma_f32_16x16x32_bf16 v[116:119], v[148:151], v[180:183], v[116:119]
	v_mfma_f32_16x16x32_bf16 v[112:115], v[172:175], v[180:183], v[112:115]
	v_mfma_f32_16x16x32_bf16 v[100:103], v[148:151], v[200:203], v[100:103]
	v_mfma_f32_16x16x32_bf16 v[96:99], v[172:175], v[200:203], v[96:99]
	v_mfma_f32_16x16x32_bf16 v[84:87], v[148:151], v[208:211], v[84:87]
	v_mfma_f32_16x16x32_bf16 v[80:83], v[172:175], v[208:211], v[80:83]
	v_mfma_f32_16x16x32_bf16 v[68:71], v[148:151], v[216:219], v[68:71]
	v_mfma_f32_16x16x32_bf16 v[64:67], v[172:175], v[216:219], v[64:67]
	s_barrier
	s_setprio 0
	s_add_i32 s22, s44, s31
	v_lshl_add_u64 v[184:185], s[26:27], 0, v[154:155]
	s_mov_b32 m0, s22
	ds_read_b128 v[176:179], v193 offset:16384
	ds_read_b128 v[180:183], v193 offset:17408
	ds_read_b128 v[196:199], v193 offset:18432
	ds_read_b128 v[200:203], v193 offset:19456
	ds_read_b128 v[204:207], v193 offset:20480
	ds_read_b128 v[208:211], v193 offset:21504
	ds_read_b128 v[212:215], v193 offset:22528
	ds_read_b128 v[216:219], v193 offset:23552
	global_load_lds_dwordx4 v[184:185], off
	s_add_i32 m0, s22, 0x2000
	s_add_u32 s22, s26, 0xb0000
	v_lshl_add_u64 v[220:221], s[26:27], 0, v[158:159]
	s_addc_u32 s23, s27, 0
	s_add_i32 s58, s45, s31
	global_load_lds_dwordx4 v[220:221], off
	v_lshl_add_u64 v[222:223], s[22:23], 0, v[154:155]
	s_mov_b32 m0, s58
	v_lshl_add_u64 v[224:225], s[28:29], 0, v[156:157]
	global_load_lds_dwordx4 v[222:223], off
	s_add_i32 m0, s58, 0x2000
	v_lshl_add_u64 v[222:223], s[22:23], 0, v[158:159]
	global_load_lds_dwordx4 v[222:223], off
	s_mov_b32 m0, s34
	v_lshl_add_u64 v[222:223], s[28:29], 0, v[152:153]
	global_load_lds_dwordx4 v[222:223], off
	s_mov_b32 m0, s35
	s_nop 0
	global_load_lds_dwordx4 v[224:225], off
	s_waitcnt vmcnt(8) lgkmcnt(0)
	s_barrier
; #define PG8_STAGE(bufoff, gbase, voff) do { _Pragma("unroll") for (int _i = 0; _i < 2; ++_i) \
;         __builtin_amdgcn_global_load_lds((const unsigned*)((const char*)(gbase) + (voff)[_i]), (PG8_LAS unsigned*)(lds + (bufoff) + ldsw + _i * 8192), 16, 0, 0); } while (0)
; #define PG8_LDA(dst, b, h) do { _Pragma("unroll") for (int m = 0; m < 4; ++m) _Pragma("unroll") for (int k = 0; k < 2; ++k) dst[m][k] = *(const PG8_LAS bf16x8*)(lds + PG8_SA(b, h) + aoff + m * 2048 + k * 1024); } while (0)
; #define PG8_LDB(dst, b, h) do { _Pragma("unroll") for (int n = 0; n < 2; ++n) _Pragma("unroll") for (int k = 0; k < 2; ++k) dst[n][k] = *(const PG8_LAS bf16x8*)(lds + PG8_SB(b, h) + boff + n * 2048 + k * 1024); } while (0)
; #define PG8_MMA(ai, bj, At, Bt) do { __builtin_amdgcn_s_setprio(1); _Pragma("unroll") for (int m = 0; m < 4; ++m) _Pragma("unroll") for (int n = 0; n < 2; ++n) _Pragma("unroll") for (int k = 0; k < 2; ++k) \
;         acc[ai][bj][m][n] = __builtin_amdgcn_mfma_f32_16x16x32_bf16(Bt[n][k], At[m][k], acc[ai][bj][m][n], 0, 0, 0); __builtin_amdgcn_s_setprio(0); } while (0)
; #define PG8_WAIT_V(n) asm volatile("s_waitcnt vmcnt(" #n ")" ::: "memory")
; #define PG8_WAIT_L(n) asm volatile("s_waitcnt lgkmcnt(" #n ")" ::: "memory")
; #define PG8_BAR __builtin_amdgcn_s_barrier()
; #define PG8_SCHED __builtin_amdgcn_sched_barrier(0)
; template <class Epi, class Sched, bool ALIGN_EPI = false, bool SP2 = false>
; __device__ __forceinline__ void gemm_phase(PG8_LAS unsigned char* lds, const Gemm g, const Sched& S, const Epi& E) {
;     ...
;             PG8_WAIT_V(8); PG8_WAIT_L(0); PG8_BAR; PG8_MMA(1, 0, At, B0); PG8_MMA(1, 1, At, B1); PG8_BAR; PG8_SCHED;
;             PG8_LDB(B0, 1, 0); PG8_LDB(B1, 1, 1); PG8_SCHED; PG8_LDA(At, 1, 0); PG8_STAGE(PG8_SA(0, 1), a2 + hstepA, voffA);
;             PG8_WAIT_V(8); PG8_WAIT_L(0); PG8_BAR; PG8_MMA(0, 0, At, B0); PG8_MMA(0, 1, At, B1); PG8_BAR; PG8_SCHED;
	s_setprio 1
	v_mfma_f32_16x16x32_bf16 v[60:63], v[128:131], v[176:179], v[60:63]
	v_mfma_f32_16x16x32_bf16 v[56:59], v[136:139], v[176:179], v[56:59]
	v_mfma_f32_16x16x32_bf16 v[44:47], v[128:131], v[196:199], v[44:47]
	v_mfma_f32_16x16x32_bf16 v[40:43], v[136:139], v[196:199], v[40:43]
	v_mfma_f32_16x16x32_bf16 v[28:31], v[128:131], v[204:207], v[28:31]
	v_mfma_f32_16x16x32_bf16 v[24:27], v[136:139], v[204:207], v[24:27]
	v_mfma_f32_16x16x32_bf16 v[12:15], v[128:131], v[212:215], v[12:15]
	v_mfma_f32_16x16x32_bf16 v[8:11], v[136:139], v[212:215], v[8:11]
	v_mfma_f32_16x16x32_bf16 v[60:63], v[132:135], v[180:183], v[60:63]
	v_mfma_f32_16x16x32_bf16 v[56:59], v[140:143], v[180:183], v[56:59]
	v_mfma_f32_16x16x32_bf16 v[44:47], v[132:135], v[200:203], v[44:47]
	v_mfma_f32_16x16x32_bf16 v[40:43], v[140:143], v[200:203], v[40:43]
	v_mfma_f32_16x16x32_bf16 v[28:31], v[132:135], v[208:211], v[28:31]
	v_mfma_f32_16x16x32_bf16 v[24:27], v[140:143], v[208:211], v[24:27]
	v_mfma_f32_16x16x32_bf16 v[12:15], v[132:135], v[216:219], v[12:15]
	v_mfma_f32_16x16x32_bf16 v[8:11], v[140:143], v[216:219], v[8:11]
	s_setprio 0
	s_setprio 1
	v_mfma_f32_16x16x32_bf16 v[52:55], v[144:147], v[176:179], v[52:55]
	v_mfma_f32_16x16x32_bf16 v[48:51], v[168:171], v[176:179], v[48:51]
	v_mfma_f32_16x16x32_bf16 v[36:39], v[144:147], v[196:199], v[36:39]
	v_mfma_f32_16x16x32_bf16 v[32:35], v[168:171], v[196:199], v[32:35]
	v_mfma_f32_16x16x32_bf16 v[20:23], v[144:147], v[204:207], v[20:23]
	v_mfma_f32_16x16x32_bf16 v[16:19], v[168:171], v[204:207], v[16:19]
	v_mfma_f32_16x16x32_bf16 v[4:7], v[144:147], v[212:215], v[4:7]
	v_mfma_f32_16x16x32_bf16 v[0:3], v[168:171], v[212:215], v[0:3]
	v_mfma_f32_16x16x32_bf16 v[52:55], v[148:151], v[180:183], v[52:55]
	v_mfma_f32_16x16x32_bf16 v[48:51], v[172:175], v[180:183], v[48:51]
	v_mfma_f32_16x16x32_bf16 v[36:39], v[148:151], v[200:203], v[36:39]
	v_mfma_f32_16x16x32_bf16 v[32:35], v[172:175], v[200:203], v[32:35]
	v_mfma_f32_16x16x32_bf16 v[20:23], v[148:151], v[208:211], v[20:23]
	v_mfma_f32_16x16x32_bf16 v[16:19], v[172:175], v[208:211], v[16:19]
	v_mfma_f32_16x16x32_bf16 v[4:7], v[148:151], v[216:219], v[4:7]
	v_mfma_f32_16x16x32_bf16 v[0:3], v[172:175], v[216:219], v[0:3]
	s_barrier
	s_setprio 0
	s_add_i32 s58, 0, 0x18000
	s_add_i32 s59, 0, 0x1c000
	v_add_u32_e32 v140, s58, v189
	v_add_u32_e32 v172, s59, v189
	ds_read_b128 v[128:131], v140
	ds_read_b128 v[132:135], v140 offset:1024
	ds_read_b128 v[136:139], v140 offset:2048
	ds_read_b128 v[140:143], v140 offset:3072
	ds_read_b128 v[144:147], v172
	ds_read_b128 v[148:151], v172 offset:1024
	ds_read_b128 v[168:171], v172 offset:2048
	ds_read_b128 v[172:175], v172 offset:3072
	s_add_u32 s22, s28, 0xb0000
	s_addc_u32 s23, s29, 0
	s_mov_b32 m0, s36
	v_lshl_add_u64 v[226:227], s[22:23], 0, v[152:153]
	ds_read_b128 v[176:179], v193 offset:32768
	ds_read_b128 v[180:183], v193 offset:33792
	ds_read_b128 v[196:199], v193 offset:34816
	ds_read_b128 v[200:203], v193 offset:35840
	ds_read_b128 v[204:207], v193 offset:36864
	ds_read_b128 v[208:211], v193 offset:37888
	ds_read_b128 v[212:215], v193 offset:38912
	ds_read_b128 v[216:219], v193 offset:39936
	global_load_lds_dwordx4 v[226:227], off
	s_mov_b32 m0, s37
	v_lshl_add_u64 v[226:227], s[22:23], 0, v[156:157]
	global_load_lds_dwordx4 v[226:227], off
	s_waitcnt vmcnt(8) lgkmcnt(0)
	s_barrier
	s_setprio 1
	v_mfma_f32_16x16x32_bf16 v[124:127], v[128:131], v[176:179], v[124:127]
	v_mfma_f32_16x16x32_bf16 v[120:123], v[136:139], v[176:179], v[120:123]
	v_mfma_f32_16x16x32_bf16 v[108:111], v[128:131], v[196:199], v[108:111]
	v_mfma_f32_16x16x32_bf16 v[104:107], v[136:139], v[196:199], v[104:107]
	v_mfma_f32_16x16x32_bf16 v[92:95], v[128:131], v[204:207], v[92:95]
	v_mfma_f32_16x16x32_bf16 v[88:91], v[136:139], v[204:207], v[88:91]
	v_mfma_f32_16x16x32_bf16 v[76:79], v[128:131], v[212:215], v[76:79]
	v_mfma_f32_16x16x32_bf16 v[72:75], v[136:139], v[212:215], v[72:75]
	v_mfma_f32_16x16x32_bf16 v[124:127], v[132:135], v[180:183], v[124:127]
	v_mfma_f32_16x16x32_bf16 v[120:123], v[140:143], v[180:183], v[120:123]
	v_mfma_f32_16x16x32_bf16 v[108:111], v[132:135], v[200:203], v[108:111]
	v_mfma_f32_16x16x32_bf16 v[104:107], v[140:143], v[200:203], v[104:107]
	v_mfma_f32_16x16x32_bf16 v[92:95], v[132:135], v[208:211], v[92:95]
	v_mfma_f32_16x16x32_bf16 v[88:91], v[140:143], v[208:211], v[88:91]
	v_mfma_f32_16x16x32_bf16 v[76:79], v[132:135], v[216:219], v[76:79]
	v_mfma_f32_16x16x32_bf16 v[72:75], v[140:143], v[216:219], v[72:75]
	s_setprio 0
	s_setprio 1
	v_mfma_f32_16x16x32_bf16 v[116:119], v[144:147], v[176:179], v[116:119]
	v_mfma_f32_16x16x32_bf16 v[112:115], v[168:171], v[176:179], v[112:115]
	v_mfma_f32_16x16x32_bf16 v[100:103], v[144:147], v[196:199], v[100:103]
	v_mfma_f32_16x16x32_bf16 v[96:99], v[168:171], v[196:199], v[96:99]
	v_mfma_f32_16x16x32_bf16 v[84:87], v[144:147], v[204:207], v[84:87]
	v_mfma_f32_16x16x32_bf16 v[80:83], v[168:171], v[204:207], v[80:83]
	v_mfma_f32_16x16x32_bf16 v[68:71], v[144:147], v[212:215], v[68:71]
	v_mfma_f32_16x16x32_bf16 v[64:67], v[168:171], v[212:215], v[64:67]
	v_mfma_f32_16x16x32_bf16 v[116:119], v[148:151], v[180:183], v[116:119]
	v_mfma_f32_16x16x32_bf16 v[112:115], v[172:175], v[180:183], v[112:115]
	v_mfma_f32_16x16x32_bf16 v[100:103], v[148:151], v[200:203], v[100:103]
	v_mfma_f32_16x16x32_bf16 v[96:99], v[172:175], v[200:203], v[96:99]
	v_mfma_f32_16x16x32_bf16 v[84:87], v[148:151], v[208:211], v[84:87]
	v_mfma_f32_16x16x32_bf16 v[80:83], v[172:175], v[208:211], v[80:83]
	v_mfma_f32_16x16x32_bf16 v[68:71], v[148:151], v[216:219], v[68:71]
	v_mfma_f32_16x16x32_bf16 v[64:67], v[172:175], v[216:219], v[64:67]
	s_barrier
; #define PG8_STAGE(bufoff, gbase, voff) do { _Pragma("unroll") for (int _i = 0; _i < 2; ++_i) \
;         __builtin_amdgcn_global_load_lds((const unsigned*)((const char*)(gbase) + (voff)[_i]), (PG8_LAS unsigned*)(lds + (bufoff) + ldsw + _i * 8192), 16, 0, 0); } while (0)
; #define PG8_LDA(dst, b, h) do { _Pragma("unroll") for (int m = 0; m < 4; ++m) _Pragma("unroll") for (int k = 0; k < 2; ++k) dst[m][k] = *(const PG8_LAS bf16x8*)(lds + PG8_SA(b, h) + aoff + m * 2048 + k * 1024); } while (0)
; #define PG8_MMA(ai, bj, At, Bt) do { __builtin_amdgcn_s_setprio(1); _Pragma("unroll") for (int m = 0; m < 4; ++m) _Pragma("unroll") for (int n = 0; n < 2; ++n) _Pragma("unroll") for (int k = 0; k < 2; ++k) \
;         acc[ai][bj][m][n] = __builtin_amdgcn_mfma_f32_16x16x32_bf16(Bt[n][k], At[m][k], acc[ai][bj][m][n], 0, 0, 0); __builtin_amdgcn_s_setprio(0); } while (0)
; #define PG8_WAIT_V(n) asm volatile("s_waitcnt vmcnt(" #n ")" ::: "memory")
; #define PG8_WAIT_L(n) asm volatile("s_waitcnt lgkmcnt(" #n ")" ::: "memory")
; #define PG8_BAR __builtin_amdgcn_s_barrier()
; #define PG8_SCHED __builtin_amdgcn_sched_barrier(0)
; template <class Epi, class Sched, bool ALIGN_EPI = false, bool SP2 = false>
; __device__ __forceinline__ void gemm_phase(PG8_LAS unsigned char* lds, const Gemm g, const Sched& S, const Epi& E) {
;     ...
;             PG8_LDA(At, 1, 1); PG8_STAGE(PG8_SB(1, 0), b3, voffB); PG8_STAGE(PG8_SB(1, 1), b3 + hstepB, voffB); PG8_STAGE(PG8_SA(1, 0), a3, voffA);
;             PG8_WAIT_V(8); PG8_WAIT_L(0); PG8_BAR; PG8_MMA(1, 0, At, B0); PG8_MMA(1, 1, At, B1); PG8_BAR; PG8_SCHED;
	s_setprio 0
	s_add_i32 s22, s58, s31
	v_lshl_add_u64 v[184:185], v[184:185], 0, s[16:17]
	s_mov_b32 m0, s22
	ds_read_b128 v[176:179], v193 offset:49152
	ds_read_b128 v[180:183], v193 offset:50176
	ds_read_b128 v[196:199], v193 offset:51200
	ds_read_b128 v[200:203], v193 offset:52224
	ds_read_b128 v[204:207], v193 offset:53248
	ds_read_b128 v[208:211], v193 offset:54272
	ds_read_b128 v[212:215], v193 offset:55296
	ds_read_b128 v[216:219], v193 offset:56320
	global_load_lds_dwordx4 v[184:185], off
	s_add_i32 m0, s22, 0x2000
	s_add_u32 s22, s26, 0xb0080
	v_lshl_add_u64 v[184:185], v[220:221], 0, s[16:17]
	s_addc_u32 s23, s27, 0
	s_add_i32 s26, s59, s31
	global_load_lds_dwordx4 v[184:185], off
	s_mov_b32 m0, s26
	v_lshl_add_u64 v[184:185], s[22:23], 0, v[154:155]
	global_load_lds_dwordx4 v[184:185], off
	s_add_i32 m0, s26, 0x2000
	v_lshl_add_u64 v[184:185], s[22:23], 0, v[158:159]
	global_load_lds_dwordx4 v[184:185], off
	s_mov_b32 m0, s39
	v_lshl_add_u64 v[184:185], v[222:223], 0, s[16:17]
	global_load_lds_dwordx4 v[184:185], off
	s_mov_b32 m0, s40
	v_lshl_add_u64 v[184:185], v[224:225], 0, s[16:17]
	global_load_lds_dwordx4 v[184:185], off
	s_waitcnt vmcnt(8) lgkmcnt(0)
	s_barrier
	s_setprio 1
	v_mfma_f32_16x16x32_bf16 v[60:63], v[128:131], v[176:179], v[60:63]
	v_mfma_f32_16x16x32_bf16 v[56:59], v[136:139], v[176:179], v[56:59]
	v_mfma_f32_16x16x32_bf16 v[44:47], v[128:131], v[196:199], v[44:47]
	v_mfma_f32_16x16x32_bf16 v[40:43], v[136:139], v[196:199], v[40:43]
	v_mfma_f32_16x16x32_bf16 v[28:31], v[128:131], v[204:207], v[28:31]
	v_mfma_f32_16x16x32_bf16 v[24:27], v[136:139], v[204:207], v[24:27]
	v_mfma_f32_16x16x32_bf16 v[12:15], v[128:131], v[212:215], v[12:15]
	v_mfma_f32_16x16x32_bf16 v[8:11], v[136:139], v[212:215], v[8:11]
	v_mfma_f32_16x16x32_bf16 v[60:63], v[132:135], v[180:183], v[60:63]
	v_mfma_f32_16x16x32_bf16 v[56:59], v[140:143], v[180:183], v[56:59]
	v_mfma_f32_16x16x32_bf16 v[44:47], v[132:135], v[200:203], v[44:47]
	v_mfma_f32_16x16x32_bf16 v[40:43], v[140:143], v[200:203], v[40:43]
	v_mfma_f32_16x16x32_bf16 v[28:31], v[132:135], v[208:211], v[28:31]
	v_mfma_f32_16x16x32_bf16 v[24:27], v[140:143], v[208:211], v[24:27]
	v_mfma_f32_16x16x32_bf16 v[12:15], v[132:135], v[216:219], v[12:15]
	v_mfma_f32_16x16x32_bf16 v[8:11], v[140:143], v[216:219], v[8:11]
	s_setprio 0
	s_setprio 1
	v_mfma_f32_16x16x32_bf16 v[52:55], v[144:147], v[176:179], v[52:55]
	v_mfma_f32_16x16x32_bf16 v[48:51], v[168:171], v[176:179], v[48:51]
	v_mfma_f32_16x16x32_bf16 v[36:39], v[144:147], v[196:199], v[36:39]
	v_mfma_f32_16x16x32_bf16 v[32:35], v[168:171], v[196:199], v[32:35]
	v_mfma_f32_16x16x32_bf16 v[20:23], v[144:147], v[204:207], v[20:23]
	v_mfma_f32_16x16x32_bf16 v[16:19], v[168:171], v[204:207], v[16:19]
	v_mfma_f32_16x16x32_bf16 v[4:7], v[144:147], v[212:215], v[4:7]
	v_mfma_f32_16x16x32_bf16 v[0:3], v[168:171], v[212:215], v[0:3]
	v_mfma_f32_16x16x32_bf16 v[52:55], v[148:151], v[180:183], v[52:55]
	v_mfma_f32_16x16x32_bf16 v[48:51], v[172:175], v[180:183], v[48:51]
	v_mfma_f32_16x16x32_bf16 v[36:39], v[148:151], v[200:203], v[36:39]
	v_mfma_f32_16x16x32_bf16 v[32:35], v[172:175], v[200:203], v[32:35]
	v_mfma_f32_16x16x32_bf16 v[20:23], v[148:151], v[208:211], v[20:23]
	v_mfma_f32_16x16x32_bf16 v[16:19], v[172:175], v[208:211], v[16:19]
	v_mfma_f32_16x16x32_bf16 v[4:7], v[148:151], v[216:219], v[4:7]
	v_mfma_f32_16x16x32_bf16 v[0:3], v[172:175], v[216:219], v[0:3]
	s_barrier
	s_setprio 0
	s_add_i32 s69, s69, 2
	s_add_u32 s67, s67, 0x100
	s_addc_u32 s68, s68, 0
	s_cmp_gt_u32 s69, 41
	s_mov_b64 s[22:23], s[24:25]
	s_cbranch_scc0 .LBB0_1129
	s_and_b64 vcc, exec, s[18:19]
	s_cbranch_vccz .LBB0_1132
	s_barrier

; #define PG8_STAGE(bufoff, gbase, voff) do { _Pragma("unroll") for (int _i = 0; _i < 2; ++_i) \
;         __builtin_amdgcn_global_load_lds((const unsigned*)((const char*)(gbase) + (voff)[_i]), (PG8_LAS unsigned*)(lds + (bufoff) + ldsw + _i * 8192), 16, 0, 0); } while (0)
; #define PG8_LDA(dst, b, h) do { _Pragma("unroll") for (int m = 0; m < 4; ++m) _Pragma("unroll") for (int k = 0; k < 2; ++k) dst[m][k] = *(const PG8_LAS bf16x8*)(lds + PG8_SA(b, h) + aoff + m * 2048 + k * 1024); } while (0)
; #define PG8_LDB(dst, b, h) do { _Pragma("unroll") for (int n = 0; n < 2; ++n) _Pragma("unroll") for (int k = 0; k < 2; ++k) dst[n][k] = *(const PG8_LAS bf16x8*)(lds + PG8_SB(b, h) + boff + n * 2048 + k * 1024); } while (0)
; #define PG8_MMA(ai, bj, At, Bt) do { __builtin_amdgcn_s_setprio(1); _Pragma("unroll") for (int m = 0; m < 4; ++m) _Pragma("unroll") for (int n = 0; n < 2; ++n) _Pragma("unroll") for (int k = 0; k < 2; ++k) \
;         acc[ai][bj][m][n] = __builtin_amdgcn_mfma_f32_16x16x32_bf16(Bt[n][k], At[m][k], acc[ai][bj][m][n], 0, 0, 0); __builtin_amdgcn_s_setprio(0); } while (0)
; #define PG8_WAIT_V(n) asm volatile("s_waitcnt vmcnt(" #n ")" ::: "memory")
; #define PG8_WAIT_L(n) asm volatile("s_waitcnt lgkmcnt(" #n ")" ::: "memory")
; template <class Epi, class Sched, bool ALIGN_EPI = false, bool SP2 = false>
; __device__ __forceinline__ void gemm_phase(PG8_LAS unsigned char* lds, const Gemm g, const Sched& S, const Epi& E) {
;     ...
;             const bool last = (t == nt - 2);
;             const char* a1 = cA + (size_t)(t + 1) * kstep;
;             const char* a2 = last ? nA : cA + (size_t)(t + 2) * kstep; const char* b2 = last ? nB : cB + (size_t)(t + 2) * kstep;
;             const char* a3 = a2 + kstep; const char* b3 = b2 + kstep;
;             if (last && has_next) S.a_ready(nxt);
;             if constexpr (SP2) {
;             PG8_LDB(B0, 0, 0); PG8_LDB(B1, 0, 1); PG8_SCHED; PG8_LDA(At, 0, 0); PG8_STAGE(PG8_SA(1, 1), a1 + hstepA, voffA);
;             PG8_WAIT_V(8); PG8_WAIT_L(0); PG8_BAR; PG8_MMA(0, 0, At, B0); PG8_MMA(0, 1, At, B1); PG8_BAR; PG8_SCHED;
;             PG8_LDA(At, 0, 1); PG8_STAGE(PG8_SB(0, 0), b2, voffB); PG8_STAGE(PG8_SB(0, 1), b2 + hstepB, voffB); PG8_STAGE(PG8_SA(0, 0), a2, voffA);
;             PG8_WAIT_V(8); PG8_WAIT_L(0); PG8_BAR; PG8_MMA(1, 0, At, B0); PG8_MMA(1, 1, At, B1); PG8_BAR; PG8_SCHED;
.LBB0_1161:
	s_add_u32 s43, s36, s42
	s_addc_u32 s48, s37, 0
	s_add_u32 s46, s43, 0x100
	s_addc_u32 s47, s48, 0
	s_and_b64 s[44:45], s[40:41], exec
	s_cselect_b32 s45, s25, s47
	s_cselect_b32 s44, s89, s46
	s_add_u32 s42, s34, s42
	s_addc_u32 s46, s35, 0
	s_add_u32 s42, s42, 0x100
	s_addc_u32 s46, s46, 0
	s_and_b64 s[40:41], s[40:41], exec
	s_cselect_b32 s47, s23, s46
	s_cselect_b32 s46, s90, s42
	s_add_u32 s64, s43, 0x10080
	ds_read_b128 v[146:149], v143
	ds_read_b128 v[150:153], v143 offset:1024
	ds_read_b128 v[154:157], v143 offset:2048
	ds_read_b128 v[158:161], v143 offset:3072
	ds_read_b128 v[162:165], v144
	ds_read_b128 v[166:169], v144 offset:1024
	ds_read_b128 v[170:173], v144 offset:2048
	ds_read_b128 v[174:177], v144 offset:3072
	s_addc_u32 s65, s48, 0
	s_add_i32 s97, s82, s67
	s_add_i32 m0, s31, 0xc000
	s_add_i32 s59, s31, 0xe000
	s_add_i32 s58, s97, 0x2000
	s_add_u32 s48, s46, 0x10000
	s_addc_u32 s49, s47, 0
	s_add_i32 vcc_hi, s83, s67
	s_add_i32 vcc_lo, vcc_hi, 0x2000
	s_add_i32 s96, 0, 0x18000
	s_add_i32 s95, 0, 0x1c000
	s_add_u32 s42, s44, 0x10000
	s_addc_u32 s43, s45, 0
	s_add_i32 s94, s96, s67
	s_add_i32 s92, s94, 0x2000
	s_add_u32 s40, s46, 0x10080
	s_addc_u32 s41, s47, 0
	s_add_i32 s93, s95, s67
	s_add_i32 s91, s93, 0x2000
	v_lshl_add_u64 v[212:213], s[64:65], 0, v[134:135]
	ds_read_b128 v[178:181], v145
	ds_read_b128 v[182:185], v145 offset:1024
	ds_read_b128 v[188:191], v145 offset:2048
	ds_read_b128 v[192:195], v145 offset:3072
	ds_read_b128 v[196:199], v145 offset:4096
	ds_read_b128 v[200:203], v145 offset:5120
	ds_read_b128 v[204:207], v145 offset:6144
	ds_read_b128 v[208:211], v145 offset:7168
	global_load_lds_dwordx4 v[212:213], off
	s_mov_b32 m0, s59
	v_lshl_add_u64 v[212:213], s[64:65], 0, v[130:131]
	global_load_lds_dwordx4 v[212:213], off
	s_waitcnt vmcnt(8) lgkmcnt(0)
	s_barrier
	s_setprio 1
	v_mfma_f32_16x16x32_bf16 v[124:127], v[146:149], v[178:181], v[124:127]
	v_mfma_f32_16x16x32_bf16 v[120:123], v[154:157], v[178:181], v[120:123]
	v_mfma_f32_16x16x32_bf16 v[116:119], v[146:149], v[188:191], v[116:119]
	v_mfma_f32_16x16x32_bf16 v[108:111], v[154:157], v[188:191], v[108:111]
	v_mfma_f32_16x16x32_bf16 v[100:103], v[146:149], v[196:199], v[100:103]
	v_mfma_f32_16x16x32_bf16 v[92:95], v[154:157], v[196:199], v[92:95]
	v_mfma_f32_16x16x32_bf16 v[84:87], v[146:149], v[204:207], v[84:87]
	v_mfma_f32_16x16x32_bf16 v[76:79], v[154:157], v[204:207], v[76:79]
	v_mfma_f32_16x16x32_bf16 v[124:127], v[150:153], v[182:185], v[124:127]
	v_mfma_f32_16x16x32_bf16 v[120:123], v[158:161], v[182:185], v[120:123]
	v_mfma_f32_16x16x32_bf16 v[116:119], v[150:153], v[192:195], v[116:119]
	v_mfma_f32_16x16x32_bf16 v[108:111], v[158:161], v[192:195], v[108:111]
	v_mfma_f32_16x16x32_bf16 v[100:103], v[150:153], v[200:203], v[100:103]
	v_mfma_f32_16x16x32_bf16 v[92:95], v[158:161], v[200:203], v[92:95]
	v_mfma_f32_16x16x32_bf16 v[84:87], v[150:153], v[208:211], v[84:87]
	v_mfma_f32_16x16x32_bf16 v[76:79], v[158:161], v[208:211], v[76:79]
	s_setprio 0
	s_setprio 1
	v_mfma_f32_16x16x32_bf16 v[112:115], v[162:165], v[178:181], v[112:115]
	v_mfma_f32_16x16x32_bf16 v[104:107], v[170:173], v[178:181], v[104:107]
	v_mfma_f32_16x16x32_bf16 v[96:99], v[162:165], v[188:191], v[96:99]
	v_mfma_f32_16x16x32_bf16 v[88:91], v[170:173], v[188:191], v[88:91]
	v_mfma_f32_16x16x32_bf16 v[80:83], v[162:165], v[196:199], v[80:83]
	v_mfma_f32_16x16x32_bf16 v[72:75], v[170:173], v[196:199], v[72:75]
	v_mfma_f32_16x16x32_bf16 v[68:71], v[162:165], v[204:207], v[68:71]
	v_mfma_f32_16x16x32_bf16 v[64:67], v[170:173], v[204:207], v[64:67]
	v_mfma_f32_16x16x32_bf16 v[112:115], v[166:169], v[182:185], v[112:115]
	v_mfma_f32_16x16x32_bf16 v[104:107], v[174:177], v[182:185], v[104:107]
	v_mfma_f32_16x16x32_bf16 v[96:99], v[166:169], v[192:195], v[96:99]
	v_mfma_f32_16x16x32_bf16 v[88:91], v[174:177], v[192:195], v[88:91]
	v_mfma_f32_16x16x32_bf16 v[80:83], v[166:169], v[200:203], v[80:83]
	v_mfma_f32_16x16x32_bf16 v[72:75], v[174:177], v[200:203], v[72:75]
	v_mfma_f32_16x16x32_bf16 v[68:71], v[166:169], v[208:211], v[68:71]
	v_mfma_f32_16x16x32_bf16 v[64:67], v[174:177], v[208:211], v[64:67]
	s_barrier
	s_setprio 0
	s_mov_b32 m0, s97
	v_lshl_add_u64 v[212:213], s[46:47], 0, v[132:133]
	ds_read_b128 v[178:181], v145 offset:16384
	ds_read_b128 v[182:185], v145 offset:17408
	ds_read_b128 v[188:191], v145 offset:18432
	ds_read_b128 v[192:195], v145 offset:19456
	ds_read_b128 v[196:199], v145 offset:20480
	ds_read_b128 v[200:203], v145 offset:21504
	ds_read_b128 v[204:207], v145 offset:22528
	ds_read_b128 v[208:211], v145 offset:23552
	global_load_lds_dwordx4 v[212:213], off
	v_lshl_add_u64 v[214:215], s[46:47], 0, v[128:129]
	s_mov_b32 m0, s58
	v_lshl_add_u64 v[216:217], s[48:49], 0, v[132:133]
	global_load_lds_dwordx4 v[214:215], off
	s_mov_b32 m0, vcc_hi
	v_lshl_add_u64 v[218:219], s[44:45], 0, v[130:131]
	global_load_lds_dwordx4 v[216:217], off
	s_mov_b32 m0, vcc_lo
	v_lshl_add_u64 v[216:217], s[48:49], 0, v[128:129]
	global_load_lds_dwordx4 v[216:217], off
	s_mov_b32 m0, s31
	v_lshl_add_u64 v[216:217], s[44:45], 0, v[134:135]
	global_load_lds_dwordx4 v[216:217], off
	s_mov_b32 m0, s74
	s_nop 0
	global_load_lds_dwordx4 v[218:219], off
	s_waitcnt vmcnt(8) lgkmcnt(0)
	s_barrier
; #define PG8_STAGE(bufoff, gbase, voff) do { _Pragma("unroll") for (int _i = 0; _i < 2; ++_i) \
;         __builtin_amdgcn_global_load_lds((const unsigned*)((const char*)(gbase) + (voff)[_i]), (PG8_LAS unsigned*)(lds + (bufoff) + ldsw + _i * 8192), 16, 0, 0); } while (0)
; #define PG8_LDA(dst, b, h) do { _Pragma("unroll") for (int m = 0; m < 4; ++m) _Pragma("unroll") for (int k = 0; k < 2; ++k) dst[m][k] = *(const PG8_LAS bf16x8*)(lds + PG8_SA(b, h) + aoff + m * 2048 + k * 1024); } while (0)
; #define PG8_LDB(dst, b, h) do { _Pragma("unroll") for (int n = 0; n < 2; ++n) _Pragma("unroll") for (int k = 0; k < 2; ++k) dst[n][k] = *(const PG8_LAS bf16x8*)(lds + PG8_SB(b, h) + boff + n * 2048 + k * 1024); } while (0)
; #define PG8_MMA(ai, bj, At, Bt) do { __builtin_amdgcn_s_setprio(1); _Pragma("unroll") for (int m = 0; m < 4; ++m) _Pragma("unroll") for (int n = 0; n < 2; ++n) _Pragma("unroll") for (int k = 0; k < 2; ++k) \
;         acc[ai][bj][m][n] = __builtin_amdgcn_mfma_f32_16x16x32_bf16(Bt[n][k], At[m][k], acc[ai][bj][m][n], 0, 0, 0); __builtin_amdgcn_s_setprio(0); } while (0)
; #define PG8_WAIT_V(n) asm volatile("s_waitcnt vmcnt(" #n ")" ::: "memory")
; #define PG8_WAIT_L(n) asm volatile("s_waitcnt lgkmcnt(" #n ")" ::: "memory")
; #define PG8_BAR __builtin_amdgcn_s_barrier()
; #define PG8_SCHED __builtin_amdgcn_sched_barrier(0)
; template <class Epi, class Sched, bool ALIGN_EPI = false, bool SP2 = false>
; __device__ __forceinline__ void gemm_phase(PG8_LAS unsigned char* lds, const Gemm g, const Sched& S, const Epi& E) {
;     ...
;             PG8_WAIT_V(8); PG8_WAIT_L(0); PG8_BAR; PG8_MMA(1, 0, At, B0); PG8_MMA(1, 1, At, B1); PG8_BAR; PG8_SCHED;
;             PG8_LDB(B0, 1, 0); PG8_LDB(B1, 1, 1); PG8_SCHED; PG8_LDA(At, 1, 0); PG8_STAGE(PG8_SA(0, 1), a2 + hstepA, voffA);
;             PG8_WAIT_V(8); PG8_WAIT_L(0); PG8_BAR; PG8_MMA(0, 0, At, B0); PG8_MMA(0, 1, At, B1); PG8_BAR; PG8_SCHED;
	s_setprio 1
	v_mfma_f32_16x16x32_bf16 v[60:63], v[146:149], v[178:181], v[60:63]
	v_mfma_f32_16x16x32_bf16 v[56:59], v[154:157], v[178:181], v[56:59]
	v_mfma_f32_16x16x32_bf16 v[52:55], v[146:149], v[188:191], v[52:55]
	v_mfma_f32_16x16x32_bf16 v[44:47], v[154:157], v[188:191], v[44:47]
	v_mfma_f32_16x16x32_bf16 v[36:39], v[146:149], v[196:199], v[36:39]
	v_mfma_f32_16x16x32_bf16 v[28:31], v[154:157], v[196:199], v[28:31]
	v_mfma_f32_16x16x32_bf16 v[20:23], v[146:149], v[204:207], v[20:23]
	v_mfma_f32_16x16x32_bf16 v[12:15], v[154:157], v[204:207], v[12:15]
	v_mfma_f32_16x16x32_bf16 v[60:63], v[150:153], v[182:185], v[60:63]
	v_mfma_f32_16x16x32_bf16 v[56:59], v[158:161], v[182:185], v[56:59]
	v_mfma_f32_16x16x32_bf16 v[52:55], v[150:153], v[192:195], v[52:55]
	v_mfma_f32_16x16x32_bf16 v[44:47], v[158:161], v[192:195], v[44:47]
	v_mfma_f32_16x16x32_bf16 v[36:39], v[150:153], v[200:203], v[36:39]
	v_mfma_f32_16x16x32_bf16 v[28:31], v[158:161], v[200:203], v[28:31]
	v_mfma_f32_16x16x32_bf16 v[20:23], v[150:153], v[208:211], v[20:23]
	v_mfma_f32_16x16x32_bf16 v[12:15], v[158:161], v[208:211], v[12:15]
	s_setprio 0
	s_setprio 1
	v_mfma_f32_16x16x32_bf16 v[48:51], v[162:165], v[178:181], v[48:51]
	v_mfma_f32_16x16x32_bf16 v[40:43], v[170:173], v[178:181], v[40:43]
	v_mfma_f32_16x16x32_bf16 v[32:35], v[162:165], v[188:191], v[32:35]
	v_mfma_f32_16x16x32_bf16 v[24:27], v[170:173], v[188:191], v[24:27]
	v_mfma_f32_16x16x32_bf16 v[16:19], v[162:165], v[196:199], v[16:19]
	v_mfma_f32_16x16x32_bf16 v[8:11], v[170:173], v[196:199], v[8:11]
	v_mfma_f32_16x16x32_bf16 v[4:7], v[162:165], v[204:207], v[4:7]
	v_mfma_f32_16x16x32_bf16 v[0:3], v[170:173], v[204:207], v[0:3]
	v_mfma_f32_16x16x32_bf16 v[48:51], v[166:169], v[182:185], v[48:51]
	v_mfma_f32_16x16x32_bf16 v[40:43], v[174:177], v[182:185], v[40:43]
	v_mfma_f32_16x16x32_bf16 v[32:35], v[166:169], v[192:195], v[32:35]
	v_mfma_f32_16x16x32_bf16 v[24:27], v[174:177], v[192:195], v[24:27]
	v_mfma_f32_16x16x32_bf16 v[16:19], v[166:169], v[200:203], v[16:19]
	v_mfma_f32_16x16x32_bf16 v[8:11], v[174:177], v[200:203], v[8:11]
	v_mfma_f32_16x16x32_bf16 v[4:7], v[166:169], v[208:211], v[4:7]
	v_mfma_f32_16x16x32_bf16 v[0:3], v[174:177], v[208:211], v[0:3]
	s_barrier
	s_setprio 0
	v_add_u32_e32 v158, s96, v141
	v_add_u32_e32 v174, s95, v141
	ds_read_b128 v[146:149], v158
	ds_read_b128 v[150:153], v158 offset:1024
	ds_read_b128 v[154:157], v158 offset:2048
	ds_read_b128 v[158:161], v158 offset:3072
	ds_read_b128 v[162:165], v174
	ds_read_b128 v[166:169], v174 offset:1024
	ds_read_b128 v[170:173], v174 offset:2048
	ds_read_b128 v[174:177], v174 offset:3072
	s_mov_b32 m0, s75
	v_lshl_add_u64 v[220:221], s[42:43], 0, v[134:135]
	ds_read_b128 v[178:181], v145 offset:32768
	ds_read_b128 v[182:185], v145 offset:33792
	ds_read_b128 v[188:191], v145 offset:34816
	ds_read_b128 v[192:195], v145 offset:35840
	ds_read_b128 v[196:199], v145 offset:36864
	ds_read_b128 v[200:203], v145 offset:37888
	ds_read_b128 v[204:207], v145 offset:38912
	ds_read_b128 v[208:211], v145 offset:39936
	global_load_lds_dwordx4 v[220:221], off
	s_mov_b32 m0, s76
	v_lshl_add_u64 v[220:221], s[42:43], 0, v[130:131]
	global_load_lds_dwordx4 v[220:221], off
	s_waitcnt vmcnt(8) lgkmcnt(0)
	s_barrier
	s_setprio 1
	v_mfma_f32_16x16x32_bf16 v[124:127], v[146:149], v[178:181], v[124:127]
	v_mfma_f32_16x16x32_bf16 v[120:123], v[154:157], v[178:181], v[120:123]
	v_mfma_f32_16x16x32_bf16 v[116:119], v[146:149], v[188:191], v[116:119]
	v_mfma_f32_16x16x32_bf16 v[108:111], v[154:157], v[188:191], v[108:111]
	v_mfma_f32_16x16x32_bf16 v[100:103], v[146:149], v[196:199], v[100:103]
	v_mfma_f32_16x16x32_bf16 v[92:95], v[154:157], v[196:199], v[92:95]
	v_mfma_f32_16x16x32_bf16 v[84:87], v[146:149], v[204:207], v[84:87]
	v_mfma_f32_16x16x32_bf16 v[76:79], v[154:157], v[204:207], v[76:79]
	v_mfma_f32_16x16x32_bf16 v[124:127], v[150:153], v[182:185], v[124:127]
	v_mfma_f32_16x16x32_bf16 v[120:123], v[158:161], v[182:185], v[120:123]
	v_mfma_f32_16x16x32_bf16 v[116:119], v[150:153], v[192:195], v[116:119]
	v_mfma_f32_16x16x32_bf16 v[108:111], v[158:161], v[192:195], v[108:111]
	v_mfma_f32_16x16x32_bf16 v[100:103], v[150:153], v[200:203], v[100:103]
	v_mfma_f32_16x16x32_bf16 v[92:95], v[158:161], v[200:203], v[92:95]
	v_mfma_f32_16x16x32_bf16 v[84:87], v[150:153], v[208:211], v[84:87]
	v_mfma_f32_16x16x32_bf16 v[76:79], v[158:161], v[208:211], v[76:79]
	s_setprio 0
	s_setprio 1
	v_mfma_f32_16x16x32_bf16 v[112:115], v[162:165], v[178:181], v[112:115]
	v_mfma_f32_16x16x32_bf16 v[104:107], v[170:173], v[178:181], v[104:107]
	v_mfma_f32_16x16x32_bf16 v[96:99], v[162:165], v[188:191], v[96:99]
	v_mfma_f32_16x16x32_bf16 v[88:91], v[170:173], v[188:191], v[88:91]
	v_mfma_f32_16x16x32_bf16 v[80:83], v[162:165], v[196:199], v[80:83]
	v_mfma_f32_16x16x32_bf16 v[72:75], v[170:173], v[196:199], v[72:75]
	v_mfma_f32_16x16x32_bf16 v[68:71], v[162:165], v[204:207], v[68:71]
	v_mfma_f32_16x16x32_bf16 v[64:67], v[170:173], v[204:207], v[64:67]
	v_mfma_f32_16x16x32_bf16 v[112:115], v[166:169], v[182:185], v[112:115]
	v_mfma_f32_16x16x32_bf16 v[104:107], v[174:177], v[182:185], v[104:107]
	v_mfma_f32_16x16x32_bf16 v[96:99], v[166:169], v[192:195], v[96:99]
	v_mfma_f32_16x16x32_bf16 v[88:91], v[174:177], v[192:195], v[88:91]
	v_mfma_f32_16x16x32_bf16 v[80:83], v[166:169], v[200:203], v[80:83]
	v_mfma_f32_16x16x32_bf16 v[72:75], v[174:177], v[200:203], v[72:75]
	v_mfma_f32_16x16x32_bf16 v[68:71], v[166:169], v[208:211], v[68:71]
	v_mfma_f32_16x16x32_bf16 v[64:67], v[174:177], v[208:211], v[64:67]
	s_barrier
; #define PG8_STAGE(bufoff, gbase, voff) do { _Pragma("unroll") for (int _i = 0; _i < 2; ++_i) \
;         __builtin_amdgcn_global_load_lds((const unsigned*)((const char*)(gbase) + (voff)[_i]), (PG8_LAS unsigned*)(lds + (bufoff) + ldsw + _i * 8192), 16, 0, 0); } while (0)
; #define PG8_LDA(dst, b, h) do { _Pragma("unroll") for (int m = 0; m < 4; ++m) _Pragma("unroll") for (int k = 0; k < 2; ++k) dst[m][k] = *(const PG8_LAS bf16x8*)(lds + PG8_SA(b, h) + aoff + m * 2048 + k * 1024); } while (0)
; #define PG8_MMA(ai, bj, At, Bt) do { __builtin_amdgcn_s_setprio(1); _Pragma("unroll") for (int m = 0; m < 4; ++m) _Pragma("unroll") for (int n = 0; n < 2; ++n) _Pragma("unroll") for (int k = 0; k < 2; ++k) \
;         acc[ai][bj][m][n] = __builtin_amdgcn_mfma_f32_16x16x32_bf16(Bt[n][k], At[m][k], acc[ai][bj][m][n], 0, 0, 0); __builtin_amdgcn_s_setprio(0); } while (0)
; #define PG8_WAIT_V(n) asm volatile("s_waitcnt vmcnt(" #n ")" ::: "memory")
; #define PG8_WAIT_L(n) asm volatile("s_waitcnt lgkmcnt(" #n ")" ::: "memory")
; #define PG8_BAR __builtin_amdgcn_s_barrier()
; #define PG8_SCHED __builtin_amdgcn_sched_barrier(0)
; template <class Epi, class Sched, bool ALIGN_EPI = false, bool SP2 = false>
; __device__ __forceinline__ void gemm_phase(PG8_LAS unsigned char* lds, const Gemm g, const Sched& S, const Epi& E) {
;     ...
;             PG8_LDA(At, 1, 1); PG8_STAGE(PG8_SB(1, 0), b3, voffB); PG8_STAGE(PG8_SB(1, 1), b3 + hstepB, voffB); PG8_STAGE(PG8_SA(1, 0), a3, voffA);
;             PG8_WAIT_V(8); PG8_WAIT_L(0); PG8_BAR; PG8_MMA(1, 0, At, B0); PG8_MMA(1, 1, At, B1); PG8_BAR; PG8_SCHED;
	s_setprio 0
	s_mov_b32 m0, s94
	v_lshl_add_u64 v[212:213], v[212:213], 0, s[10:11]
	ds_read_b128 v[178:181], v145 offset:49152
	ds_read_b128 v[182:185], v145 offset:50176
	ds_read_b128 v[188:191], v145 offset:51200
	ds_read_b128 v[192:195], v145 offset:52224
	ds_read_b128 v[196:199], v145 offset:53248
	ds_read_b128 v[200:203], v145 offset:54272
	ds_read_b128 v[204:207], v145 offset:55296
	ds_read_b128 v[208:211], v145 offset:56320
	global_load_lds_dwordx4 v[212:213], off
	s_mov_b32 m0, s92
	v_lshl_add_u64 v[212:213], v[214:215], 0, s[10:11]
	global_load_lds_dwordx4 v[212:213], off
	s_mov_b32 m0, s93
	v_lshl_add_u64 v[212:213], s[40:41], 0, v[132:133]
	global_load_lds_dwordx4 v[212:213], off
	s_mov_b32 m0, s91
	v_lshl_add_u64 v[212:213], s[40:41], 0, v[128:129]
	global_load_lds_dwordx4 v[212:213], off
	s_mov_b32 m0, s78
	v_lshl_add_u64 v[212:213], v[216:217], 0, s[10:11]
	global_load_lds_dwordx4 v[212:213], off
	s_mov_b32 m0, s79
	v_lshl_add_u64 v[212:213], v[218:219], 0, s[10:11]
	global_load_lds_dwordx4 v[212:213], off
	s_waitcnt vmcnt(8) lgkmcnt(0)
	s_barrier
	s_setprio 1
	v_mfma_f32_16x16x32_bf16 v[60:63], v[146:149], v[178:181], v[60:63]
	v_mfma_f32_16x16x32_bf16 v[56:59], v[154:157], v[178:181], v[56:59]
	v_mfma_f32_16x16x32_bf16 v[52:55], v[146:149], v[188:191], v[52:55]
	v_mfma_f32_16x16x32_bf16 v[44:47], v[154:157], v[188:191], v[44:47]
	v_mfma_f32_16x16x32_bf16 v[36:39], v[146:149], v[196:199], v[36:39]
	v_mfma_f32_16x16x32_bf16 v[28:31], v[154:157], v[196:199], v[28:31]
	v_mfma_f32_16x16x32_bf16 v[20:23], v[146:149], v[204:207], v[20:23]
	v_mfma_f32_16x16x32_bf16 v[12:15], v[154:157], v[204:207], v[12:15]
	v_mfma_f32_16x16x32_bf16 v[60:63], v[150:153], v[182:185], v[60:63]
	v_mfma_f32_16x16x32_bf16 v[56:59], v[158:161], v[182:185], v[56:59]
	v_mfma_f32_16x16x32_bf16 v[52:55], v[150:153], v[192:195], v[52:55]
	v_mfma_f32_16x16x32_bf16 v[44:47], v[158:161], v[192:195], v[44:47]
	v_mfma_f32_16x16x32_bf16 v[36:39], v[150:153], v[200:203], v[36:39]
	v_mfma_f32_16x16x32_bf16 v[28:31], v[158:161], v[200:203], v[28:31]
	v_mfma_f32_16x16x32_bf16 v[20:23], v[150:153], v[208:211], v[20:23]
	v_mfma_f32_16x16x32_bf16 v[12:15], v[158:161], v[208:211], v[12:15]
	s_setprio 0
	s_setprio 1
	v_mfma_f32_16x16x32_bf16 v[48:51], v[162:165], v[178:181], v[48:51]
	v_mfma_f32_16x16x32_bf16 v[40:43], v[170:173], v[178:181], v[40:43]
	v_mfma_f32_16x16x32_bf16 v[32:35], v[162:165], v[188:191], v[32:35]
	v_mfma_f32_16x16x32_bf16 v[24:27], v[170:173], v[188:191], v[24:27]
	v_mfma_f32_16x16x32_bf16 v[16:19], v[162:165], v[196:199], v[16:19]
	v_mfma_f32_16x16x32_bf16 v[8:11], v[170:173], v[196:199], v[8:11]
	v_mfma_f32_16x16x32_bf16 v[4:7], v[162:165], v[204:207], v[4:7]
	v_mfma_f32_16x16x32_bf16 v[0:3], v[170:173], v[204:207], v[0:3]
	v_mfma_f32_16x16x32_bf16 v[48:51], v[166:169], v[182:185], v[48:51]
	v_mfma_f32_16x16x32_bf16 v[40:43], v[174:177], v[182:185], v[40:43]
	v_mfma_f32_16x16x32_bf16 v[32:35], v[166:169], v[192:195], v[32:35]
	v_mfma_f32_16x16x32_bf16 v[24:27], v[174:177], v[192:195], v[24:27]
	v_mfma_f32_16x16x32_bf16 v[16:19], v[166:169], v[200:203], v[16:19]
	v_mfma_f32_16x16x32_bf16 v[8:11], v[174:177], v[200:203], v[8:11]
	v_mfma_f32_16x16x32_bf16 v[4:7], v[166:169], v[208:211], v[4:7]
	v_mfma_f32_16x16x32_bf16 v[0:3], v[174:177], v[208:211], v[0:3]
	s_barrier
	s_setprio 0
	s_movk_i32 s42, 0x100
	s_andn2_b64 vcc, exec, s[38:39]
	s_mov_b64 s[40:41], -1
	s_mov_b64 s[38:39], 0
	s_cbranch_vccz .LBB0_1161
	s_and_b64 vcc, exec, s[14:15]
	s_cbranch_vccz .LBB0_1164
	s_barrier

; #define PG8_STAGE(bufoff, gbase, voff) do { _Pragma("unroll") for (int _i = 0; _i < 2; ++_i) \
;         __builtin_amdgcn_global_load_lds((const unsigned*)((const char*)(gbase) + (voff)[_i]), (PG8_LAS unsigned*)(lds + (bufoff) + ldsw + _i * 8192), 16, 0, 0); } while (0)
; #define PG8_LDA(dst, b, h) do { _Pragma("unroll") for (int m = 0; m < 4; ++m) _Pragma("unroll") for (int k = 0; k < 2; ++k) dst[m][k] = *(const PG8_LAS bf16x8*)(lds + PG8_SA(b, h) + aoff + m * 2048 + k * 1024); } while (0)
; #define PG8_LDB(dst, b, h) do { _Pragma("unroll") for (int n = 0; n < 2; ++n) _Pragma("unroll") for (int k = 0; k < 2; ++k) dst[n][k] = *(const PG8_LAS bf16x8*)(lds + PG8_SB(b, h) + boff + n * 2048 + k * 1024); } while (0)
; #define PG8_MMA(ai, bj, At, Bt) do { __builtin_amdgcn_s_setprio(1); _Pragma("unroll") for (int m = 0; m < 4; ++m) _Pragma("unroll") for (int n = 0; n < 2; ++n) _Pragma("unroll") for (int k = 0; k < 2; ++k) \
;         acc[ai][bj][m][n] = __builtin_amdgcn_mfma_f32_16x16x32_bf16(Bt[n][k], At[m][k], acc[ai][bj][m][n], 0, 0, 0); __builtin_amdgcn_s_setprio(0); } while (0)
; #define PG8_WAIT_V(n) asm volatile("s_waitcnt vmcnt(" #n ")" ::: "memory")
; #define PG8_WAIT_L(n) asm volatile("s_waitcnt lgkmcnt(" #n ")" ::: "memory")
; template <class Epi, class Sched, bool ALIGN_EPI = false, bool SP2 = false>
; __device__ __forceinline__ void gemm_phase(PG8_LAS unsigned char* lds, const Gemm g, const Sched& S, const Epi& E) {
;     ...
;             const bool last = (t == nt - 2);
;             const char* a1 = cA + (size_t)(t + 1) * kstep;
;             const char* a2 = last ? nA : cA + (size_t)(t + 2) * kstep; const char* b2 = last ? nB : cB + (size_t)(t + 2) * kstep;
;             const char* a3 = a2 + kstep; const char* b3 = b2 + kstep;
;             if (last && has_next) S.a_ready(nxt);
;             if constexpr (SP2) {
;             PG8_LDB(B0, 0, 0); PG8_LDB(B1, 0, 1); PG8_SCHED; PG8_LDA(At, 0, 0); PG8_STAGE(PG8_SA(1, 1), a1 + hstepA, voffA);
;             PG8_WAIT_V(8); PG8_WAIT_L(0); PG8_BAR; PG8_MMA(0, 0, At, B0); PG8_MMA(0, 1, At, B1); PG8_BAR; PG8_SCHED;
;             PG8_LDA(At, 0, 1); PG8_STAGE(PG8_SB(0, 0), b2, voffB); PG8_STAGE(PG8_SB(0, 1), b2 + hstepB, voffB); PG8_STAGE(PG8_SA(0, 0), a2, voffA);
;             PG8_WAIT_V(8); PG8_WAIT_L(0); PG8_BAR; PG8_MMA(1, 0, At, B0); PG8_MMA(1, 1, At, B1); PG8_BAR; PG8_SCHED;
.LBB0_1231:
	ds_read_b128 v[112:115], v185
	ds_read_b128 v[116:119], v185 offset:1024
	ds_read_b128 v[128:131], v185 offset:2048
	ds_read_b128 v[140:143], v185 offset:3072
	ds_read_b128 v[144:147], v188
	ds_read_b128 v[148:151], v188 offset:1024
	ds_read_b128 v[168:171], v188 offset:2048
	ds_read_b128 v[172:175], v188 offset:3072
	s_add_u32 s34, s30, 0xfffc0080
	s_addc_u32 s35, s31, -1
	s_cmp_eq_u32 s69, 12
	s_cselect_b32 s37, s21, s35
	s_cselect_b32 s36, s27, s34
	s_cselect_b32 s35, s19, s68
	s_cselect_b32 s34, s66, s67
	v_lshl_add_u64 v[180:181], s[30:31], 0, v[160:161]
	s_add_i32 m0, s29, 0xc000
	ds_read_b128 v[176:179], v189
	ds_read_b128 v[192:195], v189 offset:1024
	ds_read_b128 v[196:199], v189 offset:2048
	ds_read_b128 v[200:203], v189 offset:3072
	ds_read_b128 v[204:207], v189 offset:4096
	ds_read_b128 v[208:211], v189 offset:5120
	ds_read_b128 v[212:215], v189 offset:6144
	ds_read_b128 v[216:219], v189 offset:7168
	global_load_lds_dwordx4 v[180:181], off
	s_add_i32 m0, s29, 0xe000
	v_lshl_add_u64 v[180:181], s[30:31], 0, v[162:163]
	global_load_lds_dwordx4 v[180:181], off
	s_waitcnt vmcnt(8) lgkmcnt(0)
	s_barrier
	s_setprio 1
	v_mfma_f32_16x16x32_bf16 v[136:139], v[112:115], v[176:179], v[136:139]
	v_mfma_f32_16x16x32_bf16 v[132:135], v[128:131], v[176:179], v[132:135]
	v_mfma_f32_16x16x32_bf16 v[108:111], v[112:115], v[196:199], v[108:111]
	v_mfma_f32_16x16x32_bf16 v[104:107], v[128:131], v[196:199], v[104:107]
	v_mfma_f32_16x16x32_bf16 v[92:95], v[112:115], v[204:207], v[92:95]
	v_mfma_f32_16x16x32_bf16 v[88:91], v[128:131], v[204:207], v[88:91]
	v_mfma_f32_16x16x32_bf16 v[76:79], v[112:115], v[212:215], v[76:79]
	v_mfma_f32_16x16x32_bf16 v[72:75], v[128:131], v[212:215], v[72:75]
	v_mfma_f32_16x16x32_bf16 v[136:139], v[116:119], v[192:195], v[136:139]
	v_mfma_f32_16x16x32_bf16 v[132:135], v[140:143], v[192:195], v[132:135]
	v_mfma_f32_16x16x32_bf16 v[108:111], v[116:119], v[200:203], v[108:111]
	v_mfma_f32_16x16x32_bf16 v[104:107], v[140:143], v[200:203], v[104:107]
	v_mfma_f32_16x16x32_bf16 v[92:95], v[116:119], v[208:211], v[92:95]
	v_mfma_f32_16x16x32_bf16 v[88:91], v[140:143], v[208:211], v[88:91]
	v_mfma_f32_16x16x32_bf16 v[76:79], v[116:119], v[216:219], v[76:79]
	v_mfma_f32_16x16x32_bf16 v[72:75], v[140:143], v[216:219], v[72:75]
	s_setprio 0
	s_setprio 1
	v_mfma_f32_16x16x32_bf16 v[124:127], v[144:147], v[176:179], v[124:127]
	v_mfma_f32_16x16x32_bf16 v[120:123], v[168:171], v[176:179], v[120:123]
	v_mfma_f32_16x16x32_bf16 v[100:103], v[144:147], v[196:199], v[100:103]
	v_mfma_f32_16x16x32_bf16 v[96:99], v[168:171], v[196:199], v[96:99]
	v_mfma_f32_16x16x32_bf16 v[84:87], v[144:147], v[204:207], v[84:87]
	v_mfma_f32_16x16x32_bf16 v[80:83], v[168:171], v[204:207], v[80:83]
	v_mfma_f32_16x16x32_bf16 v[68:71], v[144:147], v[212:215], v[68:71]
	v_mfma_f32_16x16x32_bf16 v[64:67], v[168:171], v[212:215], v[64:67]
	v_mfma_f32_16x16x32_bf16 v[124:127], v[148:151], v[192:195], v[124:127]
	v_mfma_f32_16x16x32_bf16 v[120:123], v[172:175], v[192:195], v[120:123]
	v_mfma_f32_16x16x32_bf16 v[100:103], v[148:151], v[200:203], v[100:103]
	v_mfma_f32_16x16x32_bf16 v[96:99], v[172:175], v[200:203], v[96:99]
	v_mfma_f32_16x16x32_bf16 v[84:87], v[148:151], v[208:211], v[84:87]
	v_mfma_f32_16x16x32_bf16 v[80:83], v[172:175], v[208:211], v[80:83]
	v_mfma_f32_16x16x32_bf16 v[68:71], v[148:151], v[216:219], v[68:71]
	v_mfma_f32_16x16x32_bf16 v[64:67], v[172:175], v[216:219], v[64:67]
	s_barrier
	s_setprio 0
	s_add_i32 s58, s49, s39
	v_lshl_add_u64 v[180:181], s[34:35], 0, v[154:155]
	s_mov_b32 m0, s58
	ds_read_b128 v[176:179], v189 offset:16384
	ds_read_b128 v[192:195], v189 offset:17408
	ds_read_b128 v[196:199], v189 offset:18432
	ds_read_b128 v[200:203], v189 offset:19456
	ds_read_b128 v[204:207], v189 offset:20480
	ds_read_b128 v[208:211], v189 offset:21504
	ds_read_b128 v[212:215], v189 offset:22528
	ds_read_b128 v[216:219], v189 offset:23552
	global_load_lds_dwordx4 v[180:181], off
	s_add_i32 m0, s58, 0x2000
	s_add_u32 s58, s34, 0x40000
	v_lshl_add_u64 v[220:221], s[34:35], 0, v[158:159]
	s_addc_u32 s59, s35, 0
	s_add_i32 s73, s64, s39
	global_load_lds_dwordx4 v[220:221], off
	v_lshl_add_u64 v[222:223], s[58:59], 0, v[154:155]
	s_mov_b32 m0, s73
	v_lshl_add_u64 v[224:225], s[36:37], 0, v[156:157]
	global_load_lds_dwordx4 v[222:223], off
	s_add_i32 m0, s73, 0x2000
	v_lshl_add_u64 v[222:223], s[58:59], 0, v[158:159]
	global_load_lds_dwordx4 v[222:223], off
	s_mov_b32 m0, s29
	v_lshl_add_u64 v[222:223], s[36:37], 0, v[152:153]
	global_load_lds_dwordx4 v[222:223], off
	s_mov_b32 m0, s40
	s_nop 0
	global_load_lds_dwordx4 v[224:225], off
	s_waitcnt vmcnt(8) lgkmcnt(0)
	s_barrier
; #define PG8_STAGE(bufoff, gbase, voff) do { _Pragma("unroll") for (int _i = 0; _i < 2; ++_i) \
;         __builtin_amdgcn_global_load_lds((const unsigned*)((const char*)(gbase) + (voff)[_i]), (PG8_LAS unsigned*)(lds + (bufoff) + ldsw + _i * 8192), 16, 0, 0); } while (0)
; #define PG8_LDA(dst, b, h) do { _Pragma("unroll") for (int m = 0; m < 4; ++m) _Pragma("unroll") for (int k = 0; k < 2; ++k) dst[m][k] = *(const PG8_LAS bf16x8*)(lds + PG8_SA(b, h) + aoff + m * 2048 + k * 1024); } while (0)
; #define PG8_LDB(dst, b, h) do { _Pragma("unroll") for (int n = 0; n < 2; ++n) _Pragma("unroll") for (int k = 0; k < 2; ++k) dst[n][k] = *(const PG8_LAS bf16x8*)(lds + PG8_SB(b, h) + boff + n * 2048 + k * 1024); } while (0)
; #define PG8_MMA(ai, bj, At, Bt) do { __builtin_amdgcn_s_setprio(1); _Pragma("unroll") for (int m = 0; m < 4; ++m) _Pragma("unroll") for (int n = 0; n < 2; ++n) _Pragma("unroll") for (int k = 0; k < 2; ++k) \
;         acc[ai][bj][m][n] = __builtin_amdgcn_mfma_f32_16x16x32_bf16(Bt[n][k], At[m][k], acc[ai][bj][m][n], 0, 0, 0); __builtin_amdgcn_s_setprio(0); } while (0)
; #define PG8_WAIT_V(n) asm volatile("s_waitcnt vmcnt(" #n ")" ::: "memory")
; #define PG8_WAIT_L(n) asm volatile("s_waitcnt lgkmcnt(" #n ")" ::: "memory")
; #define PG8_BAR __builtin_amdgcn_s_barrier()
; #define PG8_SCHED __builtin_amdgcn_sched_barrier(0)
; template <class Epi, class Sched, bool ALIGN_EPI = false, bool SP2 = false>
; __device__ __forceinline__ void gemm_phase(PG8_LAS unsigned char* lds, const Gemm g, const Sched& S, const Epi& E) {
;     ...
;             PG8_WAIT_V(8); PG8_WAIT_L(0); PG8_BAR; PG8_MMA(1, 0, At, B0); PG8_MMA(1, 1, At, B1); PG8_BAR; PG8_SCHED;
;             PG8_LDB(B0, 1, 0); PG8_LDB(B1, 1, 1); PG8_SCHED; PG8_LDA(At, 1, 0); PG8_STAGE(PG8_SA(0, 1), a2 + hstepA, voffA);
;             PG8_WAIT_V(8); PG8_WAIT_L(0); PG8_BAR; PG8_MMA(0, 0, At, B0); PG8_MMA(0, 1, At, B1); PG8_BAR; PG8_SCHED;
	s_setprio 1
	v_mfma_f32_16x16x32_bf16 v[60:63], v[112:115], v[176:179], v[60:63]
	v_mfma_f32_16x16x32_bf16 v[56:59], v[128:131], v[176:179], v[56:59]
	v_mfma_f32_16x16x32_bf16 v[44:47], v[112:115], v[196:199], v[44:47]
	v_mfma_f32_16x16x32_bf16 v[40:43], v[128:131], v[196:199], v[40:43]
	v_mfma_f32_16x16x32_bf16 v[28:31], v[112:115], v[204:207], v[28:31]
	v_mfma_f32_16x16x32_bf16 v[24:27], v[128:131], v[204:207], v[24:27]
	v_mfma_f32_16x16x32_bf16 v[12:15], v[112:115], v[212:215], v[12:15]
	v_mfma_f32_16x16x32_bf16 v[8:11], v[128:131], v[212:215], v[8:11]
	v_mfma_f32_16x16x32_bf16 v[60:63], v[116:119], v[192:195], v[60:63]
	v_mfma_f32_16x16x32_bf16 v[56:59], v[140:143], v[192:195], v[56:59]
	v_mfma_f32_16x16x32_bf16 v[44:47], v[116:119], v[200:203], v[44:47]
	v_mfma_f32_16x16x32_bf16 v[40:43], v[140:143], v[200:203], v[40:43]
	v_mfma_f32_16x16x32_bf16 v[28:31], v[116:119], v[208:211], v[28:31]
	v_mfma_f32_16x16x32_bf16 v[24:27], v[140:143], v[208:211], v[24:27]
	v_mfma_f32_16x16x32_bf16 v[12:15], v[116:119], v[216:219], v[12:15]
	v_mfma_f32_16x16x32_bf16 v[8:11], v[140:143], v[216:219], v[8:11]
	s_setprio 0
	s_setprio 1
	v_mfma_f32_16x16x32_bf16 v[52:55], v[144:147], v[176:179], v[52:55]
	v_mfma_f32_16x16x32_bf16 v[48:51], v[168:171], v[176:179], v[48:51]
	v_mfma_f32_16x16x32_bf16 v[36:39], v[144:147], v[196:199], v[36:39]
	v_mfma_f32_16x16x32_bf16 v[32:35], v[168:171], v[196:199], v[32:35]
	v_mfma_f32_16x16x32_bf16 v[20:23], v[144:147], v[204:207], v[20:23]
	v_mfma_f32_16x16x32_bf16 v[16:19], v[168:171], v[204:207], v[16:19]
	v_mfma_f32_16x16x32_bf16 v[4:7], v[144:147], v[212:215], v[4:7]
	v_mfma_f32_16x16x32_bf16 v[0:3], v[168:171], v[212:215], v[0:3]
	v_mfma_f32_16x16x32_bf16 v[52:55], v[148:151], v[192:195], v[52:55]
	v_mfma_f32_16x16x32_bf16 v[48:51], v[172:175], v[192:195], v[48:51]
	v_mfma_f32_16x16x32_bf16 v[36:39], v[148:151], v[200:203], v[36:39]
	v_mfma_f32_16x16x32_bf16 v[32:35], v[172:175], v[200:203], v[32:35]
	v_mfma_f32_16x16x32_bf16 v[20:23], v[148:151], v[208:211], v[20:23]
	v_mfma_f32_16x16x32_bf16 v[16:19], v[172:175], v[208:211], v[16:19]
	v_mfma_f32_16x16x32_bf16 v[4:7], v[148:151], v[216:219], v[4:7]
	v_mfma_f32_16x16x32_bf16 v[0:3], v[172:175], v[216:219], v[0:3]
	s_barrier
	s_setprio 0
	s_add_i32 s58, 0, 0x18000
	s_add_i32 s59, 0, 0x1c000
	v_add_u32_e32 v140, s58, v183
	v_add_u32_e32 v172, s59, v183
	ds_read_b128 v[112:115], v140
	ds_read_b128 v[116:119], v140 offset:1024
	ds_read_b128 v[128:131], v140 offset:2048
	ds_read_b128 v[140:143], v140 offset:3072
	ds_read_b128 v[144:147], v172
	ds_read_b128 v[148:151], v172 offset:1024
	ds_read_b128 v[168:171], v172 offset:2048
	ds_read_b128 v[172:175], v172 offset:3072
	s_add_u32 s36, s36, 0x40000
	s_addc_u32 s37, s37, 0
	s_mov_b32 m0, s41
	v_lshl_add_u64 v[226:227], s[36:37], 0, v[152:153]
	ds_read_b128 v[176:179], v189 offset:32768
	ds_read_b128 v[192:195], v189 offset:33792
	ds_read_b128 v[196:199], v189 offset:34816
	ds_read_b128 v[200:203], v189 offset:35840
	ds_read_b128 v[204:207], v189 offset:36864
	ds_read_b128 v[208:211], v189 offset:37888
	ds_read_b128 v[212:215], v189 offset:38912
	ds_read_b128 v[216:219], v189 offset:39936
	global_load_lds_dwordx4 v[226:227], off
	s_mov_b32 m0, s42
	v_lshl_add_u64 v[226:227], s[36:37], 0, v[156:157]
	global_load_lds_dwordx4 v[226:227], off
	s_waitcnt vmcnt(8) lgkmcnt(0)
	s_barrier
	s_setprio 1
	v_mfma_f32_16x16x32_bf16 v[136:139], v[112:115], v[176:179], v[136:139]
	v_mfma_f32_16x16x32_bf16 v[132:135], v[128:131], v[176:179], v[132:135]
	v_mfma_f32_16x16x32_bf16 v[108:111], v[112:115], v[196:199], v[108:111]
	v_mfma_f32_16x16x32_bf16 v[104:107], v[128:131], v[196:199], v[104:107]
	v_mfma_f32_16x16x32_bf16 v[92:95], v[112:115], v[204:207], v[92:95]
	v_mfma_f32_16x16x32_bf16 v[88:91], v[128:131], v[204:207], v[88:91]
	v_mfma_f32_16x16x32_bf16 v[76:79], v[112:115], v[212:215], v[76:79]
	v_mfma_f32_16x16x32_bf16 v[72:75], v[128:131], v[212:215], v[72:75]
	v_mfma_f32_16x16x32_bf16 v[136:139], v[116:119], v[192:195], v[136:139]
	v_mfma_f32_16x16x32_bf16 v[132:135], v[140:143], v[192:195], v[132:135]
	v_mfma_f32_16x16x32_bf16 v[108:111], v[116:119], v[200:203], v[108:111]
	v_mfma_f32_16x16x32_bf16 v[104:107], v[140:143], v[200:203], v[104:107]
	v_mfma_f32_16x16x32_bf16 v[92:95], v[116:119], v[208:211], v[92:95]
	v_mfma_f32_16x16x32_bf16 v[88:91], v[140:143], v[208:211], v[88:91]
	v_mfma_f32_16x16x32_bf16 v[76:79], v[116:119], v[216:219], v[76:79]
	v_mfma_f32_16x16x32_bf16 v[72:75], v[140:143], v[216:219], v[72:75]
	s_setprio 0
	s_setprio 1
	v_mfma_f32_16x16x32_bf16 v[124:127], v[144:147], v[176:179], v[124:127]
	v_mfma_f32_16x16x32_bf16 v[120:123], v[168:171], v[176:179], v[120:123]
	v_mfma_f32_16x16x32_bf16 v[100:103], v[144:147], v[196:199], v[100:103]
	v_mfma_f32_16x16x32_bf16 v[96:99], v[168:171], v[196:199], v[96:99]
	v_mfma_f32_16x16x32_bf16 v[84:87], v[144:147], v[204:207], v[84:87]
	v_mfma_f32_16x16x32_bf16 v[80:83], v[168:171], v[204:207], v[80:83]
	v_mfma_f32_16x16x32_bf16 v[68:71], v[144:147], v[212:215], v[68:71]
	v_mfma_f32_16x16x32_bf16 v[64:67], v[168:171], v[212:215], v[64:67]
	v_mfma_f32_16x16x32_bf16 v[124:127], v[148:151], v[192:195], v[124:127]
	v_mfma_f32_16x16x32_bf16 v[120:123], v[172:175], v[192:195], v[120:123]
	v_mfma_f32_16x16x32_bf16 v[100:103], v[148:151], v[200:203], v[100:103]
	v_mfma_f32_16x16x32_bf16 v[96:99], v[172:175], v[200:203], v[96:99]
	v_mfma_f32_16x16x32_bf16 v[84:87], v[148:151], v[208:211], v[84:87]
	v_mfma_f32_16x16x32_bf16 v[80:83], v[172:175], v[208:211], v[80:83]
	v_mfma_f32_16x16x32_bf16 v[68:71], v[148:151], v[216:219], v[68:71]
	v_mfma_f32_16x16x32_bf16 v[64:67], v[172:175], v[216:219], v[64:67]
	s_barrier
; #define PG8_STAGE(bufoff, gbase, voff) do { _Pragma("unroll") for (int _i = 0; _i < 2; ++_i) \
;         __builtin_amdgcn_global_load_lds((const unsigned*)((const char*)(gbase) + (voff)[_i]), (PG8_LAS unsigned*)(lds + (bufoff) + ldsw + _i * 8192), 16, 0, 0); } while (0)
; #define PG8_LDA(dst, b, h) do { _Pragma("unroll") for (int m = 0; m < 4; ++m) _Pragma("unroll") for (int k = 0; k < 2; ++k) dst[m][k] = *(const PG8_LAS bf16x8*)(lds + PG8_SA(b, h) + aoff + m * 2048 + k * 1024); } while (0)
; #define PG8_MMA(ai, bj, At, Bt) do { __builtin_amdgcn_s_setprio(1); _Pragma("unroll") for (int m = 0; m < 4; ++m) _Pragma("unroll") for (int n = 0; n < 2; ++n) _Pragma("unroll") for (int k = 0; k < 2; ++k) \
;         acc[ai][bj][m][n] = __builtin_amdgcn_mfma_f32_16x16x32_bf16(Bt[n][k], At[m][k], acc[ai][bj][m][n], 0, 0, 0); __builtin_amdgcn_s_setprio(0); } while (0)
; #define PG8_WAIT_V(n) asm volatile("s_waitcnt vmcnt(" #n ")" ::: "memory")
; #define PG8_WAIT_L(n) asm volatile("s_waitcnt lgkmcnt(" #n ")" ::: "memory")
; #define PG8_BAR __builtin_amdgcn_s_barrier()
; #define PG8_SCHED __builtin_amdgcn_sched_barrier(0)
; template <class Epi, class Sched, bool ALIGN_EPI = false, bool SP2 = false>
; __device__ __forceinline__ void gemm_phase(PG8_LAS unsigned char* lds, const Gemm g, const Sched& S, const Epi& E) {
;     ...
;             PG8_LDA(At, 1, 1); PG8_STAGE(PG8_SB(1, 0), b3, voffB); PG8_STAGE(PG8_SB(1, 1), b3 + hstepB, voffB); PG8_STAGE(PG8_SA(1, 0), a3, voffA);
;             PG8_WAIT_V(8); PG8_WAIT_L(0); PG8_BAR; PG8_MMA(1, 0, At, B0); PG8_MMA(1, 1, At, B1); PG8_BAR; PG8_SCHED;
	s_setprio 0
	s_add_i32 s36, s58, s39
	v_lshl_add_u64 v[180:181], v[180:181], 0, s[14:15]
	s_mov_b32 m0, s36
	ds_read_b128 v[176:179], v189 offset:49152
	ds_read_b128 v[192:195], v189 offset:50176
	ds_read_b128 v[196:199], v189 offset:51200
	ds_read_b128 v[200:203], v189 offset:52224
	ds_read_b128 v[204:207], v189 offset:53248
	ds_read_b128 v[208:211], v189 offset:54272
	ds_read_b128 v[212:215], v189 offset:55296
	ds_read_b128 v[216:219], v189 offset:56320
	global_load_lds_dwordx4 v[180:181], off
	s_add_i32 m0, s36, 0x2000
	s_add_u32 s34, s34, 0x40080
	v_lshl_add_u64 v[180:181], v[220:221], 0, s[14:15]
	s_addc_u32 s35, s35, 0
	s_add_i32 s36, s59, s39
	global_load_lds_dwordx4 v[180:181], off
	s_mov_b32 m0, s36
	v_lshl_add_u64 v[180:181], s[34:35], 0, v[154:155]
	global_load_lds_dwordx4 v[180:181], off
	s_add_i32 m0, s36, 0x2000
	v_lshl_add_u64 v[180:181], s[34:35], 0, v[158:159]
	global_load_lds_dwordx4 v[180:181], off
	s_mov_b32 m0, s44
	v_lshl_add_u64 v[180:181], v[222:223], 0, s[14:15]
	global_load_lds_dwordx4 v[180:181], off
	s_mov_b32 m0, s45
	v_lshl_add_u64 v[180:181], v[224:225], 0, s[14:15]
	global_load_lds_dwordx4 v[180:181], off
	s_waitcnt vmcnt(8) lgkmcnt(0)
	s_barrier
	s_setprio 1
	v_mfma_f32_16x16x32_bf16 v[60:63], v[112:115], v[176:179], v[60:63]
	v_mfma_f32_16x16x32_bf16 v[56:59], v[128:131], v[176:179], v[56:59]
	v_mfma_f32_16x16x32_bf16 v[44:47], v[112:115], v[196:199], v[44:47]
	v_mfma_f32_16x16x32_bf16 v[40:43], v[128:131], v[196:199], v[40:43]
	v_mfma_f32_16x16x32_bf16 v[28:31], v[112:115], v[204:207], v[28:31]
	v_mfma_f32_16x16x32_bf16 v[24:27], v[128:131], v[204:207], v[24:27]
	v_mfma_f32_16x16x32_bf16 v[12:15], v[112:115], v[212:215], v[12:15]
	v_mfma_f32_16x16x32_bf16 v[8:11], v[128:131], v[212:215], v[8:11]
	v_mfma_f32_16x16x32_bf16 v[60:63], v[116:119], v[192:195], v[60:63]
	v_mfma_f32_16x16x32_bf16 v[56:59], v[140:143], v[192:195], v[56:59]
	v_mfma_f32_16x16x32_bf16 v[44:47], v[116:119], v[200:203], v[44:47]
	v_mfma_f32_16x16x32_bf16 v[40:43], v[140:143], v[200:203], v[40:43]
	v_mfma_f32_16x16x32_bf16 v[28:31], v[116:119], v[208:211], v[28:31]
	v_mfma_f32_16x16x32_bf16 v[24:27], v[140:143], v[208:211], v[24:27]
	v_mfma_f32_16x16x32_bf16 v[12:15], v[116:119], v[216:219], v[12:15]
	v_mfma_f32_16x16x32_bf16 v[8:11], v[140:143], v[216:219], v[8:11]
	s_setprio 0
	s_setprio 1
	v_mfma_f32_16x16x32_bf16 v[52:55], v[144:147], v[176:179], v[52:55]
	v_mfma_f32_16x16x32_bf16 v[48:51], v[168:171], v[176:179], v[48:51]
	v_mfma_f32_16x16x32_bf16 v[36:39], v[144:147], v[196:199], v[36:39]
	v_mfma_f32_16x16x32_bf16 v[32:35], v[168:171], v[196:199], v[32:35]
	v_mfma_f32_16x16x32_bf16 v[20:23], v[144:147], v[204:207], v[20:23]
	v_mfma_f32_16x16x32_bf16 v[16:19], v[168:171], v[204:207], v[16:19]
	v_mfma_f32_16x16x32_bf16 v[4:7], v[144:147], v[212:215], v[4:7]
	v_mfma_f32_16x16x32_bf16 v[0:3], v[168:171], v[212:215], v[0:3]
	v_mfma_f32_16x16x32_bf16 v[52:55], v[148:151], v[192:195], v[52:55]
	v_mfma_f32_16x16x32_bf16 v[48:51], v[172:175], v[192:195], v[48:51]
	v_mfma_f32_16x16x32_bf16 v[36:39], v[148:151], v[200:203], v[36:39]
	v_mfma_f32_16x16x32_bf16 v[32:35], v[172:175], v[200:203], v[32:35]
	v_mfma_f32_16x16x32_bf16 v[20:23], v[148:151], v[208:211], v[20:23]
	v_mfma_f32_16x16x32_bf16 v[16:19], v[172:175], v[208:211], v[16:19]
	v_mfma_f32_16x16x32_bf16 v[4:7], v[148:151], v[216:219], v[4:7]
	v_mfma_f32_16x16x32_bf16 v[0:3], v[172:175], v[216:219], v[0:3]
	s_barrier
	s_setprio 0
	s_add_i32 s69, s69, 2
	s_add_u32 s30, s30, 0x100
	s_addc_u32 s31, s31, 0
	s_add_u32 s67, s67, 0x100
	s_addc_u32 s68, s68, 0
	s_cmp_gt_u32 s69, 13
	s_cbranch_scc0 .LBB0_1231
	s_and_b64 vcc, exec, s[16:17]
	s_cbranch_vccz .LBB0_1234
	s_barrier
